# dt GEMM K-loops unrolled with two stages of loads in flight (on phase 0 + gate load hoist)
# baseline (speedup 1.0000x reference)
; __device__ __forceinline__ void dt_phase(Frame& F, const bf16* A, const bf16* Wdt, const unsigned long long* rowss, const float* dt_bias, float* dt_out) {
;     ...
;     for (int u = blockIdx.x; u < M / 32; u += F.G) {
;         const bf16* ap = A + (size_t)(u * 32 + r) * D + F.wave * 512 + hh * 8;
;         const bf16* bp = Wdt + (size_t)r * D + F.wave * 512 + hh * 8;
;         f32x16 acc[4];
; #pragma unroll
;         for (int nb = 0; nb < 4; ++nb) acc[nb] = zero16();
; #pragma unroll 4
;         for (int ks = 0; ks < 32; ++ks) {
;             const bf16x8 a = *(const bf16x8*)(ap + ks * 16);
; #pragma unroll
;             for (int nb = 0; nb < 4; ++nb) { const bf16x8 b = *(const bf16x8*)(bp + (size_t)nb * 32 * D + ks * 16); acc[nb] = __builtin_amdgcn_mfma_f32_32x32x16_bf16(a, b, acc[nb], 0, 0, 0); }
.LBB0_202:
	v_add_co_u32_e32 v236, vcc, 0x9100000, v86
	s_nop 1
	v_addc_co_u32_e32 v237, vcc, 0, v87, vcc
	v_add_co_u32_e32 v238, vcc, 0x9140000, v86
	s_nop 1
	v_addc_co_u32_e32 v239, vcc, 0, v87, vcc
	v_add_co_u32_e32 v180, vcc, 0x9180000, v86
	s_nop 1
	v_addc_co_u32_e32 v181, vcc, 0, v87, vcc
	v_add_co_u32_e32 v182, vcc, 0x91c0000, v86
	s_nop 1
	v_addc_co_u32_e32 v183, vcc, 0, v87, vcc
	global_load_dwordx4 v[140:143], v[92:93], off offset:-64
	global_load_dwordx4 v[144:147], v[92:93], off offset:-32
	global_load_dwordx4 v[148:151], v[236:237], off
	global_load_dwordx4 v[152:155], v[236:237], off offset:32
	global_load_dwordx4 v[156:159], v[238:239], off
	global_load_dwordx4 v[160:163], v[238:239], off offset:32
	global_load_dwordx4 v[164:167], v[180:181], off
	global_load_dwordx4 v[168:171], v[180:181], off offset:32
	global_load_dwordx4 v[172:175], v[182:183], off
	global_load_dwordx4 v[176:179], v[182:183], off offset:32
	global_load_dwordx4 v[196:199], v[92:93], off offset:0
	global_load_dwordx4 v[200:203], v[92:93], off offset:32
	global_load_dwordx4 v[204:207], v[236:237], off offset:64
	global_load_dwordx4 v[208:211], v[236:237], off offset:96
	global_load_dwordx4 v[212:215], v[238:239], off offset:64
	global_load_dwordx4 v[216:219], v[238:239], off offset:96
	global_load_dwordx4 v[220:223], v[180:181], off offset:64
	global_load_dwordx4 v[224:227], v[180:181], off offset:96
	global_load_dwordx4 v[228:231], v[182:183], off offset:64
	global_load_dwordx4 v[232:235], v[182:183], off offset:96
	s_waitcnt vmcnt(10)
	v_mfma_f32_32x32x16_bf16 v[50:65], v[140:143], v[148:151], v[50:65]
	v_mfma_f32_32x32x16_bf16 v[66:81], v[140:143], v[156:159], v[66:81]
	v_mfma_f32_32x32x16_bf16 v[18:33], v[140:143], v[164:167], v[18:33]
	v_mfma_f32_32x32x16_bf16 v[34:49], v[140:143], v[172:175], v[34:49]
	v_mfma_f32_32x32x16_bf16 v[50:65], v[144:147], v[152:155], v[50:65]
	v_mfma_f32_32x32x16_bf16 v[66:81], v[144:147], v[160:163], v[66:81]
	v_mfma_f32_32x32x16_bf16 v[18:33], v[144:147], v[168:171], v[18:33]
	v_mfma_f32_32x32x16_bf16 v[34:49], v[144:147], v[176:179], v[34:49]
	global_load_dwordx4 v[140:143], v[92:93], off offset:64
	global_load_dwordx4 v[144:147], v[92:93], off offset:96
	global_load_dwordx4 v[148:151], v[236:237], off offset:128
	global_load_dwordx4 v[152:155], v[236:237], off offset:160
	global_load_dwordx4 v[156:159], v[238:239], off offset:128
	global_load_dwordx4 v[160:163], v[238:239], off offset:160
	global_load_dwordx4 v[164:167], v[180:181], off offset:128
	global_load_dwordx4 v[168:171], v[180:181], off offset:160
	global_load_dwordx4 v[172:175], v[182:183], off offset:128
	global_load_dwordx4 v[176:179], v[182:183], off offset:160
	s_waitcnt vmcnt(10)
	v_mfma_f32_32x32x16_bf16 v[50:65], v[196:199], v[204:207], v[50:65]
	v_mfma_f32_32x32x16_bf16 v[66:81], v[196:199], v[212:215], v[66:81]
	v_mfma_f32_32x32x16_bf16 v[18:33], v[196:199], v[220:223], v[18:33]
	v_mfma_f32_32x32x16_bf16 v[34:49], v[196:199], v[228:231], v[34:49]
	v_mfma_f32_32x32x16_bf16 v[50:65], v[200:203], v[208:211], v[50:65]
	v_mfma_f32_32x32x16_bf16 v[66:81], v[200:203], v[216:219], v[66:81]
	v_mfma_f32_32x32x16_bf16 v[18:33], v[200:203], v[224:227], v[18:33]
	v_mfma_f32_32x32x16_bf16 v[34:49], v[200:203], v[232:235], v[34:49]
	global_load_dwordx4 v[196:199], v[92:93], off offset:128
	global_load_dwordx4 v[200:203], v[92:93], off offset:160
	global_load_dwordx4 v[204:207], v[236:237], off offset:192
	global_load_dwordx4 v[208:211], v[236:237], off offset:224
	global_load_dwordx4 v[212:215], v[238:239], off offset:192
	global_load_dwordx4 v[216:219], v[238:239], off offset:224
	global_load_dwordx4 v[220:223], v[180:181], off offset:192
	global_load_dwordx4 v[224:227], v[180:181], off offset:224
	global_load_dwordx4 v[228:231], v[182:183], off offset:192
	global_load_dwordx4 v[232:235], v[182:183], off offset:224
	s_waitcnt vmcnt(10)
	v_mfma_f32_32x32x16_bf16 v[50:65], v[140:143], v[148:151], v[50:65]
	v_mfma_f32_32x32x16_bf16 v[66:81], v[140:143], v[156:159], v[66:81]
	v_mfma_f32_32x32x16_bf16 v[18:33], v[140:143], v[164:167], v[18:33]
	v_mfma_f32_32x32x16_bf16 v[34:49], v[140:143], v[172:175], v[34:49]
	v_mfma_f32_32x32x16_bf16 v[50:65], v[144:147], v[152:155], v[50:65]
	v_mfma_f32_32x32x16_bf16 v[66:81], v[144:147], v[160:163], v[66:81]
	v_mfma_f32_32x32x16_bf16 v[18:33], v[144:147], v[168:171], v[18:33]
	v_mfma_f32_32x32x16_bf16 v[34:49], v[144:147], v[176:179], v[34:49]
	global_load_dwordx4 v[140:143], v[92:93], off offset:192
	global_load_dwordx4 v[144:147], v[92:93], off offset:224
	global_load_dwordx4 v[148:151], v[236:237], off offset:256
	global_load_dwordx4 v[152:155], v[236:237], off offset:288
	global_load_dwordx4 v[156:159], v[238:239], off offset:256
	global_load_dwordx4 v[160:163], v[238:239], off offset:288
	global_load_dwordx4 v[164:167], v[180:181], off offset:256
	global_load_dwordx4 v[168:171], v[180:181], off offset:288
	global_load_dwordx4 v[172:175], v[182:183], off offset:256
	global_load_dwordx4 v[176:179], v[182:183], off offset:288
	s_waitcnt vmcnt(10)
	v_mfma_f32_32x32x16_bf16 v[50:65], v[196:199], v[204:207], v[50:65]
	v_mfma_f32_32x32x16_bf16 v[66:81], v[196:199], v[212:215], v[66:81]
	v_mfma_f32_32x32x16_bf16 v[18:33], v[196:199], v[220:223], v[18:33]
	v_mfma_f32_32x32x16_bf16 v[34:49], v[196:199], v[228:231], v[34:49]
	v_mfma_f32_32x32x16_bf16 v[50:65], v[200:203], v[208:211], v[50:65]
	v_mfma_f32_32x32x16_bf16 v[66:81], v[200:203], v[216:219], v[66:81]
	v_mfma_f32_32x32x16_bf16 v[18:33], v[200:203], v[224:227], v[18:33]
	v_mfma_f32_32x32x16_bf16 v[34:49], v[200:203], v[232:235], v[34:49]
	global_load_dwordx4 v[196:199], v[92:93], off offset:256
	global_load_dwordx4 v[200:203], v[92:93], off offset:288
	global_load_dwordx4 v[204:207], v[236:237], off offset:320
	global_load_dwordx4 v[208:211], v[236:237], off offset:352
	global_load_dwordx4 v[212:215], v[238:239], off offset:320
	global_load_dwordx4 v[216:219], v[238:239], off offset:352
	global_load_dwordx4 v[220:223], v[180:181], off offset:320
	global_load_dwordx4 v[224:227], v[180:181], off offset:352
	global_load_dwordx4 v[228:231], v[182:183], off offset:320
	global_load_dwordx4 v[232:235], v[182:183], off offset:352
	s_waitcnt vmcnt(10)
; __device__ __forceinline__ void dt_phase(Frame& F, const bf16* A, const bf16* Wdt, const unsigned long long* rowss, const float* dt_bias, float* dt_out) {
;     ...
;         for (int ks = 0; ks < 32; ++ks) {
;             const bf16x8 a = *(const bf16x8*)(ap + ks * 16);
; #pragma unroll
;             for (int nb = 0; nb < 4; ++nb) { const bf16x8 b = *(const bf16x8*)(bp + (size_t)nb * 32 * D + ks * 16); acc[nb] = __builtin_amdgcn_mfma_f32_32x32x16_bf16(a, b, acc[nb], 0, 0, 0); }
	v_mfma_f32_32x32x16_bf16 v[50:65], v[140:143], v[148:151], v[50:65]
	v_mfma_f32_32x32x16_bf16 v[66:81], v[140:143], v[156:159], v[66:81]
	v_mfma_f32_32x32x16_bf16 v[18:33], v[140:143], v[164:167], v[18:33]
	v_mfma_f32_32x32x16_bf16 v[34:49], v[140:143], v[172:175], v[34:49]
	v_mfma_f32_32x32x16_bf16 v[50:65], v[144:147], v[152:155], v[50:65]
	v_mfma_f32_32x32x16_bf16 v[66:81], v[144:147], v[160:163], v[66:81]
	v_mfma_f32_32x32x16_bf16 v[18:33], v[144:147], v[168:171], v[18:33]
	v_mfma_f32_32x32x16_bf16 v[34:49], v[144:147], v[176:179], v[34:49]
	global_load_dwordx4 v[140:143], v[92:93], off offset:320
	global_load_dwordx4 v[144:147], v[92:93], off offset:352
	global_load_dwordx4 v[148:151], v[236:237], off offset:384
	global_load_dwordx4 v[152:155], v[236:237], off offset:416
	global_load_dwordx4 v[156:159], v[238:239], off offset:384
	global_load_dwordx4 v[160:163], v[238:239], off offset:416
	global_load_dwordx4 v[164:167], v[180:181], off offset:384
	global_load_dwordx4 v[168:171], v[180:181], off offset:416
	global_load_dwordx4 v[172:175], v[182:183], off offset:384
	global_load_dwordx4 v[176:179], v[182:183], off offset:416
	s_waitcnt vmcnt(10)
	v_mfma_f32_32x32x16_bf16 v[50:65], v[196:199], v[204:207], v[50:65]
	v_mfma_f32_32x32x16_bf16 v[66:81], v[196:199], v[212:215], v[66:81]
	v_mfma_f32_32x32x16_bf16 v[18:33], v[196:199], v[220:223], v[18:33]
	v_mfma_f32_32x32x16_bf16 v[34:49], v[196:199], v[228:231], v[34:49]
	v_mfma_f32_32x32x16_bf16 v[50:65], v[200:203], v[208:211], v[50:65]
	v_mfma_f32_32x32x16_bf16 v[66:81], v[200:203], v[216:219], v[66:81]
	v_mfma_f32_32x32x16_bf16 v[18:33], v[200:203], v[224:227], v[18:33]
	v_mfma_f32_32x32x16_bf16 v[34:49], v[200:203], v[232:235], v[34:49]
	global_load_dwordx4 v[196:199], v[92:93], off offset:384
	global_load_dwordx4 v[200:203], v[92:93], off offset:416
	global_load_dwordx4 v[204:207], v[236:237], off offset:448
	global_load_dwordx4 v[208:211], v[236:237], off offset:480
	global_load_dwordx4 v[212:215], v[238:239], off offset:448
	global_load_dwordx4 v[216:219], v[238:239], off offset:480
	global_load_dwordx4 v[220:223], v[180:181], off offset:448
	global_load_dwordx4 v[224:227], v[180:181], off offset:480
	global_load_dwordx4 v[228:231], v[182:183], off offset:448
	global_load_dwordx4 v[232:235], v[182:183], off offset:480
	s_waitcnt vmcnt(10)
	v_mfma_f32_32x32x16_bf16 v[50:65], v[140:143], v[148:151], v[50:65]
	v_mfma_f32_32x32x16_bf16 v[66:81], v[140:143], v[156:159], v[66:81]
	v_mfma_f32_32x32x16_bf16 v[18:33], v[140:143], v[164:167], v[18:33]
	v_mfma_f32_32x32x16_bf16 v[34:49], v[140:143], v[172:175], v[34:49]
	v_mfma_f32_32x32x16_bf16 v[50:65], v[144:147], v[152:155], v[50:65]
	v_mfma_f32_32x32x16_bf16 v[66:81], v[144:147], v[160:163], v[66:81]
	v_mfma_f32_32x32x16_bf16 v[18:33], v[144:147], v[168:171], v[18:33]
	v_mfma_f32_32x32x16_bf16 v[34:49], v[144:147], v[176:179], v[34:49]
	global_load_dwordx4 v[140:143], v[92:93], off offset:448
	global_load_dwordx4 v[144:147], v[92:93], off offset:480
	global_load_dwordx4 v[148:151], v[236:237], off offset:512
	global_load_dwordx4 v[152:155], v[236:237], off offset:544
	global_load_dwordx4 v[156:159], v[238:239], off offset:512
	global_load_dwordx4 v[160:163], v[238:239], off offset:544
	global_load_dwordx4 v[164:167], v[180:181], off offset:512
	global_load_dwordx4 v[168:171], v[180:181], off offset:544
	global_load_dwordx4 v[172:175], v[182:183], off offset:512
	global_load_dwordx4 v[176:179], v[182:183], off offset:544
	s_waitcnt vmcnt(10)
	v_mfma_f32_32x32x16_bf16 v[50:65], v[196:199], v[204:207], v[50:65]
	v_mfma_f32_32x32x16_bf16 v[66:81], v[196:199], v[212:215], v[66:81]
	v_mfma_f32_32x32x16_bf16 v[18:33], v[196:199], v[220:223], v[18:33]
	v_mfma_f32_32x32x16_bf16 v[34:49], v[196:199], v[228:231], v[34:49]
	v_mfma_f32_32x32x16_bf16 v[50:65], v[200:203], v[208:211], v[50:65]
	v_mfma_f32_32x32x16_bf16 v[66:81], v[200:203], v[216:219], v[66:81]
	v_mfma_f32_32x32x16_bf16 v[18:33], v[200:203], v[224:227], v[18:33]
	v_mfma_f32_32x32x16_bf16 v[34:49], v[200:203], v[232:235], v[34:49]
	global_load_dwordx4 v[196:199], v[92:93], off offset:512
	global_load_dwordx4 v[200:203], v[92:93], off offset:544
	global_load_dwordx4 v[204:207], v[236:237], off offset:576
	global_load_dwordx4 v[208:211], v[236:237], off offset:608
	global_load_dwordx4 v[212:215], v[238:239], off offset:576
	global_load_dwordx4 v[216:219], v[238:239], off offset:608
	global_load_dwordx4 v[220:223], v[180:181], off offset:576
	global_load_dwordx4 v[224:227], v[180:181], off offset:608
	global_load_dwordx4 v[228:231], v[182:183], off offset:576
	global_load_dwordx4 v[232:235], v[182:183], off offset:608
	s_waitcnt vmcnt(10)
	v_mfma_f32_32x32x16_bf16 v[50:65], v[140:143], v[148:151], v[50:65]
	v_mfma_f32_32x32x16_bf16 v[66:81], v[140:143], v[156:159], v[66:81]
	v_mfma_f32_32x32x16_bf16 v[18:33], v[140:143], v[164:167], v[18:33]
	v_mfma_f32_32x32x16_bf16 v[34:49], v[140:143], v[172:175], v[34:49]
	v_mfma_f32_32x32x16_bf16 v[50:65], v[144:147], v[152:155], v[50:65]
	v_mfma_f32_32x32x16_bf16 v[66:81], v[144:147], v[160:163], v[66:81]
	v_mfma_f32_32x32x16_bf16 v[18:33], v[144:147], v[168:171], v[18:33]
	v_mfma_f32_32x32x16_bf16 v[34:49], v[144:147], v[176:179], v[34:49]
	global_load_dwordx4 v[140:143], v[92:93], off offset:576
	global_load_dwordx4 v[144:147], v[92:93], off offset:608
	global_load_dwordx4 v[148:151], v[236:237], off offset:640
	global_load_dwordx4 v[152:155], v[236:237], off offset:672
	global_load_dwordx4 v[156:159], v[238:239], off offset:640
	global_load_dwordx4 v[160:163], v[238:239], off offset:672
	global_load_dwordx4 v[164:167], v[180:181], off offset:640
	global_load_dwordx4 v[168:171], v[180:181], off offset:672
	global_load_dwordx4 v[172:175], v[182:183], off offset:640
	global_load_dwordx4 v[176:179], v[182:183], off offset:672
	s_waitcnt vmcnt(10)
; __device__ __forceinline__ void dt_phase(Frame& F, const bf16* A, const bf16* Wdt, const unsigned long long* rowss, const float* dt_bias, float* dt_out) {
;     ...
;         for (int ks = 0; ks < 32; ++ks) {
;             const bf16x8 a = *(const bf16x8*)(ap + ks * 16);
; #pragma unroll
;             for (int nb = 0; nb < 4; ++nb) { const bf16x8 b = *(const bf16x8*)(bp + (size_t)nb * 32 * D + ks * 16); acc[nb] = __builtin_amdgcn_mfma_f32_32x32x16_bf16(a, b, acc[nb], 0, 0, 0); }
	v_mfma_f32_32x32x16_bf16 v[50:65], v[196:199], v[204:207], v[50:65]
	v_mfma_f32_32x32x16_bf16 v[66:81], v[196:199], v[212:215], v[66:81]
	v_mfma_f32_32x32x16_bf16 v[18:33], v[196:199], v[220:223], v[18:33]
	v_mfma_f32_32x32x16_bf16 v[34:49], v[196:199], v[228:231], v[34:49]
	v_mfma_f32_32x32x16_bf16 v[50:65], v[200:203], v[208:211], v[50:65]
	v_mfma_f32_32x32x16_bf16 v[66:81], v[200:203], v[216:219], v[66:81]
	v_mfma_f32_32x32x16_bf16 v[18:33], v[200:203], v[224:227], v[18:33]
	v_mfma_f32_32x32x16_bf16 v[34:49], v[200:203], v[232:235], v[34:49]
	global_load_dwordx4 v[196:199], v[92:93], off offset:640
	global_load_dwordx4 v[200:203], v[92:93], off offset:672
	global_load_dwordx4 v[204:207], v[236:237], off offset:704
	global_load_dwordx4 v[208:211], v[236:237], off offset:736
	global_load_dwordx4 v[212:215], v[238:239], off offset:704
	global_load_dwordx4 v[216:219], v[238:239], off offset:736
	global_load_dwordx4 v[220:223], v[180:181], off offset:704
	global_load_dwordx4 v[224:227], v[180:181], off offset:736
	global_load_dwordx4 v[228:231], v[182:183], off offset:704
	global_load_dwordx4 v[232:235], v[182:183], off offset:736
	s_waitcnt vmcnt(10)
	v_mfma_f32_32x32x16_bf16 v[50:65], v[140:143], v[148:151], v[50:65]
	v_mfma_f32_32x32x16_bf16 v[66:81], v[140:143], v[156:159], v[66:81]
	v_mfma_f32_32x32x16_bf16 v[18:33], v[140:143], v[164:167], v[18:33]
	v_mfma_f32_32x32x16_bf16 v[34:49], v[140:143], v[172:175], v[34:49]
	v_mfma_f32_32x32x16_bf16 v[50:65], v[144:147], v[152:155], v[50:65]
	v_mfma_f32_32x32x16_bf16 v[66:81], v[144:147], v[160:163], v[66:81]
	v_mfma_f32_32x32x16_bf16 v[18:33], v[144:147], v[168:171], v[18:33]
	v_mfma_f32_32x32x16_bf16 v[34:49], v[144:147], v[176:179], v[34:49]
	global_load_dwordx4 v[140:143], v[92:93], off offset:704
	global_load_dwordx4 v[144:147], v[92:93], off offset:736
	global_load_dwordx4 v[148:151], v[236:237], off offset:768
	global_load_dwordx4 v[152:155], v[236:237], off offset:800
	global_load_dwordx4 v[156:159], v[238:239], off offset:768
	global_load_dwordx4 v[160:163], v[238:239], off offset:800
	global_load_dwordx4 v[164:167], v[180:181], off offset:768
	global_load_dwordx4 v[168:171], v[180:181], off offset:800
	global_load_dwordx4 v[172:175], v[182:183], off offset:768
	global_load_dwordx4 v[176:179], v[182:183], off offset:800
	s_waitcnt vmcnt(10)
	v_mfma_f32_32x32x16_bf16 v[50:65], v[196:199], v[204:207], v[50:65]
	v_mfma_f32_32x32x16_bf16 v[66:81], v[196:199], v[212:215], v[66:81]
	v_mfma_f32_32x32x16_bf16 v[18:33], v[196:199], v[220:223], v[18:33]
	v_mfma_f32_32x32x16_bf16 v[34:49], v[196:199], v[228:231], v[34:49]
	v_mfma_f32_32x32x16_bf16 v[50:65], v[200:203], v[208:211], v[50:65]
	v_mfma_f32_32x32x16_bf16 v[66:81], v[200:203], v[216:219], v[66:81]
	v_mfma_f32_32x32x16_bf16 v[18:33], v[200:203], v[224:227], v[18:33]
	v_mfma_f32_32x32x16_bf16 v[34:49], v[200:203], v[232:235], v[34:49]
	global_load_dwordx4 v[196:199], v[92:93], off offset:768
	global_load_dwordx4 v[200:203], v[92:93], off offset:800
	global_load_dwordx4 v[204:207], v[236:237], off offset:832
	global_load_dwordx4 v[208:211], v[236:237], off offset:864
	global_load_dwordx4 v[212:215], v[238:239], off offset:832
	global_load_dwordx4 v[216:219], v[238:239], off offset:864
	global_load_dwordx4 v[220:223], v[180:181], off offset:832
	global_load_dwordx4 v[224:227], v[180:181], off offset:864
	global_load_dwordx4 v[228:231], v[182:183], off offset:832
	global_load_dwordx4 v[232:235], v[182:183], off offset:864
	s_waitcnt vmcnt(10)
	v_mfma_f32_32x32x16_bf16 v[50:65], v[140:143], v[148:151], v[50:65]
	v_mfma_f32_32x32x16_bf16 v[66:81], v[140:143], v[156:159], v[66:81]
	v_mfma_f32_32x32x16_bf16 v[18:33], v[140:143], v[164:167], v[18:33]
	v_mfma_f32_32x32x16_bf16 v[34:49], v[140:143], v[172:175], v[34:49]
	v_mfma_f32_32x32x16_bf16 v[50:65], v[144:147], v[152:155], v[50:65]
	v_mfma_f32_32x32x16_bf16 v[66:81], v[144:147], v[160:163], v[66:81]
	v_mfma_f32_32x32x16_bf16 v[18:33], v[144:147], v[168:171], v[18:33]
	v_mfma_f32_32x32x16_bf16 v[34:49], v[144:147], v[176:179], v[34:49]
	global_load_dwordx4 v[140:143], v[92:93], off offset:832
	global_load_dwordx4 v[144:147], v[92:93], off offset:864
	global_load_dwordx4 v[148:151], v[236:237], off offset:896
	global_load_dwordx4 v[152:155], v[236:237], off offset:928
	global_load_dwordx4 v[156:159], v[238:239], off offset:896
	global_load_dwordx4 v[160:163], v[238:239], off offset:928
	global_load_dwordx4 v[164:167], v[180:181], off offset:896
	global_load_dwordx4 v[168:171], v[180:181], off offset:928
	global_load_dwordx4 v[172:175], v[182:183], off offset:896
	global_load_dwordx4 v[176:179], v[182:183], off offset:928
	s_waitcnt vmcnt(10)
	v_mfma_f32_32x32x16_bf16 v[50:65], v[196:199], v[204:207], v[50:65]
	v_mfma_f32_32x32x16_bf16 v[66:81], v[196:199], v[212:215], v[66:81]
	v_mfma_f32_32x32x16_bf16 v[18:33], v[196:199], v[220:223], v[18:33]
	v_mfma_f32_32x32x16_bf16 v[34:49], v[196:199], v[228:231], v[34:49]
	v_mfma_f32_32x32x16_bf16 v[50:65], v[200:203], v[208:211], v[50:65]
	v_mfma_f32_32x32x16_bf16 v[66:81], v[200:203], v[216:219], v[66:81]
	v_mfma_f32_32x32x16_bf16 v[18:33], v[200:203], v[224:227], v[18:33]
	v_mfma_f32_32x32x16_bf16 v[34:49], v[200:203], v[232:235], v[34:49]
	global_load_dwordx4 v[196:199], v[92:93], off offset:896
	global_load_dwordx4 v[200:203], v[92:93], off offset:928
	global_load_dwordx4 v[204:207], v[236:237], off offset:960
	global_load_dwordx4 v[208:211], v[236:237], off offset:992
	global_load_dwordx4 v[212:215], v[238:239], off offset:960
	global_load_dwordx4 v[216:219], v[238:239], off offset:992
	global_load_dwordx4 v[220:223], v[180:181], off offset:960
	global_load_dwordx4 v[224:227], v[180:181], off offset:992
	global_load_dwordx4 v[228:231], v[182:183], off offset:960
	global_load_dwordx4 v[232:235], v[182:183], off offset:992
	s_waitcnt vmcnt(10)
; __device__ __forceinline__ void dt_phase(Frame& F, const bf16* A, const bf16* Wdt, const unsigned long long* rowss, const float* dt_bias, float* dt_out) {
;     ...
;         for (int ks = 0; ks < 32; ++ks) {
;             const bf16x8 a = *(const bf16x8*)(ap + ks * 16);
; #pragma unroll
;             for (int nb = 0; nb < 4; ++nb) { const bf16x8 b = *(const bf16x8*)(bp + (size_t)nb * 32 * D + ks * 16); acc[nb] = __builtin_amdgcn_mfma_f32_32x32x16_bf16(a, b, acc[nb], 0, 0, 0); }
;         }
; #pragma unroll
;         for (int nb = 0; nb < 4; ++nb)
; #pragma unroll
;             for (int j = 0; j < 16; ++j) { const int row = (j & 3) + 8 * (j >> 2) + 4 * hh; P[F.wave * 4096 + row * 128 + nb * 32 + r] = acc[nb][j]; }
;         __syncthreads();
; #pragma unroll
;         for (int j = 0; j < 8; ++j) { const int idx = F.tid + 512 * j; float s = 0.f;
; #pragma unroll
;             for (int w = 0; w < 8; ++w) s += P[w * 4096 + idx];
;             const int row = u * 32 + (idx >> 7), col = idx & 127;
;             const float v = s * rsqrtf((float)rowss[row] * (1.0f / (4096.0f * 16777216.0f)) + RMS_EPS) + dt_bias[col];
;             dt_out[(size_t)row * 128 + col] = fmaxf(v, 0.f) + log1pf(__expf(-fabsf(v))); }
	v_mfma_f32_32x32x16_bf16 v[50:65], v[140:143], v[148:151], v[50:65]
	v_mfma_f32_32x32x16_bf16 v[66:81], v[140:143], v[156:159], v[66:81]
	v_mfma_f32_32x32x16_bf16 v[18:33], v[140:143], v[164:167], v[18:33]
	v_mfma_f32_32x32x16_bf16 v[34:49], v[140:143], v[172:175], v[34:49]
	v_mfma_f32_32x32x16_bf16 v[50:65], v[144:147], v[152:155], v[50:65]
	v_mfma_f32_32x32x16_bf16 v[66:81], v[144:147], v[160:163], v[66:81]
	v_mfma_f32_32x32x16_bf16 v[18:33], v[144:147], v[168:171], v[18:33]
	v_mfma_f32_32x32x16_bf16 v[34:49], v[144:147], v[176:179], v[34:49]
	s_waitcnt vmcnt(0)
	v_mfma_f32_32x32x16_bf16 v[50:65], v[196:199], v[204:207], v[50:65]
	v_mfma_f32_32x32x16_bf16 v[66:81], v[196:199], v[212:215], v[66:81]
	v_mfma_f32_32x32x16_bf16 v[18:33], v[196:199], v[220:223], v[18:33]
	v_mfma_f32_32x32x16_bf16 v[34:49], v[196:199], v[228:231], v[34:49]
	v_mfma_f32_32x32x16_bf16 v[50:65], v[200:203], v[208:211], v[50:65]
	v_mfma_f32_32x32x16_bf16 v[66:81], v[200:203], v[216:219], v[66:81]
	v_mfma_f32_32x32x16_bf16 v[18:33], v[200:203], v[224:227], v[18:33]
	v_mfma_f32_32x32x16_bf16 v[34:49], v[200:203], v[232:235], v[34:49]
	s_nop 15
	s_nop 1
	ds_write2_b32 v1, v50, v66 offset1:32
	ds_write2_b32 v1, v51, v67 offset0:128 offset1:160
	v_add_u32_e32 v50, 0x400, v1
	ds_write2_b32 v50, v52, v68 offset1:32
	ds_write2_b32 v50, v53, v69 offset0:128 offset1:160
	v_add_u32_e32 v51, 0x1000, v1
	v_add_u32_e32 v52, 0x1400, v1
	s_lshl_b32 s0, s8, 5
	ds_write2_b32 v51, v54, v70 offset1:32
	ds_write2_b32 v51, v55, v71 offset0:128 offset1:160
	ds_write2_b32 v52, v56, v72 offset1:32
	ds_write2_b32 v52, v57, v73 offset0:128 offset1:160
	v_add_u32_e32 v53, 0x2000, v1
	v_add_u32_e32 v54, 0x2400, v1
	v_add_u32_e32 v55, 0x3000, v1
	v_add_u32_e32 v56, 0x3400, v1
	ds_write2_b32 v53, v58, v74 offset1:32
	ds_write2_b32 v53, v59, v75 offset0:128 offset1:160
	ds_write2_b32 v54, v60, v76 offset1:32
	ds_write2_b32 v54, v61, v77 offset0:128 offset1:160
	ds_write2_b32 v55, v62, v78 offset1:32
	ds_write2_b32 v55, v63, v79 offset0:128 offset1:160
	ds_write2_b32 v56, v64, v80 offset1:32
	ds_write2_b32 v56, v65, v81 offset0:128 offset1:160
	ds_write2_b32 v1, v18, v34 offset0:64 offset1:96
	ds_write2_b32 v1, v19, v35 offset0:192 offset1:224
	ds_write2_b32 v50, v20, v36 offset0:64 offset1:96
	ds_write2_b32 v50, v21, v37 offset0:192 offset1:224
	ds_write2_b32 v51, v22, v38 offset0:64 offset1:96
	ds_write2_b32 v51, v23, v39 offset0:192 offset1:224
	ds_write2_b32 v52, v24, v40 offset0:64 offset1:96
	ds_write2_b32 v52, v25, v41 offset0:192 offset1:224
	ds_write2_b32 v53, v26, v42 offset0:64 offset1:96
	ds_write2_b32 v53, v27, v43 offset0:192 offset1:224
	ds_write2_b32 v54, v28, v44 offset0:64 offset1:96
	ds_write2_b32 v54, v29, v45 offset0:192 offset1:224
	ds_write2_b32 v55, v30, v46 offset0:64 offset1:96
	ds_write2_b32 v55, v31, v47 offset0:192 offset1:224
	ds_write2_b32 v56, v32, v48 offset0:64 offset1:96
	ds_write2_b32 v56, v33, v49 offset0:192 offset1:224
	v_or_b32_e32 v20, s0, v99
	v_ashrrev_i32_e32 v21, 31, v20
	v_lshl_add_u64 v[18:19], v[20:21], 3, s[18:19]
	s_waitcnt lgkmcnt(0)
	s_barrier
	global_load_dwordx2 v[34:35], v[18:19], off
	global_load_dword v40, v[82:83], off
	ds_read2st64_b32 v[24:25], v94 offset1:8
	ds_read2st64_b32 v[26:27], v94 offset0:64 offset1:72
	ds_read2st64_b32 v[28:29], v94 offset0:128 offset1:136
	ds_read2st64_b32 v[22:23], v94 offset0:192 offset1:200
	ds_read_b32 v50, v95
	ds_read_b32 v51, v96
	ds_read_b32 v52, v97
	ds_read_b32 v53, v98
	ds_read_b32 v54, v100
	ds_read_b32 v41, v101
	ds_read_b32 v55, v102
	ds_read_b32 v56, v103
	s_waitcnt lgkmcnt(11)
	v_add_f32_e32 v24, 0, v24
	s_waitcnt lgkmcnt(10)
	v_add_f32_e32 v24, v24, v26
	s_waitcnt lgkmcnt(9)
	v_add_f32_e32 v24, v24, v28
	s_waitcnt lgkmcnt(8)
	v_add_f32_e32 v22, v24, v22
	s_waitcnt lgkmcnt(7)
	v_add_f32_e32 v22, v22, v50
	s_waitcnt lgkmcnt(6)
	v_add_f32_e32 v22, v22, v51
	s_waitcnt lgkmcnt(5)
	v_add_f32_e32 v22, v22, v52
	s_waitcnt lgkmcnt(4)
	v_add_f32_e32 v22, v22, v53
	v_or_b32_e32 v30, s0, v104
	v_or_b32_e32 v32, s0, v109
	v_or_b32_e32 v18, s0, v114
	v_ashrrev_i32_e32 v31, 31, v30
	v_ashrrev_i32_e32 v33, 31, v32
	v_ashrrev_i32_e32 v19, 31, v18
	v_lshl_add_u64 v[42:43], v[30:31], 3, s[18:19]
	v_lshl_add_u64 v[44:45], v[32:33], 3, s[18:19]
	v_lshl_add_u64 v[46:47], v[18:19], 3, s[18:19]
	global_load_dwordx2 v[48:49], v[42:43], off
	global_load_dwordx2 v[38:39], v[44:45], off
	global_load_dwordx2 v[36:37], v[46:47], off
	v_lshlrev_b64 v[20:21], 9, v[20:21]
	v_lshl_add_u64 v[20:21], v[84:85], 0, v[20:21]
	v_lshlrev_b64 v[18:19], 9, v[18:19]
	v_lshl_add_u64 v[18:19], v[84:85], 0, v[18:19]
	v_add_u32_e32 v90, s20, v90
	s_waitcnt vmcnt(4)
	v_ffbh_u32_e32 v26, v35
	v_min_u32_e32 v26, 32, v26
	v_lshlrev_b64 v[34:35], v26, v[34:35]
	v_min_u32_e32 v28, 1, v34
	v_or_b32_e32 v28, v35, v28
	v_cvt_f32_u32_e32 v28, v28
	v_sub_u32_e32 v24, 32, v26
	v_ldexp_f32 v24, v28, v24
	v_fmamk_f32 v24, v24, 0x2d800000, v135
	v_mul_f32_e32 v26, 0x4b800000, v24
	v_cmp_gt_f32_e32 vcc, s2, v24
	s_nop 1
	v_cndmask_b32_e32 v24, v24, v26, vcc
	v_rsq_f32_e32 v24, v24
	s_nop 0
	v_mul_f32_e32 v26, 0x45800000, v24
	v_cndmask_b32_e32 v24, v24, v26, vcc
	s_waitcnt vmcnt(3)
; __device__ __forceinline__ void dt_phase(Frame& F, const bf16* A, const bf16* Wdt, const unsigned long long* rowss, const float* dt_bias, float* dt_out) {
;     ...
;         for (int j = 0; j < 8; ++j) { const int idx = F.tid + 512 * j; float s = 0.f;
; #pragma unroll
;             for (int w = 0; w < 8; ++w) s += P[w * 4096 + idx];
;             const int row = u * 32 + (idx >> 7), col = idx & 127;
;             const float v = s * rsqrtf((float)rowss[row] * (1.0f / (4096.0f * 16777216.0f)) + RMS_EPS) + dt_bias[col];
;             dt_out[(size_t)row * 128 + col] = fmaxf(v, 0.f) + log1pf(__expf(-fabsf(v))); }
	v_fmac_f32_e32 v40, v22, v24
	v_mul_f32_e64 v22, |v40|, s3
	v_exp_f32_e32 v22, v22
	v_max_f32_e32 v24, 0, v40
	v_add_f32_e32 v26, 1.0, v22
	v_add_f32_e32 v28, -1.0, v26
	v_frexp_mant_f32_e32 v40, v26
	v_cvt_f64_f32_e32 v[34:35], v26
	v_sub_f32_e32 v42, v28, v26
	v_frexp_exp_i32_f64_e32 v34, v[34:35]
	v_cmp_gt_f32_e32 vcc, s4, v40
	v_sub_f32_e32 v28, v22, v28
	v_add_f32_e32 v35, 1.0, v42
	v_subbrev_co_u32_e32 v34, vcc, 0, v34, vcc
	v_add_f32_e32 v28, v28, v35
	v_sub_u32_e32 v35, 0, v34
	v_ldexp_f32 v26, v26, v35
	v_ldexp_f32 v28, v28, v35
	v_add_f32_e32 v35, -1.0, v26
	v_add_f32_e32 v40, 1.0, v26
	v_add_f32_e32 v42, 1.0, v35
	v_add_f32_e32 v44, -1.0, v40
	v_sub_f32_e32 v42, v26, v42
	v_sub_f32_e32 v26, v26, v44
	v_add_f32_e32 v26, v28, v26
	v_add_f32_e32 v42, v28, v42
	v_add_f32_e32 v28, v40, v26
	v_rcp_f32_e32 v44, v28
	v_add_f32_e32 v43, v35, v42
	v_sub_f32_e32 v40, v28, v40
	v_sub_f32_e32 v35, v43, v35
	v_sub_f32_e32 v26, v26, v40
	v_mul_f32_e32 v40, v43, v44
	v_sub_f32_e32 v35, v42, v35
	v_mul_f32_e32 v42, v28, v40
	v_fma_f32 v45, v40, v28, -v42
	v_fmac_f32_e32 v45, v40, v26
	v_add_f32_e32 v46, v42, v45
	v_sub_f32_e32 v47, v43, v46
	v_sub_f32_e32 v43, v43, v47
	v_sub_f32_e32 v42, v46, v42
	v_sub_f32_e32 v43, v43, v46
	v_add_f32_e32 v35, v35, v43
	v_sub_f32_e32 v42, v42, v45
	v_add_f32_e32 v35, v42, v35
	v_add_f32_e32 v42, v47, v35
	v_mul_f32_e32 v43, v44, v42
	v_mul_f32_e32 v45, v28, v43
	v_fma_f32 v28, v43, v28, -v45
	v_fmac_f32_e32 v28, v43, v26
	v_sub_f32_e32 v26, v47, v42
	v_add_f32_e32 v26, v35, v26
	v_add_f32_e32 v35, v45, v28
	v_sub_f32_e32 v46, v42, v35
	v_sub_f32_e32 v42, v42, v46
	v_sub_f32_e32 v45, v35, v45
	v_sub_f32_e32 v35, v42, v35
	v_add_f32_e32 v26, v26, v35
	v_sub_f32_e32 v28, v45, v28
	v_cvt_f32_i32_e32 v34, v34
	v_add_f32_e32 v26, v28, v26
	v_add_f32_e32 v28, v40, v43
	v_add_f32_e32 v26, v46, v26
	v_sub_f32_e32 v35, v28, v40
	v_mul_f32_e32 v26, v44, v26
	v_sub_f32_e32 v35, v43, v35
	v_add_f32_e32 v26, v35, v26
	v_mul_f32_e32 v43, 0x3f317218, v34
	v_add_f32_e32 v35, v28, v26
	v_fma_f32 v44, v34, s5, -v43
	v_mul_f32_e32 v40, v35, v35
	v_fmac_f32_e32 v44, 0xb102e308, v34
	v_sub_f32_e32 v28, v35, v28
	v_fmamk_f32 v42, v40, 0x3e9b6dac, v136
	v_sub_f32_e32 v26, v26, v28
	v_add_f32_e32 v28, v43, v44
	v_fmaak_f32 v42, v40, v42, 0x3f2aaada
	v_sub_f32_e32 v34, v28, v43
	v_ldexp_f32 v43, v35, 1
	v_mul_f32_e32 v35, v35, v40
	v_mul_f32_e32 v35, v35, v42
	v_add_f32_e32 v40, v43, v35
	v_sub_f32_e32 v42, v40, v43
	v_ldexp_f32 v26, v26, 1
	v_sub_f32_e32 v35, v35, v42
	v_add_f32_e32 v26, v26, v35
	v_add_f32_e32 v35, v40, v26
	v_sub_f32_e32 v40, v35, v40
	v_sub_f32_e32 v26, v26, v40
	v_add_f32_e32 v40, v28, v35
	v_sub_f32_e32 v42, v40, v28
	v_sub_f32_e32 v43, v40, v42
	v_sub_f32_e32 v34, v44, v34
	v_sub_f32_e32 v28, v28, v43
	v_sub_f32_e32 v35, v35, v42
	v_add_f32_e32 v28, v35, v28
	v_add_f32_e32 v35, v34, v26
	v_sub_f32_e32 v42, v35, v34
	v_sub_f32_e32 v43, v35, v42
	v_sub_f32_e32 v34, v34, v43
	v_sub_f32_e32 v26, v26, v42
	v_add_f32_e32 v28, v35, v28
	v_add_f32_e32 v26, v26, v34
	v_add_f32_e32 v34, v40, v28
	v_sub_f32_e32 v35, v34, v40
	v_sub_f32_e32 v28, v28, v35
	v_add_f32_e32 v26, v26, v28
	v_add_f32_e32 v26, v34, v26
	v_cmp_neq_f32_e32 vcc, s6, v22
	s_nop 1
	v_cndmask_b32_e32 v26, v137, v26, vcc
	v_cmp_ngt_f32_e32 vcc, -1.0, v22
	s_nop 1
	v_cndmask_b32_e32 v26, v138, v26, vcc
	v_cmp_neq_f32_e32 vcc, -1.0, v22
	s_nop 1
	v_cndmask_b32_e32 v26, v139, v26, vcc
	v_cmp_lt_f32_e64 vcc, |v22|, s7
	s_nop 1
	v_cndmask_b32_e32 v22, v26, v22, vcc
	v_add_f32_e32 v22, v24, v22
	global_store_dword v[20:21], v22, off
	global_load_dword v22, v[82:83], off
	v_add_f32_e32 v20, 0, v25
	v_add_f32_e32 v20, v20, v27
	v_add_f32_e32 v24, v20, v29
	s_waitcnt vmcnt(4)
	v_ffbh_u32_e32 v20, v49
	v_min_u32_e32 v25, 32, v20
	v_lshlrev_b64 v[20:21], v25, v[48:49]
	v_min_u32_e32 v20, 1, v20
	v_or_b32_e32 v20, v21, v20
	v_cvt_f32_u32_e32 v20, v20
	v_add_f32_e32 v21, v24, v23
	v_sub_u32_e32 v23, 32, v25
	s_waitcnt lgkmcnt(3)
	v_add_f32_e32 v21, v21, v54
	v_ldexp_f32 v20, v20, v23
	v_fmamk_f32 v20, v20, 0x2d800000, v135
	v_mul_f32_e32 v23, 0x4b800000, v20
	v_cmp_gt_f32_e32 vcc, s2, v20
	s_waitcnt lgkmcnt(2)
	v_add_f32_e32 v21, v21, v41
	s_waitcnt lgkmcnt(1)
	v_add_f32_e32 v21, v21, v55
	v_cndmask_b32_e32 v20, v20, v23, vcc
	v_rsq_f32_e32 v20, v20
	s_waitcnt lgkmcnt(0)
	v_add_f32_e32 v21, v21, v56
	v_mul_f32_e32 v23, 0x45800000, v20
	v_cndmask_b32_e32 v20, v20, v23, vcc
	s_waitcnt vmcnt(0)
; __device__ __forceinline__ void dt_phase(Frame& F, const bf16* A, const bf16* Wdt, const unsigned long long* rowss, const float* dt_bias, float* dt_out) {
;     ...
;         for (int j = 0; j < 8; ++j) { const int idx = F.tid + 512 * j; float s = 0.f;
; #pragma unroll
;             for (int w = 0; w < 8; ++w) s += P[w * 4096 + idx];
;             const int row = u * 32 + (idx >> 7), col = idx & 127;
;             const float v = s * rsqrtf((float)rowss[row] * (1.0f / (4096.0f * 16777216.0f)) + RMS_EPS) + dt_bias[col];
;             dt_out[(size_t)row * 128 + col] = fmaxf(v, 0.f) + log1pf(__expf(-fabsf(v))); }
	v_fmac_f32_e32 v22, v21, v20
	v_mul_f32_e64 v20, |v22|, s3
	v_exp_f32_e32 v23, v20
	v_max_f32_e32 v22, 0, v22
	v_add_f32_e32 v24, 1.0, v23
	v_add_f32_e32 v25, -1.0, v24
	v_frexp_mant_f32_e32 v26, v24
	v_cvt_f64_f32_e32 v[20:21], v24
	v_sub_f32_e32 v27, v25, v24
	v_frexp_exp_i32_f64_e32 v20, v[20:21]
	v_cmp_gt_f32_e32 vcc, s4, v26
	v_sub_f32_e32 v25, v23, v25
	v_add_f32_e32 v21, 1.0, v27
	v_subbrev_co_u32_e32 v20, vcc, 0, v20, vcc
	v_add_f32_e32 v21, v25, v21
	v_sub_u32_e32 v25, 0, v20
	v_ldexp_f32 v24, v24, v25
	v_ldexp_f32 v21, v21, v25
	v_add_f32_e32 v25, -1.0, v24
	v_add_f32_e32 v26, 1.0, v24
	v_add_f32_e32 v27, 1.0, v25
	v_add_f32_e32 v28, -1.0, v26
	v_sub_f32_e32 v27, v24, v27
	v_sub_f32_e32 v24, v24, v28
	v_add_f32_e32 v27, v21, v27
	v_add_f32_e32 v21, v21, v24
	v_add_f32_e32 v28, v26, v21
	v_rcp_f32_e32 v29, v28
	v_add_f32_e32 v24, v25, v27
	v_sub_f32_e32 v26, v28, v26
	v_sub_f32_e32 v25, v24, v25
	v_sub_f32_e32 v21, v21, v26
	v_mul_f32_e32 v26, v24, v29
	v_sub_f32_e32 v25, v27, v25
	v_mul_f32_e32 v27, v28, v26
	v_fma_f32 v34, v26, v28, -v27
	v_fmac_f32_e32 v34, v26, v21
	v_add_f32_e32 v35, v27, v34
	v_sub_f32_e32 v40, v24, v35
	v_sub_f32_e32 v24, v24, v40
	v_sub_f32_e32 v27, v35, v27
	v_sub_f32_e32 v24, v24, v35
	v_sub_f32_e32 v27, v27, v34
	v_add_f32_e32 v24, v25, v24
	v_add_f32_e32 v24, v27, v24
	v_add_f32_e32 v25, v40, v24
	v_mul_f32_e32 v27, v29, v25
	v_mul_f32_e32 v34, v28, v27
	v_fma_f32 v28, v27, v28, -v34
	v_fmac_f32_e32 v28, v27, v21
	v_sub_f32_e32 v21, v40, v25
	v_add_f32_e32 v21, v24, v21
	v_add_f32_e32 v24, v34, v28
	v_sub_f32_e32 v35, v25, v24
	v_sub_f32_e32 v25, v25, v35
	v_sub_f32_e32 v34, v24, v34
	v_sub_f32_e32 v24, v25, v24
	v_add_f32_e32 v21, v21, v24
	v_sub_f32_e32 v24, v34, v28
	v_cvt_f32_i32_e32 v20, v20
	v_add_f32_e32 v21, v24, v21
	v_add_f32_e32 v24, v26, v27
	v_add_f32_e32 v21, v35, v21
	v_sub_f32_e32 v25, v24, v26
	v_mul_f32_e32 v21, v29, v21
	v_sub_f32_e32 v25, v27, v25
	v_add_f32_e32 v21, v25, v21
	v_mul_f32_e32 v28, 0x3f317218, v20
	v_add_f32_e32 v25, v24, v21
	v_fma_f32 v29, v20, s5, -v28
	v_mul_f32_e32 v26, v25, v25
	v_fmac_f32_e32 v29, 0xb102e308, v20
	v_sub_f32_e32 v20, v25, v24
	v_fmamk_f32 v27, v26, 0x3e9b6dac, v136
	v_sub_f32_e32 v20, v21, v20
	v_add_f32_e32 v21, v28, v29
	v_fmaak_f32 v27, v26, v27, 0x3f2aaada
	v_sub_f32_e32 v24, v21, v28
	v_ldexp_f32 v28, v25, 1
	v_mul_f32_e32 v25, v25, v26
	v_mul_f32_e32 v25, v25, v27
	v_add_f32_e32 v26, v28, v25
	v_sub_f32_e32 v27, v26, v28
	v_ldexp_f32 v20, v20, 1
	v_sub_f32_e32 v25, v25, v27
	v_add_f32_e32 v20, v20, v25
	v_add_f32_e32 v25, v26, v20
	v_sub_f32_e32 v26, v25, v26
	v_sub_f32_e32 v20, v20, v26
	v_add_f32_e32 v26, v21, v25
	v_sub_f32_e32 v27, v26, v21
	v_sub_f32_e32 v28, v26, v27
	v_sub_f32_e32 v24, v29, v24
	v_sub_f32_e32 v21, v21, v28
	v_sub_f32_e32 v25, v25, v27
	v_add_f32_e32 v21, v25, v21
	v_add_f32_e32 v25, v24, v20
	v_sub_f32_e32 v27, v25, v24
	v_sub_f32_e32 v28, v25, v27
	v_sub_f32_e32 v24, v24, v28
	v_sub_f32_e32 v20, v20, v27
	v_add_f32_e32 v21, v25, v21
	v_add_f32_e32 v20, v20, v24
	v_add_f32_e32 v24, v26, v21
	v_sub_f32_e32 v25, v24, v26
	v_sub_f32_e32 v21, v21, v25
	v_add_f32_e32 v20, v20, v21
	v_add_f32_e32 v20, v24, v20
	v_cmp_neq_f32_e32 vcc, s6, v23
	s_nop 1
	v_cndmask_b32_e32 v20, v137, v20, vcc
	v_cmp_ngt_f32_e32 vcc, -1.0, v23
	s_nop 1
	v_cndmask_b32_e32 v20, v138, v20, vcc
	v_cmp_neq_f32_e32 vcc, -1.0, v23
	s_nop 1
	v_cndmask_b32_e32 v20, v139, v20, vcc
	v_cmp_lt_f32_e64 vcc, |v23|, s7
	s_nop 1
	v_cndmask_b32_e32 v20, v20, v23, vcc
	v_add_f32_e32 v22, v22, v20
	v_lshlrev_b64 v[20:21], 9, v[30:31]
	v_lshl_add_u64 v[20:21], v[84:85], 0, v[20:21]
	global_store_dword v[20:21], v22, off
	global_load_dword v30, v[82:83], off
	ds_read2st64_b32 v[20:21], v94 offset0:16 offset1:24
	ds_read2st64_b32 v[22:23], v94 offset0:80 offset1:88
	ds_read2st64_b32 v[24:25], v94 offset0:144 offset1:152
	ds_read2st64_b32 v[26:27], v94 offset0:208 offset1:216
	ds_read_b32 v31, v105
	ds_read_b32 v34, v106
	ds_read_b32 v35, v107
	ds_read_b32 v40, v108
	ds_read_b32 v41, v110
	ds_read_b32 v42, v111
	ds_read_b32 v43, v112
	ds_read_b32 v44, v113
	s_waitcnt lgkmcnt(11)
	v_add_f32_e32 v20, 0, v20
	s_waitcnt lgkmcnt(10)
	v_add_f32_e32 v20, v20, v22
	v_ffbh_u32_e32 v22, v39
	v_min_u32_e32 v22, 32, v22
	v_lshlrev_b64 v[28:29], v22, v[38:39]
	s_waitcnt lgkmcnt(9)
	v_add_f32_e32 v20, v20, v24
	v_min_u32_e32 v24, 1, v28
	v_or_b32_e32 v24, v29, v24
	v_cvt_f32_u32_e32 v24, v24
	v_sub_u32_e32 v22, 32, v22
	s_waitcnt lgkmcnt(8)
	v_add_f32_e32 v20, v20, v26
	s_waitcnt lgkmcnt(7)
	v_add_f32_e32 v20, v20, v31
	v_ldexp_f32 v22, v24, v22
	v_fmamk_f32 v22, v22, 0x2d800000, v135
	v_mul_f32_e32 v24, 0x4b800000, v22
	v_cmp_gt_f32_e32 vcc, s2, v22
	s_waitcnt lgkmcnt(6)
	v_add_f32_e32 v20, v20, v34
	s_waitcnt lgkmcnt(5)
	v_add_f32_e32 v20, v20, v35
	v_cndmask_b32_e32 v22, v22, v24, vcc
	v_rsq_f32_e32 v22, v22
	s_waitcnt lgkmcnt(4)
	v_add_f32_e32 v20, v20, v40
	v_mul_f32_e32 v24, 0x45800000, v22
	v_cndmask_b32_e32 v22, v22, v24, vcc
	s_waitcnt vmcnt(0)
; __device__ __forceinline__ void dt_phase(Frame& F, const bf16* A, const bf16* Wdt, const unsigned long long* rowss, const float* dt_bias, float* dt_out) {
;     ...
;         for (int j = 0; j < 8; ++j) { const int idx = F.tid + 512 * j; float s = 0.f;
; #pragma unroll
;             for (int w = 0; w < 8; ++w) s += P[w * 4096 + idx];
;             const int row = u * 32 + (idx >> 7), col = idx & 127;
;             const float v = s * rsqrtf((float)rowss[row] * (1.0f / (4096.0f * 16777216.0f)) + RMS_EPS) + dt_bias[col];
;             dt_out[(size_t)row * 128 + col] = fmaxf(v, 0.f) + log1pf(__expf(-fabsf(v))); }
	v_fmac_f32_e32 v30, v20, v22
	v_mul_f32_e64 v20, |v30|, s3
	v_exp_f32_e32 v20, v20
	v_max_f32_e32 v22, 0, v30
	v_add_f32_e32 v24, 1.0, v20
	v_add_f32_e32 v26, -1.0, v24
	v_frexp_mant_f32_e32 v30, v24
	v_cvt_f64_f32_e32 v[28:29], v24
	v_sub_f32_e32 v31, v26, v24
	v_frexp_exp_i32_f64_e32 v28, v[28:29]
	v_cmp_gt_f32_e32 vcc, s4, v30
	v_sub_f32_e32 v26, v20, v26
	v_add_f32_e32 v29, 1.0, v31
	v_subbrev_co_u32_e32 v28, vcc, 0, v28, vcc
	v_add_f32_e32 v26, v26, v29
	v_sub_u32_e32 v29, 0, v28
	v_ldexp_f32 v24, v24, v29
	v_ldexp_f32 v26, v26, v29
	v_add_f32_e32 v29, -1.0, v24
	v_add_f32_e32 v30, 1.0, v24
	v_add_f32_e32 v31, 1.0, v29
	v_add_f32_e32 v34, -1.0, v30
	v_sub_f32_e32 v31, v24, v31
	v_sub_f32_e32 v24, v24, v34
	v_add_f32_e32 v24, v26, v24
	v_add_f32_e32 v31, v26, v31
	v_add_f32_e32 v26, v30, v24
	v_rcp_f32_e32 v35, v26
	v_add_f32_e32 v34, v29, v31
	v_sub_f32_e32 v30, v26, v30
	v_sub_f32_e32 v29, v34, v29
	v_sub_f32_e32 v24, v24, v30
	v_mul_f32_e32 v30, v34, v35
	v_sub_f32_e32 v29, v31, v29
	v_mul_f32_e32 v31, v26, v30
	v_fma_f32 v38, v30, v26, -v31
	v_fmac_f32_e32 v38, v30, v24
	v_add_f32_e32 v39, v31, v38
	v_sub_f32_e32 v40, v34, v39
	v_sub_f32_e32 v34, v34, v40
	v_sub_f32_e32 v31, v39, v31
	v_sub_f32_e32 v34, v34, v39
	v_add_f32_e32 v29, v29, v34
	v_sub_f32_e32 v31, v31, v38
	v_add_f32_e32 v29, v31, v29
	v_add_f32_e32 v31, v40, v29
	v_mul_f32_e32 v34, v35, v31
	v_mul_f32_e32 v38, v26, v34
	v_fma_f32 v26, v34, v26, -v38
	v_fmac_f32_e32 v26, v34, v24
	v_sub_f32_e32 v24, v40, v31
	v_add_f32_e32 v24, v29, v24
	v_add_f32_e32 v29, v38, v26
	v_sub_f32_e32 v39, v31, v29
	v_sub_f32_e32 v31, v31, v39
	v_sub_f32_e32 v38, v29, v38
	v_sub_f32_e32 v29, v31, v29
	v_add_f32_e32 v24, v24, v29
	v_sub_f32_e32 v26, v38, v26
	v_cvt_f32_i32_e32 v28, v28
	v_add_f32_e32 v24, v26, v24
	v_add_f32_e32 v26, v30, v34
	v_add_f32_e32 v24, v39, v24
	v_sub_f32_e32 v29, v26, v30
	v_mul_f32_e32 v24, v35, v24
	v_sub_f32_e32 v29, v34, v29
	v_add_f32_e32 v24, v29, v24
	v_mul_f32_e32 v34, 0x3f317218, v28
	v_add_f32_e32 v29, v26, v24
	v_fma_f32 v35, v28, s5, -v34
	v_mul_f32_e32 v30, v29, v29
	v_fmac_f32_e32 v35, 0xb102e308, v28
	v_sub_f32_e32 v26, v29, v26
	v_fmamk_f32 v31, v30, 0x3e9b6dac, v136
	v_sub_f32_e32 v24, v24, v26
	v_add_f32_e32 v26, v34, v35
	v_fmaak_f32 v31, v30, v31, 0x3f2aaada
	v_sub_f32_e32 v28, v26, v34
	v_ldexp_f32 v34, v29, 1
	v_mul_f32_e32 v29, v29, v30
	v_mul_f32_e32 v29, v29, v31
	v_add_f32_e32 v30, v34, v29
	v_sub_f32_e32 v31, v30, v34
	v_ldexp_f32 v24, v24, 1
	v_sub_f32_e32 v29, v29, v31
	v_add_f32_e32 v24, v24, v29
	v_add_f32_e32 v29, v30, v24
	v_sub_f32_e32 v30, v29, v30
	v_sub_f32_e32 v24, v24, v30
	v_add_f32_e32 v30, v26, v29
	v_sub_f32_e32 v31, v30, v26
	v_sub_f32_e32 v34, v30, v31
	v_sub_f32_e32 v28, v35, v28
	v_sub_f32_e32 v26, v26, v34
	v_sub_f32_e32 v29, v29, v31
	v_add_f32_e32 v26, v29, v26
	v_add_f32_e32 v29, v28, v24
	v_sub_f32_e32 v31, v29, v28
	v_sub_f32_e32 v34, v29, v31
	v_sub_f32_e32 v28, v28, v34
	v_sub_f32_e32 v24, v24, v31
	v_add_f32_e32 v26, v29, v26
	v_add_f32_e32 v24, v24, v28
	v_add_f32_e32 v28, v30, v26
	v_sub_f32_e32 v29, v28, v30
	v_sub_f32_e32 v26, v26, v29
	v_add_f32_e32 v24, v24, v26
	v_add_f32_e32 v24, v28, v24
	v_cmp_neq_f32_e32 vcc, s6, v20
	v_lshlrev_b64 v[28:29], 9, v[32:33]
	v_lshl_add_u64 v[28:29], v[84:85], 0, v[28:29]
	v_cndmask_b32_e32 v24, v137, v24, vcc
	v_cmp_ngt_f32_e32 vcc, -1.0, v20
	s_nop 1
	v_cndmask_b32_e32 v24, v138, v24, vcc
	v_cmp_neq_f32_e32 vcc, -1.0, v20
	s_nop 1
	v_cndmask_b32_e32 v24, v139, v24, vcc
	v_cmp_lt_f32_e64 vcc, |v20|, s7
	s_nop 1
	v_cndmask_b32_e32 v20, v24, v20, vcc
	v_add_f32_e32 v20, v22, v20
	global_store_dword v[28:29], v20, off
	global_load_dword v22, v[82:83], off
	v_add_f32_e32 v20, 0, v21
	v_add_f32_e32 v20, v20, v23
	v_add_f32_e32 v23, v20, v25
	v_ffbh_u32_e32 v20, v37
	v_min_u32_e32 v24, 32, v20
	v_lshlrev_b64 v[20:21], v24, v[36:37]
	v_min_u32_e32 v20, 1, v20
	v_or_b32_e32 v20, v21, v20
	v_cvt_f32_u32_e32 v20, v20
	v_add_f32_e32 v21, v23, v27
	v_sub_u32_e32 v23, 32, v24
	s_waitcnt lgkmcnt(3)
	v_add_f32_e32 v21, v21, v41
	v_ldexp_f32 v20, v20, v23
	v_fmamk_f32 v20, v20, 0x2d800000, v135
	v_mul_f32_e32 v23, 0x4b800000, v20
	v_cmp_gt_f32_e32 vcc, s2, v20
	s_waitcnt lgkmcnt(2)
	v_add_f32_e32 v21, v21, v42
	s_waitcnt lgkmcnt(1)
	v_add_f32_e32 v21, v21, v43
	v_cndmask_b32_e32 v20, v20, v23, vcc
	v_rsq_f32_e32 v20, v20
	s_waitcnt lgkmcnt(0)
	v_add_f32_e32 v21, v21, v44
	v_mul_f32_e32 v23, 0x45800000, v20
	v_cndmask_b32_e32 v20, v20, v23, vcc
	s_waitcnt vmcnt(0)
; __device__ __forceinline__ void dt_phase(Frame& F, const bf16* A, const bf16* Wdt, const unsigned long long* rowss, const float* dt_bias, float* dt_out) {
;     ...
;         for (int j = 0; j < 8; ++j) { const int idx = F.tid + 512 * j; float s = 0.f;
; #pragma unroll
;             for (int w = 0; w < 8; ++w) s += P[w * 4096 + idx];
;             const int row = u * 32 + (idx >> 7), col = idx & 127;
;             const float v = s * rsqrtf((float)rowss[row] * (1.0f / (4096.0f * 16777216.0f)) + RMS_EPS) + dt_bias[col];
;             dt_out[(size_t)row * 128 + col] = fmaxf(v, 0.f) + log1pf(__expf(-fabsf(v))); }
	v_fmac_f32_e32 v22, v21, v20
	v_mul_f32_e64 v20, |v22|, s3
	v_exp_f32_e32 v24, v20
	v_max_f32_e32 v25, 0, v22
	v_add_f32_e32 v22, 1.0, v24
	v_add_f32_e32 v23, -1.0, v22
	v_frexp_mant_f32_e32 v26, v22
	v_cvt_f64_f32_e32 v[20:21], v22
	v_sub_f32_e32 v27, v23, v22
	v_frexp_exp_i32_f64_e32 v20, v[20:21]
	v_cmp_gt_f32_e32 vcc, s4, v26
	v_sub_f32_e32 v23, v24, v23
	v_add_f32_e32 v21, 1.0, v27
	v_subbrev_co_u32_e32 v20, vcc, 0, v20, vcc
	v_add_f32_e32 v21, v23, v21
	v_sub_u32_e32 v23, 0, v20
	v_ldexp_f32 v22, v22, v23
	v_ldexp_f32 v21, v21, v23
	v_add_f32_e32 v23, -1.0, v22
	v_add_f32_e32 v26, 1.0, v22
	v_add_f32_e32 v27, 1.0, v23
	v_add_f32_e32 v28, -1.0, v26
	v_sub_f32_e32 v27, v22, v27
	v_sub_f32_e32 v22, v22, v28
	v_add_f32_e32 v27, v21, v27
	v_add_f32_e32 v21, v21, v22
	v_add_f32_e32 v28, v26, v21
	v_rcp_f32_e32 v29, v28
	v_add_f32_e32 v22, v23, v27
	v_sub_f32_e32 v26, v28, v26
	v_sub_f32_e32 v23, v22, v23
	v_sub_f32_e32 v21, v21, v26
	v_mul_f32_e32 v26, v22, v29
	v_sub_f32_e32 v23, v27, v23
	v_mul_f32_e32 v27, v28, v26
	v_fma_f32 v30, v26, v28, -v27
	v_fmac_f32_e32 v30, v26, v21
	v_add_f32_e32 v31, v27, v30
	v_sub_f32_e32 v32, v22, v31
	v_sub_f32_e32 v22, v22, v32
	v_sub_f32_e32 v27, v31, v27
	v_sub_f32_e32 v22, v22, v31
	v_sub_f32_e32 v27, v27, v30
	v_add_f32_e32 v22, v23, v22
	v_add_f32_e32 v22, v27, v22
	v_add_f32_e32 v23, v32, v22
	v_mul_f32_e32 v27, v29, v23
	v_mul_f32_e32 v31, v28, v27
	v_fma_f32 v28, v27, v28, -v31
	v_fmac_f32_e32 v28, v27, v21
	v_sub_f32_e32 v30, v32, v23
	v_add_f32_e32 v21, v31, v28
	v_add_f32_e32 v22, v22, v30
	v_sub_f32_e32 v30, v21, v31
	v_sub_f32_e32 v31, v23, v21
	v_sub_f32_e32 v23, v23, v31
	v_sub_f32_e32 v21, v23, v21
	v_add_f32_e32 v21, v22, v21
	v_sub_f32_e32 v22, v30, v28
	v_cvt_f32_i32_e32 v20, v20
	v_add_f32_e32 v21, v22, v21
	v_add_f32_e32 v22, v26, v27
	v_add_f32_e32 v21, v31, v21
	v_sub_f32_e32 v23, v22, v26
	v_mul_f32_e32 v21, v29, v21
	v_sub_f32_e32 v23, v27, v23
	v_add_f32_e32 v21, v23, v21
	v_mul_f32_e32 v28, 0x3f317218, v20
	v_add_f32_e32 v23, v22, v21
	v_fma_f32 v29, v20, s5, -v28
	v_fmac_f32_e32 v29, 0xb102e308, v20
	v_sub_f32_e32 v20, v23, v22
	v_mul_f32_e32 v26, v23, v23
	v_sub_f32_e32 v20, v21, v20
	v_add_f32_e32 v21, v28, v29
	v_fmamk_f32 v27, v26, 0x3e9b6dac, v136
	v_sub_f32_e32 v22, v21, v28
	v_fmaak_f32 v27, v26, v27, 0x3f2aaada
	v_sub_f32_e32 v28, v29, v22
	v_ldexp_f32 v22, v23, 1
	v_mul_f32_e32 v23, v23, v26
	v_mul_f32_e32 v23, v23, v27
	v_add_f32_e32 v26, v22, v23
	v_sub_f32_e32 v22, v26, v22
	v_ldexp_f32 v20, v20, 1
	v_sub_f32_e32 v22, v23, v22
	v_add_f32_e32 v20, v20, v22
	v_add_f32_e32 v27, v26, v20
	v_add_f32_e32 v29, v21, v27
	v_sub_f32_e32 v22, v27, v26
	v_sub_f32_e32 v30, v29, v21
	v_sub_f32_e32 v26, v20, v22
	v_sub_f32_e32 v20, v29, v30
	v_sub_f32_e32 v31, v21, v20
	v_or_b32_e32 v20, s0, v119
	v_ashrrev_i32_e32 v21, 31, v20
	v_lshl_add_u64 v[22:23], v[20:21], 3, s[18:19]
	global_load_dwordx2 v[34:35], v[22:23], off
	v_sub_f32_e32 v22, v27, v30
	v_add_f32_e32 v22, v22, v31
	v_add_f32_e32 v23, v28, v26
	v_sub_f32_e32 v27, v23, v28
	v_add_f32_e32 v22, v23, v22
	v_sub_f32_e32 v30, v23, v27
	v_add_f32_e32 v23, v29, v22
	v_sub_f32_e32 v28, v28, v30
	v_sub_f32_e32 v26, v26, v27
	v_sub_f32_e32 v27, v23, v29
	v_add_f32_e32 v26, v26, v28
	v_sub_f32_e32 v22, v22, v27
	v_add_f32_e32 v22, v26, v22
	v_add_f32_e32 v22, v23, v22
	v_cmp_neq_f32_e32 vcc, s6, v24
	v_or_b32_e32 v30, s0, v124
	v_or_b32_e32 v32, s0, v129
	v_cndmask_b32_e32 v22, v137, v22, vcc
	v_cmp_ngt_f32_e32 vcc, -1.0, v24
	v_ashrrev_i32_e32 v31, 31, v30
	v_ashrrev_i32_e32 v33, 31, v32
	v_cndmask_b32_e32 v22, v138, v22, vcc
	v_cmp_neq_f32_e32 vcc, -1.0, v24
	v_lshl_add_u64 v[38:39], v[30:31], 3, s[18:19]
	v_lshl_add_u64 v[44:45], v[32:33], 3, s[18:19]
	v_cndmask_b32_e32 v22, v139, v22, vcc
	v_cmp_lt_f32_e64 vcc, |v24|, s7
	v_lshlrev_b64 v[20:21], 9, v[20:21]
	v_lshl_add_u64 v[20:21], v[84:85], 0, v[20:21]
	v_cndmask_b32_e32 v22, v22, v24, vcc
	v_add_f32_e32 v22, v25, v22
	global_store_dword v[18:19], v22, off
	global_load_dword v42, v[82:83], off
	ds_read2st64_b32 v[24:25], v94 offset0:32 offset1:40
	ds_read2st64_b32 v[26:27], v94 offset0:96 offset1:104
	ds_read2st64_b32 v[28:29], v94 offset0:160 offset1:168
	ds_read2st64_b32 v[22:23], v94 offset0:224 offset1:232
	s_waitcnt lgkmcnt(3)
	v_add_f32_e32 v18, 0, v24
	s_waitcnt lgkmcnt(2)
	v_add_f32_e32 v18, v18, v26
	s_waitcnt lgkmcnt(1)
	v_add_f32_e32 v18, v18, v28
	s_waitcnt lgkmcnt(0)
	v_add_f32_e32 v22, v18, v22
	v_or_b32_e32 v18, s0, v134
	v_ashrrev_i32_e32 v19, 31, v18
	v_lshl_add_u64 v[46:47], v[18:19], 3, s[18:19]
	global_load_dwordx2 v[48:49], v[38:39], off
	global_load_dwordx2 v[40:41], v[44:45], off
	global_load_dwordx2 v[36:37], v[46:47], off
	v_lshlrev_b64 v[18:19], 9, v[18:19]
	v_lshl_add_u64 v[18:19], v[84:85], 0, v[18:19]
	s_waitcnt vmcnt(5)
	v_ffbh_u32_e32 v24, v35
	v_min_u32_e32 v24, 32, v24
	v_lshlrev_b64 v[34:35], v24, v[34:35]
	v_min_u32_e32 v26, 1, v34
	v_or_b32_e32 v26, v35, v26
	v_cvt_f32_u32_e32 v26, v26
	v_sub_u32_e32 v24, 32, v24
	ds_read_b32 v28, v115
	ds_read_b32 v34, v116
	ds_read_b32 v35, v117
	ds_read_b32 v38, v118
	ds_read_b32 v39, v120
	ds_read_b32 v43, v121
	ds_read_b32 v44, v122
	ds_read_b32 v45, v123
	s_waitcnt lgkmcnt(7)
	v_add_f32_e32 v22, v22, v28
	v_ldexp_f32 v24, v26, v24
	v_fmamk_f32 v24, v24, 0x2d800000, v135
	v_mul_f32_e32 v26, 0x4b800000, v24
	v_cmp_gt_f32_e32 vcc, s2, v24
	s_waitcnt lgkmcnt(6)
	v_add_f32_e32 v22, v22, v34
	s_waitcnt lgkmcnt(5)
	v_add_f32_e32 v22, v22, v35
	v_cndmask_b32_e32 v24, v24, v26, vcc
	v_rsq_f32_e32 v24, v24
	s_waitcnt lgkmcnt(4)
	v_add_f32_e32 v22, v22, v38
	v_mul_f32_e32 v26, 0x45800000, v24
	v_cndmask_b32_e32 v24, v24, v26, vcc
	s_waitcnt vmcnt(3)
; __device__ __forceinline__ void dt_phase(Frame& F, const bf16* A, const bf16* Wdt, const unsigned long long* rowss, const float* dt_bias, float* dt_out) {
;     ...
;         for (int j = 0; j < 8; ++j) { const int idx = F.tid + 512 * j; float s = 0.f;
; #pragma unroll
;             for (int w = 0; w < 8; ++w) s += P[w * 4096 + idx];
;             const int row = u * 32 + (idx >> 7), col = idx & 127;
;             const float v = s * rsqrtf((float)rowss[row] * (1.0f / (4096.0f * 16777216.0f)) + RMS_EPS) + dt_bias[col];
;             dt_out[(size_t)row * 128 + col] = fmaxf(v, 0.f) + log1pf(__expf(-fabsf(v))); }
	v_fmac_f32_e32 v42, v22, v24
	v_mul_f32_e64 v22, |v42|, s3
	v_exp_f32_e32 v22, v22
	v_max_f32_e32 v24, 0, v42
	v_add_f32_e32 v26, 1.0, v22
	v_add_f32_e32 v28, -1.0, v26
	v_sub_f32_e32 v34, v28, v26
	v_add_f32_e32 v34, 1.0, v34
	v_sub_f32_e32 v28, v22, v28
	v_add_f32_e32 v28, v28, v34
	v_frexp_mant_f32_e32 v38, v26
	v_cvt_f64_f32_e32 v[34:35], v26
	v_frexp_exp_i32_f64_e32 v34, v[34:35]
	v_cmp_gt_f32_e32 vcc, s4, v38
	s_nop 1
	v_subbrev_co_u32_e32 v34, vcc, 0, v34, vcc
	v_sub_u32_e32 v35, 0, v34
	v_ldexp_f32 v26, v26, v35
	v_ldexp_f32 v28, v28, v35
	v_add_f32_e32 v35, -1.0, v26
	v_add_f32_e32 v46, 1.0, v26
	v_add_f32_e32 v38, 1.0, v35
	v_add_f32_e32 v47, -1.0, v46
	v_sub_f32_e32 v38, v26, v38
	v_sub_f32_e32 v26, v26, v47
	v_add_f32_e32 v26, v28, v26
	v_add_f32_e32 v38, v28, v38
	v_add_f32_e32 v28, v46, v26
	v_rcp_f32_e32 v47, v28
	v_add_f32_e32 v42, v35, v38
	v_sub_f32_e32 v35, v42, v35
	v_sub_f32_e32 v35, v38, v35
	v_sub_f32_e32 v38, v28, v46
	v_sub_f32_e32 v26, v26, v38
	v_mul_f32_e32 v38, v42, v47
	v_mul_f32_e32 v46, v28, v38
	v_fma_f32 v50, v38, v28, -v46
	v_fmac_f32_e32 v50, v38, v26
	v_add_f32_e32 v51, v46, v50
	v_sub_f32_e32 v52, v42, v51
	v_sub_f32_e32 v42, v42, v52
	v_sub_f32_e32 v46, v51, v46
	v_sub_f32_e32 v42, v42, v51
	v_add_f32_e32 v35, v35, v42
	v_sub_f32_e32 v42, v46, v50
	v_add_f32_e32 v35, v42, v35
	v_add_f32_e32 v42, v52, v35
	v_mul_f32_e32 v46, v47, v42
	v_mul_f32_e32 v50, v28, v46
	v_fma_f32 v28, v46, v28, -v50
	v_fmac_f32_e32 v28, v46, v26
	v_sub_f32_e32 v26, v52, v42
	v_add_f32_e32 v26, v35, v26
	v_add_f32_e32 v35, v50, v28
	v_sub_f32_e32 v51, v42, v35
	v_sub_f32_e32 v42, v42, v51
	v_sub_f32_e32 v50, v35, v50
	v_sub_f32_e32 v35, v42, v35
	v_add_f32_e32 v26, v26, v35
	v_sub_f32_e32 v28, v50, v28
	v_cvt_f32_i32_e32 v34, v34
	v_add_f32_e32 v26, v28, v26
	v_add_f32_e32 v28, v38, v46
	v_add_f32_e32 v26, v51, v26
	v_sub_f32_e32 v35, v28, v38
	v_mul_f32_e32 v26, v47, v26
	v_sub_f32_e32 v35, v46, v35
	v_add_f32_e32 v26, v35, v26
	v_mul_f32_e32 v46, 0x3f317218, v34
	v_add_f32_e32 v35, v28, v26
	v_fma_f32 v47, v34, s5, -v46
	v_mul_f32_e32 v38, v35, v35
	v_fmac_f32_e32 v47, 0xb102e308, v34
	v_sub_f32_e32 v28, v35, v28
	v_fmamk_f32 v42, v38, 0x3e9b6dac, v136
	v_sub_f32_e32 v26, v26, v28
	v_add_f32_e32 v28, v46, v47
	v_fmaak_f32 v42, v38, v42, 0x3f2aaada
	v_sub_f32_e32 v34, v28, v46
	v_ldexp_f32 v46, v35, 1
	v_mul_f32_e32 v35, v35, v38
	v_mul_f32_e32 v35, v35, v42
	v_add_f32_e32 v38, v46, v35
	v_sub_f32_e32 v42, v38, v46
	v_ldexp_f32 v26, v26, 1
	v_sub_f32_e32 v35, v35, v42
	v_add_f32_e32 v26, v26, v35
	v_add_f32_e32 v35, v38, v26
	v_sub_f32_e32 v38, v35, v38
	v_sub_f32_e32 v26, v26, v38
	v_add_f32_e32 v38, v28, v35
	v_sub_f32_e32 v42, v38, v28
	v_sub_f32_e32 v46, v38, v42
	v_sub_f32_e32 v34, v47, v34
	v_sub_f32_e32 v28, v28, v46
	v_sub_f32_e32 v35, v35, v42
	v_add_f32_e32 v28, v35, v28
	v_add_f32_e32 v35, v34, v26
	v_sub_f32_e32 v42, v35, v34
	v_sub_f32_e32 v46, v35, v42
	v_sub_f32_e32 v34, v34, v46
	v_sub_f32_e32 v26, v26, v42
	v_add_f32_e32 v28, v35, v28
	v_add_f32_e32 v26, v26, v34
	v_add_f32_e32 v34, v38, v28
	v_sub_f32_e32 v35, v34, v38
	v_sub_f32_e32 v28, v28, v35
	v_add_f32_e32 v26, v26, v28
	v_add_f32_e32 v26, v34, v26
	v_cmp_neq_f32_e32 vcc, s6, v22
	s_nop 1
	v_cndmask_b32_e32 v26, v137, v26, vcc
	v_cmp_ngt_f32_e32 vcc, -1.0, v22
	s_nop 1
	v_cndmask_b32_e32 v26, v138, v26, vcc
	v_cmp_neq_f32_e32 vcc, -1.0, v22
	s_nop 1
	v_cndmask_b32_e32 v26, v139, v26, vcc
	v_cmp_lt_f32_e64 vcc, |v22|, s7
	s_nop 1
	v_cndmask_b32_e32 v22, v26, v22, vcc
	v_add_f32_e32 v22, v24, v22
	global_store_dword v[20:21], v22, off
	global_load_dword v22, v[82:83], off
	v_add_f32_e32 v20, 0, v25
	v_add_f32_e32 v20, v20, v27
	v_add_f32_e32 v24, v20, v29
	s_waitcnt vmcnt(4)
	v_ffbh_u32_e32 v20, v49
	v_min_u32_e32 v25, 32, v20
	v_lshlrev_b64 v[20:21], v25, v[48:49]
	v_min_u32_e32 v20, 1, v20
	v_or_b32_e32 v20, v21, v20
	v_cvt_f32_u32_e32 v20, v20
	v_add_f32_e32 v21, v24, v23
	v_sub_u32_e32 v23, 32, v25
	s_waitcnt lgkmcnt(3)
	v_add_f32_e32 v21, v21, v39
	v_ldexp_f32 v20, v20, v23
	v_fmamk_f32 v20, v20, 0x2d800000, v135
	v_mul_f32_e32 v23, 0x4b800000, v20
	v_cmp_gt_f32_e32 vcc, s2, v20
	s_waitcnt lgkmcnt(2)
	v_add_f32_e32 v21, v21, v43
	s_waitcnt lgkmcnt(1)
	v_add_f32_e32 v21, v21, v44
	v_cndmask_b32_e32 v20, v20, v23, vcc
	v_rsq_f32_e32 v20, v20
	s_waitcnt lgkmcnt(0)
	v_add_f32_e32 v21, v21, v45
	v_mul_f32_e32 v23, 0x45800000, v20
	v_cndmask_b32_e32 v20, v20, v23, vcc
	s_waitcnt vmcnt(0)
; __device__ __forceinline__ void dt_phase(Frame& F, const bf16* A, const bf16* Wdt, const unsigned long long* rowss, const float* dt_bias, float* dt_out) {
;     ...
;         for (int j = 0; j < 8; ++j) { const int idx = F.tid + 512 * j; float s = 0.f;
; #pragma unroll
;             for (int w = 0; w < 8; ++w) s += P[w * 4096 + idx];
;             const int row = u * 32 + (idx >> 7), col = idx & 127;
;             const float v = s * rsqrtf((float)rowss[row] * (1.0f / (4096.0f * 16777216.0f)) + RMS_EPS) + dt_bias[col];
;             dt_out[(size_t)row * 128 + col] = fmaxf(v, 0.f) + log1pf(__expf(-fabsf(v))); }
	v_fmac_f32_e32 v22, v21, v20
	v_mul_f32_e64 v20, |v22|, s3
	v_exp_f32_e32 v23, v20
	v_max_f32_e32 v22, 0, v22
	v_add_f32_e32 v24, 1.0, v23
	v_add_f32_e32 v25, -1.0, v24
	v_frexp_mant_f32_e32 v26, v24
	v_cvt_f64_f32_e32 v[20:21], v24
	v_sub_f32_e32 v27, v25, v24
	v_frexp_exp_i32_f64_e32 v20, v[20:21]
	v_cmp_gt_f32_e32 vcc, s4, v26
	v_sub_f32_e32 v25, v23, v25
	v_add_f32_e32 v21, 1.0, v27
	v_subbrev_co_u32_e32 v20, vcc, 0, v20, vcc
	v_add_f32_e32 v21, v25, v21
	v_sub_u32_e32 v25, 0, v20
	v_ldexp_f32 v24, v24, v25
	v_ldexp_f32 v21, v21, v25
	v_add_f32_e32 v25, -1.0, v24
	v_add_f32_e32 v28, 1.0, v24
	v_add_f32_e32 v26, 1.0, v25
	v_add_f32_e32 v29, -1.0, v28
	v_sub_f32_e32 v26, v24, v26
	v_sub_f32_e32 v24, v24, v29
	v_add_f32_e32 v26, v21, v26
	v_add_f32_e32 v21, v21, v24
	v_add_f32_e32 v24, v28, v21
	v_rcp_f32_e32 v29, v24
	v_add_f32_e32 v27, v25, v26
	v_sub_f32_e32 v25, v27, v25
	v_sub_f32_e32 v25, v26, v25
	v_sub_f32_e32 v26, v24, v28
	v_sub_f32_e32 v21, v21, v26
	v_mul_f32_e32 v26, v27, v29
	v_mul_f32_e32 v28, v24, v26
	v_fma_f32 v34, v26, v24, -v28
	v_fmac_f32_e32 v34, v26, v21
	v_add_f32_e32 v35, v28, v34
	v_sub_f32_e32 v38, v27, v35
	v_sub_f32_e32 v27, v27, v38
	v_sub_f32_e32 v28, v35, v28
	v_sub_f32_e32 v27, v27, v35
	v_add_f32_e32 v25, v25, v27
	v_sub_f32_e32 v27, v28, v34
	v_add_f32_e32 v25, v27, v25
	v_add_f32_e32 v27, v38, v25
	v_mul_f32_e32 v28, v29, v27
	v_mul_f32_e32 v34, v24, v28
	v_fma_f32 v24, v28, v24, -v34
	v_fmac_f32_e32 v24, v28, v21
	v_sub_f32_e32 v21, v38, v27
	v_add_f32_e32 v21, v25, v21
	v_add_f32_e32 v25, v34, v24
	v_sub_f32_e32 v35, v27, v25
	v_sub_f32_e32 v27, v27, v35
	v_sub_f32_e32 v34, v25, v34
	v_sub_f32_e32 v25, v27, v25
	v_add_f32_e32 v21, v21, v25
	v_sub_f32_e32 v24, v34, v24
	v_cvt_f32_i32_e32 v20, v20
	v_add_f32_e32 v21, v24, v21
	v_add_f32_e32 v24, v26, v28
	v_add_f32_e32 v21, v35, v21
	v_sub_f32_e32 v25, v24, v26
	v_mul_f32_e32 v21, v29, v21
	v_sub_f32_e32 v25, v28, v25
	v_add_f32_e32 v21, v25, v21
	v_mul_f32_e32 v28, 0x3f317218, v20
	v_add_f32_e32 v25, v24, v21
	v_fma_f32 v29, v20, s5, -v28
	v_mul_f32_e32 v26, v25, v25
	v_fmac_f32_e32 v29, 0xb102e308, v20
	v_sub_f32_e32 v20, v25, v24
	v_fmamk_f32 v27, v26, 0x3e9b6dac, v136
	v_sub_f32_e32 v20, v21, v20
	v_add_f32_e32 v21, v28, v29
	v_fmaak_f32 v27, v26, v27, 0x3f2aaada
	v_sub_f32_e32 v24, v21, v28
	v_ldexp_f32 v28, v25, 1
	v_mul_f32_e32 v25, v25, v26
	v_mul_f32_e32 v25, v25, v27
	v_add_f32_e32 v26, v28, v25
	v_sub_f32_e32 v27, v26, v28
	v_ldexp_f32 v20, v20, 1
	v_sub_f32_e32 v25, v25, v27
	v_add_f32_e32 v20, v20, v25
	v_add_f32_e32 v25, v26, v20
	v_sub_f32_e32 v26, v25, v26
	v_sub_f32_e32 v20, v20, v26
	v_add_f32_e32 v26, v21, v25
	v_sub_f32_e32 v27, v26, v21
	v_sub_f32_e32 v28, v26, v27
	v_sub_f32_e32 v24, v29, v24
	v_sub_f32_e32 v21, v21, v28
	v_sub_f32_e32 v25, v25, v27
	v_add_f32_e32 v21, v25, v21
	v_add_f32_e32 v25, v24, v20
	v_sub_f32_e32 v27, v25, v24
	v_sub_f32_e32 v28, v25, v27
	v_sub_f32_e32 v24, v24, v28
	v_sub_f32_e32 v20, v20, v27
	v_add_f32_e32 v21, v25, v21
	v_add_f32_e32 v20, v20, v24
	v_add_f32_e32 v24, v26, v21
	v_sub_f32_e32 v25, v24, v26
	v_sub_f32_e32 v21, v21, v25
	v_add_f32_e32 v20, v20, v21
	v_add_f32_e32 v20, v24, v20
	v_cmp_neq_f32_e32 vcc, s6, v23
	s_nop 1
	v_cndmask_b32_e32 v20, v137, v20, vcc
	v_cmp_ngt_f32_e32 vcc, -1.0, v23
	s_nop 1
	v_cndmask_b32_e32 v20, v138, v20, vcc
	v_cmp_neq_f32_e32 vcc, -1.0, v23
	s_nop 1
	v_cndmask_b32_e32 v20, v139, v20, vcc
	v_cmp_lt_f32_e64 vcc, |v23|, s7
	s_nop 1
	v_cndmask_b32_e32 v20, v20, v23, vcc
	v_add_f32_e32 v22, v22, v20
	v_lshlrev_b64 v[20:21], 9, v[30:31]
	v_lshl_add_u64 v[20:21], v[84:85], 0, v[20:21]
	global_store_dword v[20:21], v22, off
	global_load_dword v30, v[82:83], off
	ds_read2st64_b32 v[20:21], v94 offset0:48 offset1:56
	ds_read2st64_b32 v[22:23], v94 offset0:112 offset1:120
	ds_read2st64_b32 v[24:25], v94 offset0:176 offset1:184
	ds_read2st64_b32 v[26:27], v94 offset0:240 offset1:248
	s_waitcnt lgkmcnt(3)
	v_add_f32_e32 v20, 0, v20
	s_waitcnt lgkmcnt(2)
	v_add_f32_e32 v20, v20, v22
	v_ffbh_u32_e32 v22, v41
	v_min_u32_e32 v22, 32, v22
	v_lshlrev_b64 v[28:29], v22, v[40:41]
	s_waitcnt lgkmcnt(1)
	v_add_f32_e32 v20, v20, v24
	v_min_u32_e32 v24, 1, v28
	v_or_b32_e32 v24, v29, v24
	v_cvt_f32_u32_e32 v24, v24
	v_sub_u32_e32 v22, 32, v22
	s_waitcnt lgkmcnt(0)
	v_add_f32_e32 v20, v20, v26
	ds_read_b32 v26, v125
	ds_read_b32 v28, v126
	ds_read_b32 v29, v127
	ds_read_b32 v31, v128
	ds_read_b32 v34, v130
	ds_read_b32 v35, v131
	ds_read_b32 v38, v132
	ds_read_b32 v39, v133
	v_ldexp_f32 v22, v24, v22
	v_fmamk_f32 v22, v22, 0x2d800000, v135
	v_mul_f32_e32 v24, 0x4b800000, v22
	v_cmp_gt_f32_e32 vcc, s2, v22
	s_waitcnt lgkmcnt(7)
	v_add_f32_e32 v20, v20, v26
	s_waitcnt lgkmcnt(6)
	v_add_f32_e32 v20, v20, v28
	v_cndmask_b32_e32 v22, v22, v24, vcc
	v_rsq_f32_e32 v22, v22
	s_waitcnt lgkmcnt(5)
	v_add_f32_e32 v20, v20, v29
	s_waitcnt lgkmcnt(4)
	v_add_f32_e32 v20, v20, v31
	v_mul_f32_e32 v24, 0x45800000, v22
	v_cndmask_b32_e32 v22, v22, v24, vcc
	s_waitcnt vmcnt(0)
; __device__ __forceinline__ void dt_phase(Frame& F, const bf16* A, const bf16* Wdt, const unsigned long long* rowss, const float* dt_bias, float* dt_out) {
;     ...
;         for (int j = 0; j < 8; ++j) { const int idx = F.tid + 512 * j; float s = 0.f;
; #pragma unroll
;             for (int w = 0; w < 8; ++w) s += P[w * 4096 + idx];
;             const int row = u * 32 + (idx >> 7), col = idx & 127;
;             const float v = s * rsqrtf((float)rowss[row] * (1.0f / (4096.0f * 16777216.0f)) + RMS_EPS) + dt_bias[col];
;             dt_out[(size_t)row * 128 + col] = fmaxf(v, 0.f) + log1pf(__expf(-fabsf(v))); }
	v_fmac_f32_e32 v30, v20, v22
	v_mul_f32_e64 v20, |v30|, s3
	v_exp_f32_e32 v20, v20
	v_max_f32_e32 v22, 0, v30
	v_add_f32_e32 v24, 1.0, v20
	v_add_f32_e32 v26, -1.0, v24
	v_sub_f32_e32 v28, v26, v24
	v_add_f32_e32 v28, 1.0, v28
	v_sub_f32_e32 v26, v20, v26
	v_add_f32_e32 v26, v26, v28
	v_frexp_mant_f32_e32 v30, v24
	v_cvt_f64_f32_e32 v[28:29], v24
	v_frexp_exp_i32_f64_e32 v28, v[28:29]
	v_cmp_gt_f32_e32 vcc, s4, v30
	s_nop 1
	v_subbrev_co_u32_e32 v28, vcc, 0, v28, vcc
	v_sub_u32_e32 v29, 0, v28
	v_ldexp_f32 v24, v24, v29
	v_ldexp_f32 v26, v26, v29
	v_add_f32_e32 v29, -1.0, v24
	v_add_f32_e32 v40, 1.0, v24
	v_add_f32_e32 v30, 1.0, v29
	v_add_f32_e32 v41, -1.0, v40
	v_sub_f32_e32 v30, v24, v30
	v_sub_f32_e32 v24, v24, v41
	v_add_f32_e32 v24, v26, v24
	v_add_f32_e32 v30, v26, v30
	v_add_f32_e32 v26, v40, v24
	v_rcp_f32_e32 v41, v26
	v_add_f32_e32 v31, v29, v30
	v_sub_f32_e32 v29, v31, v29
	v_sub_f32_e32 v29, v30, v29
	v_sub_f32_e32 v30, v26, v40
	v_sub_f32_e32 v24, v24, v30
	v_mul_f32_e32 v30, v31, v41
	v_mul_f32_e32 v40, v26, v30
	v_fma_f32 v42, v30, v26, -v40
	v_fmac_f32_e32 v42, v30, v24
	v_add_f32_e32 v43, v40, v42
	v_sub_f32_e32 v44, v31, v43
	v_sub_f32_e32 v31, v31, v44
	v_sub_f32_e32 v40, v43, v40
	v_sub_f32_e32 v31, v31, v43
	v_add_f32_e32 v29, v29, v31
	v_sub_f32_e32 v31, v40, v42
	v_add_f32_e32 v29, v31, v29
	v_add_f32_e32 v31, v44, v29
	v_mul_f32_e32 v40, v41, v31
	v_mul_f32_e32 v42, v26, v40
	v_fma_f32 v26, v40, v26, -v42
	v_fmac_f32_e32 v26, v40, v24
	v_sub_f32_e32 v24, v44, v31
	v_add_f32_e32 v24, v29, v24
	v_add_f32_e32 v29, v42, v26
	v_sub_f32_e32 v43, v31, v29
	v_sub_f32_e32 v31, v31, v43
	v_sub_f32_e32 v42, v29, v42
	v_sub_f32_e32 v29, v31, v29
	v_add_f32_e32 v24, v24, v29
	v_sub_f32_e32 v26, v42, v26
	v_cvt_f32_i32_e32 v28, v28
	v_add_f32_e32 v24, v26, v24
	v_add_f32_e32 v26, v30, v40
	v_add_f32_e32 v24, v43, v24
	v_sub_f32_e32 v29, v26, v30
	v_mul_f32_e32 v24, v41, v24
	v_sub_f32_e32 v29, v40, v29
	v_add_f32_e32 v24, v29, v24
	v_mul_f32_e32 v40, 0x3f317218, v28
	v_add_f32_e32 v29, v26, v24
	v_fma_f32 v41, v28, s5, -v40
	v_mul_f32_e32 v30, v29, v29
	v_fmac_f32_e32 v41, 0xb102e308, v28
	v_sub_f32_e32 v26, v29, v26
	v_fmamk_f32 v31, v30, 0x3e9b6dac, v136
	v_sub_f32_e32 v24, v24, v26
	v_add_f32_e32 v26, v40, v41
	v_fmaak_f32 v31, v30, v31, 0x3f2aaada
	v_sub_f32_e32 v28, v26, v40
	v_ldexp_f32 v40, v29, 1
	v_mul_f32_e32 v29, v29, v30
	v_mul_f32_e32 v29, v29, v31
	v_add_f32_e32 v30, v40, v29
	v_sub_f32_e32 v31, v30, v40
	v_ldexp_f32 v24, v24, 1
	v_sub_f32_e32 v29, v29, v31
	v_add_f32_e32 v24, v24, v29
	v_add_f32_e32 v29, v30, v24
	v_sub_f32_e32 v30, v29, v30
	v_sub_f32_e32 v24, v24, v30
	v_add_f32_e32 v30, v26, v29
	v_sub_f32_e32 v31, v30, v26
	v_sub_f32_e32 v40, v30, v31
	v_sub_f32_e32 v28, v41, v28
	v_sub_f32_e32 v26, v26, v40
	v_sub_f32_e32 v29, v29, v31
	v_add_f32_e32 v26, v29, v26
	v_add_f32_e32 v29, v28, v24
	v_sub_f32_e32 v31, v29, v28
	v_sub_f32_e32 v40, v29, v31
	v_sub_f32_e32 v28, v28, v40
	v_sub_f32_e32 v24, v24, v31
	v_add_f32_e32 v26, v29, v26
	v_add_f32_e32 v24, v24, v28
	v_add_f32_e32 v28, v30, v26
	v_sub_f32_e32 v29, v28, v30
	v_sub_f32_e32 v26, v26, v29
	v_add_f32_e32 v24, v24, v26
	v_add_f32_e32 v24, v28, v24
	v_cmp_neq_f32_e32 vcc, s6, v20
	v_lshlrev_b64 v[28:29], 9, v[32:33]
	v_lshl_add_u64 v[28:29], v[84:85], 0, v[28:29]
	v_cndmask_b32_e32 v24, v137, v24, vcc
	v_cmp_ngt_f32_e32 vcc, -1.0, v20
	s_nop 1
	v_cndmask_b32_e32 v24, v138, v24, vcc
	v_cmp_neq_f32_e32 vcc, -1.0, v20
	s_nop 1
	v_cndmask_b32_e32 v24, v139, v24, vcc
	v_cmp_lt_f32_e64 vcc, |v20|, s7
	s_nop 1
	v_cndmask_b32_e32 v20, v24, v20, vcc
	v_add_f32_e32 v20, v22, v20
	global_store_dword v[28:29], v20, off
	global_load_dword v22, v[82:83], off
	v_add_f32_e32 v20, 0, v21
	v_add_f32_e32 v20, v20, v23
	v_add_f32_e32 v23, v20, v25
	v_ffbh_u32_e32 v20, v37
	v_min_u32_e32 v24, 32, v20
	v_lshlrev_b64 v[20:21], v24, v[36:37]
	v_min_u32_e32 v20, 1, v20
	v_or_b32_e32 v20, v21, v20
	v_cvt_f32_u32_e32 v20, v20
	v_add_f32_e32 v21, v23, v27
	v_sub_u32_e32 v23, 32, v24
	s_waitcnt lgkmcnt(3)
; __device__ __forceinline__ void dt_phase(Frame& F, const bf16* A, const bf16* Wdt, const unsigned long long* rowss, const float* dt_bias, float* dt_out) {
;     ...
;     for (int u = blockIdx.x; u < M / 32; u += F.G) {
;     ...
;         for (int j = 0; j < 8; ++j) { const int idx = F.tid + 512 * j; float s = 0.f;
; #pragma unroll
;             for (int w = 0; w < 8; ++w) s += P[w * 4096 + idx];
;             const int row = u * 32 + (idx >> 7), col = idx & 127;
;             const float v = s * rsqrtf((float)rowss[row] * (1.0f / (4096.0f * 16777216.0f)) + RMS_EPS) + dt_bias[col];
;             dt_out[(size_t)row * 128 + col] = fmaxf(v, 0.f) + log1pf(__expf(-fabsf(v))); }
;         __syncthreads();
	v_add_f32_e32 v21, v21, v34
	v_ldexp_f32 v20, v20, v23
	v_fmamk_f32 v20, v20, 0x2d800000, v135
	v_mul_f32_e32 v23, 0x4b800000, v20
	v_cmp_gt_f32_e32 vcc, s2, v20
	s_waitcnt lgkmcnt(2)
	v_add_f32_e32 v21, v21, v35
	s_waitcnt lgkmcnt(1)
	v_add_f32_e32 v21, v21, v38
	v_cndmask_b32_e32 v20, v20, v23, vcc
	v_rsq_f32_e32 v20, v20
	s_waitcnt lgkmcnt(0)
	v_add_f32_e32 v21, v21, v39
	v_mul_f32_e32 v23, 0x45800000, v20
	v_cndmask_b32_e32 v20, v20, v23, vcc
	s_waitcnt vmcnt(0)
	v_fmac_f32_e32 v22, v21, v20
	v_mul_f32_e64 v20, |v22|, s3
	v_exp_f32_e32 v23, v20
	v_max_f32_e32 v22, 0, v22
	v_add_f32_e32 v24, 1.0, v23
	v_add_f32_e32 v25, -1.0, v24
	v_frexp_mant_f32_e32 v26, v24
	v_cvt_f64_f32_e32 v[20:21], v24
	v_sub_f32_e32 v27, v25, v24
	v_frexp_exp_i32_f64_e32 v20, v[20:21]
	v_cmp_gt_f32_e32 vcc, s4, v26
	v_sub_f32_e32 v25, v23, v25
	v_add_f32_e32 v21, 1.0, v27
	v_subbrev_co_u32_e32 v20, vcc, 0, v20, vcc
	v_add_f32_e32 v21, v25, v21
	v_sub_u32_e32 v25, 0, v20
	v_ldexp_f32 v24, v24, v25
	v_ldexp_f32 v21, v21, v25
	v_add_f32_e32 v25, -1.0, v24
	v_add_f32_e32 v28, 1.0, v24
	v_add_f32_e32 v26, 1.0, v25
	v_add_f32_e32 v29, -1.0, v28
	v_sub_f32_e32 v26, v24, v26
	v_sub_f32_e32 v24, v24, v29
	v_add_f32_e32 v26, v21, v26
	v_add_f32_e32 v21, v21, v24
	v_add_f32_e32 v24, v28, v21
	v_rcp_f32_e32 v29, v24
	v_add_f32_e32 v27, v25, v26
	v_sub_f32_e32 v25, v27, v25
	v_sub_f32_e32 v25, v26, v25
	v_sub_f32_e32 v26, v24, v28
	v_sub_f32_e32 v21, v21, v26
	v_mul_f32_e32 v26, v27, v29
	v_mul_f32_e32 v28, v24, v26
	v_fma_f32 v30, v26, v24, -v28
	v_fmac_f32_e32 v30, v26, v21
	v_add_f32_e32 v31, v28, v30
	v_sub_f32_e32 v32, v27, v31
	v_sub_f32_e32 v27, v27, v32
	v_sub_f32_e32 v28, v31, v28
	v_sub_f32_e32 v27, v27, v31
	v_add_f32_e32 v25, v25, v27
	v_sub_f32_e32 v27, v28, v30
	v_add_f32_e32 v25, v27, v25
	v_add_f32_e32 v27, v32, v25
	v_mul_f32_e32 v28, v29, v27
	v_mul_f32_e32 v30, v24, v28
	v_fma_f32 v24, v28, v24, -v30
	v_fmac_f32_e32 v24, v28, v21
	v_sub_f32_e32 v21, v32, v27
	v_add_f32_e32 v21, v25, v21
	v_add_f32_e32 v25, v30, v24
	v_sub_f32_e32 v31, v27, v25
	v_sub_f32_e32 v27, v27, v31
	v_sub_f32_e32 v30, v25, v30
	v_sub_f32_e32 v25, v27, v25
	v_add_f32_e32 v21, v21, v25
	v_sub_f32_e32 v24, v30, v24
	v_cvt_f32_i32_e32 v20, v20
	v_add_f32_e32 v21, v24, v21
	v_add_f32_e32 v24, v26, v28
	v_add_f32_e32 v21, v31, v21
	v_sub_f32_e32 v25, v24, v26
	v_mul_f32_e32 v21, v29, v21
	v_sub_f32_e32 v25, v28, v25
	v_add_f32_e32 v21, v25, v21
	v_mul_f32_e32 v28, 0x3f317218, v20
	v_add_f32_e32 v25, v24, v21
	v_fma_f32 v29, v20, s5, -v28
	v_mul_f32_e32 v26, v25, v25
	v_fmac_f32_e32 v29, 0xb102e308, v20
	v_sub_f32_e32 v20, v25, v24
	v_fmamk_f32 v27, v26, 0x3e9b6dac, v136
	v_sub_f32_e32 v20, v21, v20
	v_add_f32_e32 v21, v28, v29
	v_fmaak_f32 v27, v26, v27, 0x3f2aaada
	v_sub_f32_e32 v24, v21, v28
	v_ldexp_f32 v28, v25, 1
	v_mul_f32_e32 v25, v25, v26
	v_mul_f32_e32 v25, v25, v27
	v_add_f32_e32 v26, v28, v25
	v_sub_f32_e32 v27, v26, v28
	v_ldexp_f32 v20, v20, 1
	v_sub_f32_e32 v25, v25, v27
	v_add_f32_e32 v20, v20, v25
	v_add_f32_e32 v25, v26, v20
	v_sub_f32_e32 v26, v25, v26
	v_sub_f32_e32 v20, v20, v26
	v_add_f32_e32 v26, v21, v25
	v_sub_f32_e32 v27, v26, v21
	v_sub_f32_e32 v28, v26, v27
	v_sub_f32_e32 v24, v29, v24
	v_sub_f32_e32 v21, v21, v28
	v_sub_f32_e32 v25, v25, v27
	v_add_f32_e32 v21, v25, v21
	v_add_f32_e32 v25, v24, v20
	v_sub_f32_e32 v27, v25, v24
	v_sub_f32_e32 v28, v25, v27
	v_sub_f32_e32 v24, v24, v28
	v_sub_f32_e32 v20, v20, v27
	v_add_f32_e32 v21, v25, v21
	v_add_f32_e32 v20, v20, v24
	v_add_f32_e32 v24, v26, v21
	v_sub_f32_e32 v25, v24, v26
	v_sub_f32_e32 v21, v21, v25
	v_add_f32_e32 v20, v20, v21
	v_add_f32_e32 v20, v24, v20
	v_cmp_neq_f32_e32 vcc, s6, v23
	s_nop 1
	v_cndmask_b32_e32 v20, v137, v20, vcc
	v_cmp_ngt_f32_e32 vcc, -1.0, v23
	s_nop 1
	v_cndmask_b32_e32 v20, v138, v20, vcc
	v_cmp_neq_f32_e32 vcc, -1.0, v23
	s_nop 1
	v_cndmask_b32_e32 v20, v139, v20, vcc
	v_cmp_lt_f32_e64 vcc, |v23|, s7
	s_nop 1
	v_cndmask_b32_e32 v20, v20, v23, vcc
	v_add_f32_e32 v20, v22, v20
	global_store_dword v[18:19], v20, off
	s_barrier
	s_load_dword s0, s[74:75], 0x108
	s_waitcnt lgkmcnt(0)
	s_add_i32 s8, s8, s0
	s_cmpk_gt_i32 s8, 0xff
	s_cbranch_scc0 .LBB0_201

; __device__ __forceinline__ void dt_phase(Frame& F, const bf16* A, const bf16* Wdt, const unsigned long long* rowss, const float* dt_bias, float* dt_out) {
;     ...
; #pragma unroll 4
;         for (int ks = 0; ks < 32; ++ks) {
;             const bf16x8 a = *(const bf16x8*)(ap + ks * 16);
; #pragma unroll
;             for (int nb = 0; nb < 4; ++nb) { const bf16x8 b = *(const bf16x8*)(bp + (size_t)nb * 32 * D + ks * 16); acc[nb] = __builtin_amdgcn_mfma_f32_32x32x16_bf16(a, b, acc[nb], 0, 0, 0); }
;         }
.LBB0_1909:
	v_add_co_u32_e32 v236, vcc, 0x2e200000, v86
	s_nop 1
	v_addc_co_u32_e32 v237, vcc, 0, v87, vcc
	v_add_co_u32_e32 v238, vcc, 0x2e240000, v86
	s_nop 1
	v_addc_co_u32_e32 v239, vcc, 0, v87, vcc
	v_add_co_u32_e32 v180, vcc, 0x2e280000, v86
	s_nop 1
	v_addc_co_u32_e32 v181, vcc, 0, v87, vcc
	v_add_co_u32_e32 v182, vcc, 0x2e2c0000, v86
	s_nop 1
	v_addc_co_u32_e32 v183, vcc, 0, v87, vcc
	global_load_dwordx4 v[140:143], v[92:93], off offset:-64
	global_load_dwordx4 v[144:147], v[92:93], off offset:-32
	global_load_dwordx4 v[148:151], v[236:237], off
	global_load_dwordx4 v[152:155], v[236:237], off offset:32
	global_load_dwordx4 v[156:159], v[238:239], off
	global_load_dwordx4 v[160:163], v[238:239], off offset:32
	global_load_dwordx4 v[164:167], v[180:181], off
	global_load_dwordx4 v[168:171], v[180:181], off offset:32
	global_load_dwordx4 v[172:175], v[182:183], off
	global_load_dwordx4 v[176:179], v[182:183], off offset:32
	global_load_dwordx4 v[196:199], v[92:93], off offset:0
	global_load_dwordx4 v[200:203], v[92:93], off offset:32
	global_load_dwordx4 v[204:207], v[236:237], off offset:64
	global_load_dwordx4 v[208:211], v[236:237], off offset:96
	global_load_dwordx4 v[212:215], v[238:239], off offset:64
	global_load_dwordx4 v[216:219], v[238:239], off offset:96
	global_load_dwordx4 v[220:223], v[180:181], off offset:64
	global_load_dwordx4 v[224:227], v[180:181], off offset:96
	global_load_dwordx4 v[228:231], v[182:183], off offset:64
	global_load_dwordx4 v[232:235], v[182:183], off offset:96
	s_waitcnt vmcnt(10)
	v_mfma_f32_32x32x16_bf16 v[50:65], v[140:143], v[148:151], v[50:65]
	v_mfma_f32_32x32x16_bf16 v[66:81], v[140:143], v[156:159], v[66:81]
	v_mfma_f32_32x32x16_bf16 v[18:33], v[140:143], v[164:167], v[18:33]
	v_mfma_f32_32x32x16_bf16 v[34:49], v[140:143], v[172:175], v[34:49]
	v_mfma_f32_32x32x16_bf16 v[50:65], v[144:147], v[152:155], v[50:65]
	v_mfma_f32_32x32x16_bf16 v[66:81], v[144:147], v[160:163], v[66:81]
	v_mfma_f32_32x32x16_bf16 v[18:33], v[144:147], v[168:171], v[18:33]
	v_mfma_f32_32x32x16_bf16 v[34:49], v[144:147], v[176:179], v[34:49]
	global_load_dwordx4 v[140:143], v[92:93], off offset:64
	global_load_dwordx4 v[144:147], v[92:93], off offset:96
	global_load_dwordx4 v[148:151], v[236:237], off offset:128
	global_load_dwordx4 v[152:155], v[236:237], off offset:160
	global_load_dwordx4 v[156:159], v[238:239], off offset:128
	global_load_dwordx4 v[160:163], v[238:239], off offset:160
	global_load_dwordx4 v[164:167], v[180:181], off offset:128
	global_load_dwordx4 v[168:171], v[180:181], off offset:160
	global_load_dwordx4 v[172:175], v[182:183], off offset:128
	global_load_dwordx4 v[176:179], v[182:183], off offset:160
	s_waitcnt vmcnt(10)
	v_mfma_f32_32x32x16_bf16 v[50:65], v[196:199], v[204:207], v[50:65]
	v_mfma_f32_32x32x16_bf16 v[66:81], v[196:199], v[212:215], v[66:81]
	v_mfma_f32_32x32x16_bf16 v[18:33], v[196:199], v[220:223], v[18:33]
	v_mfma_f32_32x32x16_bf16 v[34:49], v[196:199], v[228:231], v[34:49]
	v_mfma_f32_32x32x16_bf16 v[50:65], v[200:203], v[208:211], v[50:65]
	v_mfma_f32_32x32x16_bf16 v[66:81], v[200:203], v[216:219], v[66:81]
	v_mfma_f32_32x32x16_bf16 v[18:33], v[200:203], v[224:227], v[18:33]
	v_mfma_f32_32x32x16_bf16 v[34:49], v[200:203], v[232:235], v[34:49]
	global_load_dwordx4 v[196:199], v[92:93], off offset:128
	global_load_dwordx4 v[200:203], v[92:93], off offset:160
	global_load_dwordx4 v[204:207], v[236:237], off offset:192
	global_load_dwordx4 v[208:211], v[236:237], off offset:224
	global_load_dwordx4 v[212:215], v[238:239], off offset:192
	global_load_dwordx4 v[216:219], v[238:239], off offset:224
	global_load_dwordx4 v[220:223], v[180:181], off offset:192
	global_load_dwordx4 v[224:227], v[180:181], off offset:224
	global_load_dwordx4 v[228:231], v[182:183], off offset:192
	global_load_dwordx4 v[232:235], v[182:183], off offset:224
	s_waitcnt vmcnt(10)
	v_mfma_f32_32x32x16_bf16 v[50:65], v[140:143], v[148:151], v[50:65]
	v_mfma_f32_32x32x16_bf16 v[66:81], v[140:143], v[156:159], v[66:81]
	v_mfma_f32_32x32x16_bf16 v[18:33], v[140:143], v[164:167], v[18:33]
	v_mfma_f32_32x32x16_bf16 v[34:49], v[140:143], v[172:175], v[34:49]
	v_mfma_f32_32x32x16_bf16 v[50:65], v[144:147], v[152:155], v[50:65]
	v_mfma_f32_32x32x16_bf16 v[66:81], v[144:147], v[160:163], v[66:81]
	v_mfma_f32_32x32x16_bf16 v[18:33], v[144:147], v[168:171], v[18:33]
	v_mfma_f32_32x32x16_bf16 v[34:49], v[144:147], v[176:179], v[34:49]
	global_load_dwordx4 v[140:143], v[92:93], off offset:192
	global_load_dwordx4 v[144:147], v[92:93], off offset:224
	global_load_dwordx4 v[148:151], v[236:237], off offset:256
	global_load_dwordx4 v[152:155], v[236:237], off offset:288
	global_load_dwordx4 v[156:159], v[238:239], off offset:256
	global_load_dwordx4 v[160:163], v[238:239], off offset:288
	global_load_dwordx4 v[164:167], v[180:181], off offset:256
	global_load_dwordx4 v[168:171], v[180:181], off offset:288
	global_load_dwordx4 v[172:175], v[182:183], off offset:256
	global_load_dwordx4 v[176:179], v[182:183], off offset:288
	s_waitcnt vmcnt(10)
	v_mfma_f32_32x32x16_bf16 v[50:65], v[196:199], v[204:207], v[50:65]
	v_mfma_f32_32x32x16_bf16 v[66:81], v[196:199], v[212:215], v[66:81]
	v_mfma_f32_32x32x16_bf16 v[18:33], v[196:199], v[220:223], v[18:33]
	v_mfma_f32_32x32x16_bf16 v[34:49], v[196:199], v[228:231], v[34:49]
	v_mfma_f32_32x32x16_bf16 v[50:65], v[200:203], v[208:211], v[50:65]
	v_mfma_f32_32x32x16_bf16 v[66:81], v[200:203], v[216:219], v[66:81]
	v_mfma_f32_32x32x16_bf16 v[18:33], v[200:203], v[224:227], v[18:33]
	v_mfma_f32_32x32x16_bf16 v[34:49], v[200:203], v[232:235], v[34:49]
	global_load_dwordx4 v[196:199], v[92:93], off offset:256
	global_load_dwordx4 v[200:203], v[92:93], off offset:288
	global_load_dwordx4 v[204:207], v[236:237], off offset:320
	global_load_dwordx4 v[208:211], v[236:237], off offset:352
	global_load_dwordx4 v[212:215], v[238:239], off offset:320
	global_load_dwordx4 v[216:219], v[238:239], off offset:352
	global_load_dwordx4 v[220:223], v[180:181], off offset:320
	global_load_dwordx4 v[224:227], v[180:181], off offset:352
	global_load_dwordx4 v[228:231], v[182:183], off offset:320
	global_load_dwordx4 v[232:235], v[182:183], off offset:352
	s_waitcnt vmcnt(10)
; __device__ __forceinline__ void dt_phase(Frame& F, const bf16* A, const bf16* Wdt, const unsigned long long* rowss, const float* dt_bias, float* dt_out) {
;     ...
; #pragma unroll 4
;         for (int ks = 0; ks < 32; ++ks) {
;             const bf16x8 a = *(const bf16x8*)(ap + ks * 16);
; #pragma unroll
;             for (int nb = 0; nb < 4; ++nb) { const bf16x8 b = *(const bf16x8*)(bp + (size_t)nb * 32 * D + ks * 16); acc[nb] = __builtin_amdgcn_mfma_f32_32x32x16_bf16(a, b, acc[nb], 0, 0, 0); }
;         }
	v_mfma_f32_32x32x16_bf16 v[50:65], v[140:143], v[148:151], v[50:65]
	v_mfma_f32_32x32x16_bf16 v[66:81], v[140:143], v[156:159], v[66:81]
	v_mfma_f32_32x32x16_bf16 v[18:33], v[140:143], v[164:167], v[18:33]
	v_mfma_f32_32x32x16_bf16 v[34:49], v[140:143], v[172:175], v[34:49]
	v_mfma_f32_32x32x16_bf16 v[50:65], v[144:147], v[152:155], v[50:65]
	v_mfma_f32_32x32x16_bf16 v[66:81], v[144:147], v[160:163], v[66:81]
	v_mfma_f32_32x32x16_bf16 v[18:33], v[144:147], v[168:171], v[18:33]
	v_mfma_f32_32x32x16_bf16 v[34:49], v[144:147], v[176:179], v[34:49]
	global_load_dwordx4 v[140:143], v[92:93], off offset:320
	global_load_dwordx4 v[144:147], v[92:93], off offset:352
	global_load_dwordx4 v[148:151], v[236:237], off offset:384
	global_load_dwordx4 v[152:155], v[236:237], off offset:416
	global_load_dwordx4 v[156:159], v[238:239], off offset:384
	global_load_dwordx4 v[160:163], v[238:239], off offset:416
	global_load_dwordx4 v[164:167], v[180:181], off offset:384
	global_load_dwordx4 v[168:171], v[180:181], off offset:416
	global_load_dwordx4 v[172:175], v[182:183], off offset:384
	global_load_dwordx4 v[176:179], v[182:183], off offset:416
	s_waitcnt vmcnt(10)
	v_mfma_f32_32x32x16_bf16 v[50:65], v[196:199], v[204:207], v[50:65]
	v_mfma_f32_32x32x16_bf16 v[66:81], v[196:199], v[212:215], v[66:81]
	v_mfma_f32_32x32x16_bf16 v[18:33], v[196:199], v[220:223], v[18:33]
	v_mfma_f32_32x32x16_bf16 v[34:49], v[196:199], v[228:231], v[34:49]
	v_mfma_f32_32x32x16_bf16 v[50:65], v[200:203], v[208:211], v[50:65]
	v_mfma_f32_32x32x16_bf16 v[66:81], v[200:203], v[216:219], v[66:81]
	v_mfma_f32_32x32x16_bf16 v[18:33], v[200:203], v[224:227], v[18:33]
	v_mfma_f32_32x32x16_bf16 v[34:49], v[200:203], v[232:235], v[34:49]
	global_load_dwordx4 v[196:199], v[92:93], off offset:384
	global_load_dwordx4 v[200:203], v[92:93], off offset:416
	global_load_dwordx4 v[204:207], v[236:237], off offset:448
	global_load_dwordx4 v[208:211], v[236:237], off offset:480
	global_load_dwordx4 v[212:215], v[238:239], off offset:448
	global_load_dwordx4 v[216:219], v[238:239], off offset:480
	global_load_dwordx4 v[220:223], v[180:181], off offset:448
	global_load_dwordx4 v[224:227], v[180:181], off offset:480
	global_load_dwordx4 v[228:231], v[182:183], off offset:448
	global_load_dwordx4 v[232:235], v[182:183], off offset:480
	s_waitcnt vmcnt(10)
	v_mfma_f32_32x32x16_bf16 v[50:65], v[140:143], v[148:151], v[50:65]
	v_mfma_f32_32x32x16_bf16 v[66:81], v[140:143], v[156:159], v[66:81]
	v_mfma_f32_32x32x16_bf16 v[18:33], v[140:143], v[164:167], v[18:33]
	v_mfma_f32_32x32x16_bf16 v[34:49], v[140:143], v[172:175], v[34:49]
	v_mfma_f32_32x32x16_bf16 v[50:65], v[144:147], v[152:155], v[50:65]
	v_mfma_f32_32x32x16_bf16 v[66:81], v[144:147], v[160:163], v[66:81]
	v_mfma_f32_32x32x16_bf16 v[18:33], v[144:147], v[168:171], v[18:33]
	v_mfma_f32_32x32x16_bf16 v[34:49], v[144:147], v[176:179], v[34:49]
	global_load_dwordx4 v[140:143], v[92:93], off offset:448
	global_load_dwordx4 v[144:147], v[92:93], off offset:480
	global_load_dwordx4 v[148:151], v[236:237], off offset:512
	global_load_dwordx4 v[152:155], v[236:237], off offset:544
	global_load_dwordx4 v[156:159], v[238:239], off offset:512
	global_load_dwordx4 v[160:163], v[238:239], off offset:544
	global_load_dwordx4 v[164:167], v[180:181], off offset:512
	global_load_dwordx4 v[168:171], v[180:181], off offset:544
	global_load_dwordx4 v[172:175], v[182:183], off offset:512
	global_load_dwordx4 v[176:179], v[182:183], off offset:544
	s_waitcnt vmcnt(10)
	v_mfma_f32_32x32x16_bf16 v[50:65], v[196:199], v[204:207], v[50:65]
	v_mfma_f32_32x32x16_bf16 v[66:81], v[196:199], v[212:215], v[66:81]
	v_mfma_f32_32x32x16_bf16 v[18:33], v[196:199], v[220:223], v[18:33]
	v_mfma_f32_32x32x16_bf16 v[34:49], v[196:199], v[228:231], v[34:49]
	v_mfma_f32_32x32x16_bf16 v[50:65], v[200:203], v[208:211], v[50:65]
	v_mfma_f32_32x32x16_bf16 v[66:81], v[200:203], v[216:219], v[66:81]
	v_mfma_f32_32x32x16_bf16 v[18:33], v[200:203], v[224:227], v[18:33]
	v_mfma_f32_32x32x16_bf16 v[34:49], v[200:203], v[232:235], v[34:49]
	global_load_dwordx4 v[196:199], v[92:93], off offset:512
	global_load_dwordx4 v[200:203], v[92:93], off offset:544
	global_load_dwordx4 v[204:207], v[236:237], off offset:576
	global_load_dwordx4 v[208:211], v[236:237], off offset:608
	global_load_dwordx4 v[212:215], v[238:239], off offset:576
	global_load_dwordx4 v[216:219], v[238:239], off offset:608
	global_load_dwordx4 v[220:223], v[180:181], off offset:576
	global_load_dwordx4 v[224:227], v[180:181], off offset:608
	global_load_dwordx4 v[228:231], v[182:183], off offset:576
	global_load_dwordx4 v[232:235], v[182:183], off offset:608
	s_waitcnt vmcnt(10)
	v_mfma_f32_32x32x16_bf16 v[50:65], v[140:143], v[148:151], v[50:65]
	v_mfma_f32_32x32x16_bf16 v[66:81], v[140:143], v[156:159], v[66:81]
	v_mfma_f32_32x32x16_bf16 v[18:33], v[140:143], v[164:167], v[18:33]
	v_mfma_f32_32x32x16_bf16 v[34:49], v[140:143], v[172:175], v[34:49]
	v_mfma_f32_32x32x16_bf16 v[50:65], v[144:147], v[152:155], v[50:65]
	v_mfma_f32_32x32x16_bf16 v[66:81], v[144:147], v[160:163], v[66:81]
	v_mfma_f32_32x32x16_bf16 v[18:33], v[144:147], v[168:171], v[18:33]
	v_mfma_f32_32x32x16_bf16 v[34:49], v[144:147], v[176:179], v[34:49]
	global_load_dwordx4 v[140:143], v[92:93], off offset:576
	global_load_dwordx4 v[144:147], v[92:93], off offset:608
	global_load_dwordx4 v[148:151], v[236:237], off offset:640
	global_load_dwordx4 v[152:155], v[236:237], off offset:672
	global_load_dwordx4 v[156:159], v[238:239], off offset:640
	global_load_dwordx4 v[160:163], v[238:239], off offset:672
	global_load_dwordx4 v[164:167], v[180:181], off offset:640
	global_load_dwordx4 v[168:171], v[180:181], off offset:672
	global_load_dwordx4 v[172:175], v[182:183], off offset:640
	global_load_dwordx4 v[176:179], v[182:183], off offset:672
	s_waitcnt vmcnt(10)
; __device__ __forceinline__ void dt_phase(Frame& F, const bf16* A, const bf16* Wdt, const unsigned long long* rowss, const float* dt_bias, float* dt_out) {
;     ...
; #pragma unroll 4
;         for (int ks = 0; ks < 32; ++ks) {
;             const bf16x8 a = *(const bf16x8*)(ap + ks * 16);
; #pragma unroll
;             for (int nb = 0; nb < 4; ++nb) { const bf16x8 b = *(const bf16x8*)(bp + (size_t)nb * 32 * D + ks * 16); acc[nb] = __builtin_amdgcn_mfma_f32_32x32x16_bf16(a, b, acc[nb], 0, 0, 0); }
;         }
	v_mfma_f32_32x32x16_bf16 v[50:65], v[196:199], v[204:207], v[50:65]
	v_mfma_f32_32x32x16_bf16 v[66:81], v[196:199], v[212:215], v[66:81]
	v_mfma_f32_32x32x16_bf16 v[18:33], v[196:199], v[220:223], v[18:33]
	v_mfma_f32_32x32x16_bf16 v[34:49], v[196:199], v[228:231], v[34:49]
	v_mfma_f32_32x32x16_bf16 v[50:65], v[200:203], v[208:211], v[50:65]
	v_mfma_f32_32x32x16_bf16 v[66:81], v[200:203], v[216:219], v[66:81]
	v_mfma_f32_32x32x16_bf16 v[18:33], v[200:203], v[224:227], v[18:33]
	v_mfma_f32_32x32x16_bf16 v[34:49], v[200:203], v[232:235], v[34:49]
	global_load_dwordx4 v[196:199], v[92:93], off offset:640
	global_load_dwordx4 v[200:203], v[92:93], off offset:672
	global_load_dwordx4 v[204:207], v[236:237], off offset:704
	global_load_dwordx4 v[208:211], v[236:237], off offset:736
	global_load_dwordx4 v[212:215], v[238:239], off offset:704
	global_load_dwordx4 v[216:219], v[238:239], off offset:736
	global_load_dwordx4 v[220:223], v[180:181], off offset:704
	global_load_dwordx4 v[224:227], v[180:181], off offset:736
	global_load_dwordx4 v[228:231], v[182:183], off offset:704
	global_load_dwordx4 v[232:235], v[182:183], off offset:736
	s_waitcnt vmcnt(10)
	v_mfma_f32_32x32x16_bf16 v[50:65], v[140:143], v[148:151], v[50:65]
	v_mfma_f32_32x32x16_bf16 v[66:81], v[140:143], v[156:159], v[66:81]
	v_mfma_f32_32x32x16_bf16 v[18:33], v[140:143], v[164:167], v[18:33]
	v_mfma_f32_32x32x16_bf16 v[34:49], v[140:143], v[172:175], v[34:49]
	v_mfma_f32_32x32x16_bf16 v[50:65], v[144:147], v[152:155], v[50:65]
	v_mfma_f32_32x32x16_bf16 v[66:81], v[144:147], v[160:163], v[66:81]
	v_mfma_f32_32x32x16_bf16 v[18:33], v[144:147], v[168:171], v[18:33]
	v_mfma_f32_32x32x16_bf16 v[34:49], v[144:147], v[176:179], v[34:49]
	global_load_dwordx4 v[140:143], v[92:93], off offset:704
	global_load_dwordx4 v[144:147], v[92:93], off offset:736
	global_load_dwordx4 v[148:151], v[236:237], off offset:768
	global_load_dwordx4 v[152:155], v[236:237], off offset:800
	global_load_dwordx4 v[156:159], v[238:239], off offset:768
	global_load_dwordx4 v[160:163], v[238:239], off offset:800
	global_load_dwordx4 v[164:167], v[180:181], off offset:768
	global_load_dwordx4 v[168:171], v[180:181], off offset:800
	global_load_dwordx4 v[172:175], v[182:183], off offset:768
	global_load_dwordx4 v[176:179], v[182:183], off offset:800
	s_waitcnt vmcnt(10)
	v_mfma_f32_32x32x16_bf16 v[50:65], v[196:199], v[204:207], v[50:65]
	v_mfma_f32_32x32x16_bf16 v[66:81], v[196:199], v[212:215], v[66:81]
	v_mfma_f32_32x32x16_bf16 v[18:33], v[196:199], v[220:223], v[18:33]
	v_mfma_f32_32x32x16_bf16 v[34:49], v[196:199], v[228:231], v[34:49]
	v_mfma_f32_32x32x16_bf16 v[50:65], v[200:203], v[208:211], v[50:65]
	v_mfma_f32_32x32x16_bf16 v[66:81], v[200:203], v[216:219], v[66:81]
	v_mfma_f32_32x32x16_bf16 v[18:33], v[200:203], v[224:227], v[18:33]
	v_mfma_f32_32x32x16_bf16 v[34:49], v[200:203], v[232:235], v[34:49]
	global_load_dwordx4 v[196:199], v[92:93], off offset:768
	global_load_dwordx4 v[200:203], v[92:93], off offset:800
	global_load_dwordx4 v[204:207], v[236:237], off offset:832
	global_load_dwordx4 v[208:211], v[236:237], off offset:864
	global_load_dwordx4 v[212:215], v[238:239], off offset:832
	global_load_dwordx4 v[216:219], v[238:239], off offset:864
	global_load_dwordx4 v[220:223], v[180:181], off offset:832
	global_load_dwordx4 v[224:227], v[180:181], off offset:864
	global_load_dwordx4 v[228:231], v[182:183], off offset:832
	global_load_dwordx4 v[232:235], v[182:183], off offset:864
	s_waitcnt vmcnt(10)
	v_mfma_f32_32x32x16_bf16 v[50:65], v[140:143], v[148:151], v[50:65]
	v_mfma_f32_32x32x16_bf16 v[66:81], v[140:143], v[156:159], v[66:81]
	v_mfma_f32_32x32x16_bf16 v[18:33], v[140:143], v[164:167], v[18:33]
	v_mfma_f32_32x32x16_bf16 v[34:49], v[140:143], v[172:175], v[34:49]
	v_mfma_f32_32x32x16_bf16 v[50:65], v[144:147], v[152:155], v[50:65]
	v_mfma_f32_32x32x16_bf16 v[66:81], v[144:147], v[160:163], v[66:81]
	v_mfma_f32_32x32x16_bf16 v[18:33], v[144:147], v[168:171], v[18:33]
	v_mfma_f32_32x32x16_bf16 v[34:49], v[144:147], v[176:179], v[34:49]
	global_load_dwordx4 v[140:143], v[92:93], off offset:832
	global_load_dwordx4 v[144:147], v[92:93], off offset:864
	global_load_dwordx4 v[148:151], v[236:237], off offset:896
	global_load_dwordx4 v[152:155], v[236:237], off offset:928
	global_load_dwordx4 v[156:159], v[238:239], off offset:896
	global_load_dwordx4 v[160:163], v[238:239], off offset:928
	global_load_dwordx4 v[164:167], v[180:181], off offset:896
	global_load_dwordx4 v[168:171], v[180:181], off offset:928
	global_load_dwordx4 v[172:175], v[182:183], off offset:896
	global_load_dwordx4 v[176:179], v[182:183], off offset:928
	s_waitcnt vmcnt(10)
	v_mfma_f32_32x32x16_bf16 v[50:65], v[196:199], v[204:207], v[50:65]
	v_mfma_f32_32x32x16_bf16 v[66:81], v[196:199], v[212:215], v[66:81]
	v_mfma_f32_32x32x16_bf16 v[18:33], v[196:199], v[220:223], v[18:33]
	v_mfma_f32_32x32x16_bf16 v[34:49], v[196:199], v[228:231], v[34:49]
	v_mfma_f32_32x32x16_bf16 v[50:65], v[200:203], v[208:211], v[50:65]
	v_mfma_f32_32x32x16_bf16 v[66:81], v[200:203], v[216:219], v[66:81]
	v_mfma_f32_32x32x16_bf16 v[18:33], v[200:203], v[224:227], v[18:33]
	v_mfma_f32_32x32x16_bf16 v[34:49], v[200:203], v[232:235], v[34:49]
	global_load_dwordx4 v[196:199], v[92:93], off offset:896
	global_load_dwordx4 v[200:203], v[92:93], off offset:928
	global_load_dwordx4 v[204:207], v[236:237], off offset:960
	global_load_dwordx4 v[208:211], v[236:237], off offset:992
	global_load_dwordx4 v[212:215], v[238:239], off offset:960
	global_load_dwordx4 v[216:219], v[238:239], off offset:992
	global_load_dwordx4 v[220:223], v[180:181], off offset:960
	global_load_dwordx4 v[224:227], v[180:181], off offset:992
	global_load_dwordx4 v[228:231], v[182:183], off offset:960
	global_load_dwordx4 v[232:235], v[182:183], off offset:992
	s_waitcnt vmcnt(10)
; __device__ __forceinline__ void dt_phase(Frame& F, const bf16* A, const bf16* Wdt, const unsigned long long* rowss, const float* dt_bias, float* dt_out) {
;     ...
;             for (int nb = 0; nb < 4; ++nb) { const bf16x8 b = *(const bf16x8*)(bp + (size_t)nb * 32 * D + ks * 16); acc[nb] = __builtin_amdgcn_mfma_f32_32x32x16_bf16(a, b, acc[nb], 0, 0, 0); }
;         }
; #pragma unroll
;         for (int nb = 0; nb < 4; ++nb)
; #pragma unroll
;             for (int j = 0; j < 16; ++j) { const int row = (j & 3) + 8 * (j >> 2) + 4 * hh; P[F.wave * 4096 + row * 128 + nb * 32 + r] = acc[nb][j]; }
;         __syncthreads();
; #pragma unroll
;         for (int j = 0; j < 8; ++j) { const int idx = F.tid + 512 * j; float s = 0.f;
; #pragma unroll
;             for (int w = 0; w < 8; ++w) s += P[w * 4096 + idx];
;             const int row = u * 32 + (idx >> 7), col = idx & 127;
;             const float v = s * rsqrtf((float)rowss[row] * (1.0f / (4096.0f * 16777216.0f)) + RMS_EPS) + dt_bias[col];
	v_mfma_f32_32x32x16_bf16 v[50:65], v[140:143], v[148:151], v[50:65]
	v_mfma_f32_32x32x16_bf16 v[66:81], v[140:143], v[156:159], v[66:81]
	v_mfma_f32_32x32x16_bf16 v[18:33], v[140:143], v[164:167], v[18:33]
	v_mfma_f32_32x32x16_bf16 v[34:49], v[140:143], v[172:175], v[34:49]
	v_mfma_f32_32x32x16_bf16 v[50:65], v[144:147], v[152:155], v[50:65]
	v_mfma_f32_32x32x16_bf16 v[66:81], v[144:147], v[160:163], v[66:81]
	v_mfma_f32_32x32x16_bf16 v[18:33], v[144:147], v[168:171], v[18:33]
	v_mfma_f32_32x32x16_bf16 v[34:49], v[144:147], v[176:179], v[34:49]
	s_waitcnt vmcnt(0)
	v_mfma_f32_32x32x16_bf16 v[50:65], v[196:199], v[204:207], v[50:65]
	v_mfma_f32_32x32x16_bf16 v[66:81], v[196:199], v[212:215], v[66:81]
	v_mfma_f32_32x32x16_bf16 v[18:33], v[196:199], v[220:223], v[18:33]
	v_mfma_f32_32x32x16_bf16 v[34:49], v[196:199], v[228:231], v[34:49]
	v_mfma_f32_32x32x16_bf16 v[50:65], v[200:203], v[208:211], v[50:65]
	v_mfma_f32_32x32x16_bf16 v[66:81], v[200:203], v[216:219], v[66:81]
	v_mfma_f32_32x32x16_bf16 v[18:33], v[200:203], v[224:227], v[18:33]
	v_mfma_f32_32x32x16_bf16 v[34:49], v[200:203], v[232:235], v[34:49]
	s_nop 15
	s_nop 1
	ds_write2_b32 v1, v50, v66 offset1:32
	ds_write2_b32 v1, v51, v67 offset0:128 offset1:160
	v_add_u32_e32 v50, 0x400, v1
	ds_write2_b32 v50, v52, v68 offset1:32
	ds_write2_b32 v50, v53, v69 offset0:128 offset1:160
	v_add_u32_e32 v51, 0x1000, v1
	v_add_u32_e32 v52, 0x1400, v1
	s_lshl_b32 s0, s8, 5
	ds_write2_b32 v51, v54, v70 offset1:32
	ds_write2_b32 v51, v55, v71 offset0:128 offset1:160
	ds_write2_b32 v52, v56, v72 offset1:32
	ds_write2_b32 v52, v57, v73 offset0:128 offset1:160
	v_add_u32_e32 v53, 0x2000, v1
	v_add_u32_e32 v54, 0x2400, v1
	v_add_u32_e32 v55, 0x3000, v1
	v_add_u32_e32 v56, 0x3400, v1
	ds_write2_b32 v53, v58, v74 offset1:32
	ds_write2_b32 v53, v59, v75 offset0:128 offset1:160
	ds_write2_b32 v54, v60, v76 offset1:32
	ds_write2_b32 v54, v61, v77 offset0:128 offset1:160
	ds_write2_b32 v55, v62, v78 offset1:32
	ds_write2_b32 v55, v63, v79 offset0:128 offset1:160
	ds_write2_b32 v56, v64, v80 offset1:32
	ds_write2_b32 v56, v65, v81 offset0:128 offset1:160
	ds_write2_b32 v1, v18, v34 offset0:64 offset1:96
	ds_write2_b32 v1, v19, v35 offset0:192 offset1:224
	ds_write2_b32 v50, v20, v36 offset0:64 offset1:96
	ds_write2_b32 v50, v21, v37 offset0:192 offset1:224
	ds_write2_b32 v51, v22, v38 offset0:64 offset1:96
	ds_write2_b32 v51, v23, v39 offset0:192 offset1:224
	ds_write2_b32 v52, v24, v40 offset0:64 offset1:96
	ds_write2_b32 v52, v25, v41 offset0:192 offset1:224
	ds_write2_b32 v53, v26, v42 offset0:64 offset1:96
	ds_write2_b32 v53, v27, v43 offset0:192 offset1:224
	ds_write2_b32 v54, v28, v44 offset0:64 offset1:96
	ds_write2_b32 v54, v29, v45 offset0:192 offset1:224
	ds_write2_b32 v55, v30, v46 offset0:64 offset1:96
	ds_write2_b32 v55, v31, v47 offset0:192 offset1:224
	ds_write2_b32 v56, v32, v48 offset0:64 offset1:96
	ds_write2_b32 v56, v33, v49 offset0:192 offset1:224
	v_or_b32_e32 v20, s0, v99
	v_ashrrev_i32_e32 v21, 31, v20
	v_lshl_add_u64 v[18:19], v[20:21], 3, s[18:19]
	s_waitcnt lgkmcnt(0)
	s_barrier
	global_load_dwordx2 v[34:35], v[18:19], off
	global_load_dword v40, v[82:83], off
	ds_read2st64_b32 v[24:25], v94 offset1:8
	ds_read2st64_b32 v[26:27], v94 offset0:64 offset1:72
	ds_read2st64_b32 v[28:29], v94 offset0:128 offset1:136
	ds_read2st64_b32 v[22:23], v94 offset0:192 offset1:200
	ds_read_b32 v50, v95
	ds_read_b32 v51, v96
	ds_read_b32 v52, v97
	ds_read_b32 v53, v98
	ds_read_b32 v54, v100
	ds_read_b32 v41, v101
	ds_read_b32 v55, v102
	ds_read_b32 v56, v103
	s_waitcnt lgkmcnt(11)
	v_add_f32_e32 v24, 0, v24
	s_waitcnt lgkmcnt(10)
	v_add_f32_e32 v24, v24, v26
	s_waitcnt lgkmcnt(9)
	v_add_f32_e32 v24, v24, v28
	s_waitcnt lgkmcnt(8)
	v_add_f32_e32 v22, v24, v22
	s_waitcnt lgkmcnt(7)
	v_add_f32_e32 v22, v22, v50
	s_waitcnt lgkmcnt(6)
	v_add_f32_e32 v22, v22, v51
	s_waitcnt lgkmcnt(5)
	v_add_f32_e32 v22, v22, v52
	s_waitcnt lgkmcnt(4)
	v_add_f32_e32 v22, v22, v53
	v_or_b32_e32 v30, s0, v104
	v_or_b32_e32 v32, s0, v109
	v_or_b32_e32 v18, s0, v114
	v_ashrrev_i32_e32 v31, 31, v30
	v_ashrrev_i32_e32 v33, 31, v32
	v_ashrrev_i32_e32 v19, 31, v18
	v_lshl_add_u64 v[42:43], v[30:31], 3, s[18:19]
	v_lshl_add_u64 v[44:45], v[32:33], 3, s[18:19]
	v_lshl_add_u64 v[46:47], v[18:19], 3, s[18:19]
	global_load_dwordx2 v[48:49], v[42:43], off
	global_load_dwordx2 v[38:39], v[44:45], off
	global_load_dwordx2 v[36:37], v[46:47], off
	v_lshlrev_b64 v[20:21], 9, v[20:21]
	v_lshl_add_u64 v[20:21], v[84:85], 0, v[20:21]
	v_lshlrev_b64 v[18:19], 9, v[18:19]
	v_lshl_add_u64 v[18:19], v[84:85], 0, v[18:19]
	v_add_u32_e32 v90, s20, v90
	s_waitcnt vmcnt(4)
	v_ffbh_u32_e32 v26, v35
	v_min_u32_e32 v26, 32, v26
	v_lshlrev_b64 v[34:35], v26, v[34:35]
	v_min_u32_e32 v28, 1, v34
	v_or_b32_e32 v28, v35, v28
	v_cvt_f32_u32_e32 v28, v28
	v_sub_u32_e32 v24, 32, v26
	v_ldexp_f32 v24, v28, v24
	v_fmamk_f32 v24, v24, 0x2d800000, v135
	v_mul_f32_e32 v26, 0x4b800000, v24
	v_cmp_gt_f32_e32 vcc, s2, v24
	s_nop 1
	v_cndmask_b32_e32 v24, v24, v26, vcc
	v_rsq_f32_e32 v24, v24
	s_nop 0
	v_mul_f32_e32 v26, 0x45800000, v24
	v_cndmask_b32_e32 v24, v24, v26, vcc
	s_waitcnt vmcnt(3)
; __device__ __forceinline__ void dt_phase(Frame& F, const bf16* A, const bf16* Wdt, const unsigned long long* rowss, const float* dt_bias, float* dt_out) {
;     ...
;         for (int j = 0; j < 8; ++j) { const int idx = F.tid + 512 * j; float s = 0.f;
; #pragma unroll
;             for (int w = 0; w < 8; ++w) s += P[w * 4096 + idx];
;             const int row = u * 32 + (idx >> 7), col = idx & 127;
;             const float v = s * rsqrtf((float)rowss[row] * (1.0f / (4096.0f * 16777216.0f)) + RMS_EPS) + dt_bias[col];
;             dt_out[(size_t)row * 128 + col] = fmaxf(v, 0.f) + log1pf(__expf(-fabsf(v))); }
	v_fmac_f32_e32 v40, v22, v24
	v_mul_f32_e64 v22, |v40|, s3
	v_exp_f32_e32 v22, v22
	v_max_f32_e32 v24, 0, v40
	v_add_f32_e32 v26, 1.0, v22
	v_add_f32_e32 v28, -1.0, v26
	v_frexp_mant_f32_e32 v40, v26
	v_cvt_f64_f32_e32 v[34:35], v26
	v_sub_f32_e32 v42, v28, v26
	v_frexp_exp_i32_f64_e32 v34, v[34:35]
	v_cmp_gt_f32_e32 vcc, s4, v40
	v_sub_f32_e32 v28, v22, v28
	v_add_f32_e32 v35, 1.0, v42
	v_subbrev_co_u32_e32 v34, vcc, 0, v34, vcc
	v_add_f32_e32 v28, v28, v35
	v_sub_u32_e32 v35, 0, v34
	v_ldexp_f32 v26, v26, v35
	v_ldexp_f32 v28, v28, v35
	v_add_f32_e32 v35, -1.0, v26
	v_add_f32_e32 v40, 1.0, v26
	v_add_f32_e32 v42, 1.0, v35
	v_add_f32_e32 v44, -1.0, v40
	v_sub_f32_e32 v42, v26, v42
	v_sub_f32_e32 v26, v26, v44
	v_add_f32_e32 v26, v28, v26
	v_add_f32_e32 v42, v28, v42
	v_add_f32_e32 v28, v40, v26
	v_rcp_f32_e32 v44, v28
	v_add_f32_e32 v43, v35, v42
	v_sub_f32_e32 v40, v28, v40
	v_sub_f32_e32 v35, v43, v35
	v_sub_f32_e32 v26, v26, v40
	v_mul_f32_e32 v40, v43, v44
	v_sub_f32_e32 v35, v42, v35
	v_mul_f32_e32 v42, v28, v40
	v_fma_f32 v45, v40, v28, -v42
	v_fmac_f32_e32 v45, v40, v26
	v_add_f32_e32 v46, v42, v45
	v_sub_f32_e32 v47, v43, v46
	v_sub_f32_e32 v43, v43, v47
	v_sub_f32_e32 v42, v46, v42
	v_sub_f32_e32 v43, v43, v46
	v_add_f32_e32 v35, v35, v43
	v_sub_f32_e32 v42, v42, v45
	v_add_f32_e32 v35, v42, v35
	v_add_f32_e32 v42, v47, v35
	v_mul_f32_e32 v43, v44, v42
	v_mul_f32_e32 v45, v28, v43
	v_fma_f32 v28, v43, v28, -v45
	v_fmac_f32_e32 v28, v43, v26
	v_sub_f32_e32 v26, v47, v42
	v_add_f32_e32 v26, v35, v26
	v_add_f32_e32 v35, v45, v28
	v_sub_f32_e32 v46, v42, v35
	v_sub_f32_e32 v42, v42, v46
	v_sub_f32_e32 v45, v35, v45
	v_sub_f32_e32 v35, v42, v35
	v_add_f32_e32 v26, v26, v35
	v_sub_f32_e32 v28, v45, v28
	v_cvt_f32_i32_e32 v34, v34
	v_add_f32_e32 v26, v28, v26
	v_add_f32_e32 v28, v40, v43
	v_add_f32_e32 v26, v46, v26
	v_sub_f32_e32 v35, v28, v40
	v_mul_f32_e32 v26, v44, v26
	v_sub_f32_e32 v35, v43, v35
	v_add_f32_e32 v26, v35, v26
	v_mul_f32_e32 v43, 0x3f317218, v34
	v_add_f32_e32 v35, v28, v26
	v_fma_f32 v44, v34, s5, -v43
	v_mul_f32_e32 v40, v35, v35
	v_fmac_f32_e32 v44, 0xb102e308, v34
	v_sub_f32_e32 v28, v35, v28
	v_fmamk_f32 v42, v40, 0x3e9b6dac, v136
	v_sub_f32_e32 v26, v26, v28
	v_add_f32_e32 v28, v43, v44
	v_fmaak_f32 v42, v40, v42, 0x3f2aaada
	v_sub_f32_e32 v34, v28, v43
	v_ldexp_f32 v43, v35, 1
	v_mul_f32_e32 v35, v35, v40
	v_mul_f32_e32 v35, v35, v42
	v_add_f32_e32 v40, v43, v35
	v_sub_f32_e32 v42, v40, v43
	v_ldexp_f32 v26, v26, 1
	v_sub_f32_e32 v35, v35, v42
	v_add_f32_e32 v26, v26, v35
	v_add_f32_e32 v35, v40, v26
	v_sub_f32_e32 v40, v35, v40
	v_sub_f32_e32 v26, v26, v40
	v_add_f32_e32 v40, v28, v35
	v_sub_f32_e32 v42, v40, v28
	v_sub_f32_e32 v43, v40, v42
	v_sub_f32_e32 v34, v44, v34
	v_sub_f32_e32 v28, v28, v43
	v_sub_f32_e32 v35, v35, v42
	v_add_f32_e32 v28, v35, v28
	v_add_f32_e32 v35, v34, v26
	v_sub_f32_e32 v42, v35, v34
	v_sub_f32_e32 v43, v35, v42
	v_sub_f32_e32 v34, v34, v43
	v_sub_f32_e32 v26, v26, v42
	v_add_f32_e32 v28, v35, v28
	v_add_f32_e32 v26, v26, v34
	v_add_f32_e32 v34, v40, v28
	v_sub_f32_e32 v35, v34, v40
	v_sub_f32_e32 v28, v28, v35
	v_add_f32_e32 v26, v26, v28
	v_add_f32_e32 v26, v34, v26
	v_cmp_neq_f32_e32 vcc, s6, v22
	s_nop 1
	v_cndmask_b32_e32 v26, v137, v26, vcc
	v_cmp_ngt_f32_e32 vcc, -1.0, v22
	s_nop 1
	v_cndmask_b32_e32 v26, v138, v26, vcc
	v_cmp_neq_f32_e32 vcc, -1.0, v22
	s_nop 1
	v_cndmask_b32_e32 v26, v139, v26, vcc
	v_cmp_lt_f32_e64 vcc, |v22|, s7
	s_nop 1
	v_cndmask_b32_e32 v22, v26, v22, vcc
	v_add_f32_e32 v22, v24, v22
	global_store_dword v[20:21], v22, off
	global_load_dword v22, v[82:83], off
	v_add_f32_e32 v20, 0, v25
	v_add_f32_e32 v20, v20, v27
	v_add_f32_e32 v24, v20, v29
	s_waitcnt vmcnt(4)
	v_ffbh_u32_e32 v20, v49
	v_min_u32_e32 v25, 32, v20
	v_lshlrev_b64 v[20:21], v25, v[48:49]
	v_min_u32_e32 v20, 1, v20
	v_or_b32_e32 v20, v21, v20
	v_cvt_f32_u32_e32 v20, v20
	v_add_f32_e32 v21, v24, v23
	v_sub_u32_e32 v23, 32, v25
	s_waitcnt lgkmcnt(3)
	v_add_f32_e32 v21, v21, v54
	v_ldexp_f32 v20, v20, v23
	v_fmamk_f32 v20, v20, 0x2d800000, v135
	v_mul_f32_e32 v23, 0x4b800000, v20
	v_cmp_gt_f32_e32 vcc, s2, v20
	s_waitcnt lgkmcnt(2)
	v_add_f32_e32 v21, v21, v41
	s_waitcnt lgkmcnt(1)
	v_add_f32_e32 v21, v21, v55
	v_cndmask_b32_e32 v20, v20, v23, vcc
	v_rsq_f32_e32 v20, v20
	s_waitcnt lgkmcnt(0)
	v_add_f32_e32 v21, v21, v56
	v_mul_f32_e32 v23, 0x45800000, v20
	v_cndmask_b32_e32 v20, v20, v23, vcc
	s_waitcnt vmcnt(0)
; __device__ __forceinline__ void dt_phase(Frame& F, const bf16* A, const bf16* Wdt, const unsigned long long* rowss, const float* dt_bias, float* dt_out) {
;     ...
;         for (int j = 0; j < 8; ++j) { const int idx = F.tid + 512 * j; float s = 0.f;
; #pragma unroll
;             for (int w = 0; w < 8; ++w) s += P[w * 4096 + idx];
;             const int row = u * 32 + (idx >> 7), col = idx & 127;
;             const float v = s * rsqrtf((float)rowss[row] * (1.0f / (4096.0f * 16777216.0f)) + RMS_EPS) + dt_bias[col];
;             dt_out[(size_t)row * 128 + col] = fmaxf(v, 0.f) + log1pf(__expf(-fabsf(v))); }
	v_fmac_f32_e32 v22, v21, v20
	v_mul_f32_e64 v20, |v22|, s3
	v_exp_f32_e32 v23, v20
	v_max_f32_e32 v22, 0, v22
	v_add_f32_e32 v24, 1.0, v23
	v_add_f32_e32 v25, -1.0, v24
	v_frexp_mant_f32_e32 v26, v24
	v_cvt_f64_f32_e32 v[20:21], v24
	v_sub_f32_e32 v27, v25, v24
	v_frexp_exp_i32_f64_e32 v20, v[20:21]
	v_cmp_gt_f32_e32 vcc, s4, v26
	v_sub_f32_e32 v25, v23, v25
	v_add_f32_e32 v21, 1.0, v27
	v_subbrev_co_u32_e32 v20, vcc, 0, v20, vcc
	v_add_f32_e32 v21, v25, v21
	v_sub_u32_e32 v25, 0, v20
	v_ldexp_f32 v24, v24, v25
	v_ldexp_f32 v21, v21, v25
	v_add_f32_e32 v25, -1.0, v24
	v_add_f32_e32 v26, 1.0, v24
	v_add_f32_e32 v27, 1.0, v25
	v_add_f32_e32 v28, -1.0, v26
	v_sub_f32_e32 v27, v24, v27
	v_sub_f32_e32 v24, v24, v28
	v_add_f32_e32 v27, v21, v27
	v_add_f32_e32 v21, v21, v24
	v_add_f32_e32 v28, v26, v21
	v_rcp_f32_e32 v29, v28
	v_add_f32_e32 v24, v25, v27
	v_sub_f32_e32 v26, v28, v26
	v_sub_f32_e32 v25, v24, v25
	v_sub_f32_e32 v21, v21, v26
	v_mul_f32_e32 v26, v24, v29
	v_sub_f32_e32 v25, v27, v25
	v_mul_f32_e32 v27, v28, v26
	v_fma_f32 v34, v26, v28, -v27
	v_fmac_f32_e32 v34, v26, v21
	v_add_f32_e32 v35, v27, v34
	v_sub_f32_e32 v40, v24, v35
	v_sub_f32_e32 v24, v24, v40
	v_sub_f32_e32 v27, v35, v27
	v_sub_f32_e32 v24, v24, v35
	v_sub_f32_e32 v27, v27, v34
	v_add_f32_e32 v24, v25, v24
	v_add_f32_e32 v24, v27, v24
	v_add_f32_e32 v25, v40, v24
	v_mul_f32_e32 v27, v29, v25
	v_mul_f32_e32 v34, v28, v27
	v_fma_f32 v28, v27, v28, -v34
	v_fmac_f32_e32 v28, v27, v21
	v_sub_f32_e32 v21, v40, v25
	v_add_f32_e32 v21, v24, v21
	v_add_f32_e32 v24, v34, v28
	v_sub_f32_e32 v35, v25, v24
	v_sub_f32_e32 v25, v25, v35
	v_sub_f32_e32 v34, v24, v34
	v_sub_f32_e32 v24, v25, v24
	v_add_f32_e32 v21, v21, v24
	v_sub_f32_e32 v24, v34, v28
	v_cvt_f32_i32_e32 v20, v20
	v_add_f32_e32 v21, v24, v21
	v_add_f32_e32 v24, v26, v27
	v_add_f32_e32 v21, v35, v21
	v_sub_f32_e32 v25, v24, v26
	v_mul_f32_e32 v21, v29, v21
	v_sub_f32_e32 v25, v27, v25
	v_add_f32_e32 v21, v25, v21
	v_mul_f32_e32 v28, 0x3f317218, v20
	v_add_f32_e32 v25, v24, v21
	v_fma_f32 v29, v20, s5, -v28
	v_mul_f32_e32 v26, v25, v25
	v_fmac_f32_e32 v29, 0xb102e308, v20
	v_sub_f32_e32 v20, v25, v24
	v_fmamk_f32 v27, v26, 0x3e9b6dac, v136
	v_sub_f32_e32 v20, v21, v20
	v_add_f32_e32 v21, v28, v29
	v_fmaak_f32 v27, v26, v27, 0x3f2aaada
	v_sub_f32_e32 v24, v21, v28
	v_ldexp_f32 v28, v25, 1
	v_mul_f32_e32 v25, v25, v26
	v_mul_f32_e32 v25, v25, v27
	v_add_f32_e32 v26, v28, v25
	v_sub_f32_e32 v27, v26, v28
	v_ldexp_f32 v20, v20, 1
	v_sub_f32_e32 v25, v25, v27
	v_add_f32_e32 v20, v20, v25
	v_add_f32_e32 v25, v26, v20
	v_sub_f32_e32 v26, v25, v26
	v_sub_f32_e32 v20, v20, v26
	v_add_f32_e32 v26, v21, v25
	v_sub_f32_e32 v27, v26, v21
	v_sub_f32_e32 v28, v26, v27
	v_sub_f32_e32 v24, v29, v24
	v_sub_f32_e32 v21, v21, v28
	v_sub_f32_e32 v25, v25, v27
	v_add_f32_e32 v21, v25, v21
	v_add_f32_e32 v25, v24, v20
	v_sub_f32_e32 v27, v25, v24
	v_sub_f32_e32 v28, v25, v27
	v_sub_f32_e32 v24, v24, v28
	v_sub_f32_e32 v20, v20, v27
	v_add_f32_e32 v21, v25, v21
	v_add_f32_e32 v20, v20, v24
	v_add_f32_e32 v24, v26, v21
	v_sub_f32_e32 v25, v24, v26
	v_sub_f32_e32 v21, v21, v25
	v_add_f32_e32 v20, v20, v21
	v_add_f32_e32 v20, v24, v20
	v_cmp_neq_f32_e32 vcc, s6, v23
	s_nop 1
	v_cndmask_b32_e32 v20, v137, v20, vcc
	v_cmp_ngt_f32_e32 vcc, -1.0, v23
	s_nop 1
	v_cndmask_b32_e32 v20, v138, v20, vcc
	v_cmp_neq_f32_e32 vcc, -1.0, v23
	s_nop 1
	v_cndmask_b32_e32 v20, v139, v20, vcc
	v_cmp_lt_f32_e64 vcc, |v23|, s7
	s_nop 1
	v_cndmask_b32_e32 v20, v20, v23, vcc
	v_add_f32_e32 v22, v22, v20
	v_lshlrev_b64 v[20:21], 9, v[30:31]
	v_lshl_add_u64 v[20:21], v[84:85], 0, v[20:21]
	global_store_dword v[20:21], v22, off
	global_load_dword v30, v[82:83], off
	ds_read2st64_b32 v[20:21], v94 offset0:16 offset1:24
	ds_read2st64_b32 v[22:23], v94 offset0:80 offset1:88
	ds_read2st64_b32 v[24:25], v94 offset0:144 offset1:152
	ds_read2st64_b32 v[26:27], v94 offset0:208 offset1:216
	ds_read_b32 v31, v105
	ds_read_b32 v34, v106
	ds_read_b32 v35, v107
	ds_read_b32 v40, v108
	ds_read_b32 v41, v110
	ds_read_b32 v42, v111
	ds_read_b32 v43, v112
	ds_read_b32 v44, v113
	s_waitcnt lgkmcnt(11)
	v_add_f32_e32 v20, 0, v20
	s_waitcnt lgkmcnt(10)
	v_add_f32_e32 v20, v20, v22
	v_ffbh_u32_e32 v22, v39
	v_min_u32_e32 v22, 32, v22
	v_lshlrev_b64 v[28:29], v22, v[38:39]
	s_waitcnt lgkmcnt(9)
	v_add_f32_e32 v20, v20, v24
	v_min_u32_e32 v24, 1, v28
	v_or_b32_e32 v24, v29, v24
	v_cvt_f32_u32_e32 v24, v24
	v_sub_u32_e32 v22, 32, v22
	s_waitcnt lgkmcnt(8)
	v_add_f32_e32 v20, v20, v26
	s_waitcnt lgkmcnt(7)
	v_add_f32_e32 v20, v20, v31
	v_ldexp_f32 v22, v24, v22
	v_fmamk_f32 v22, v22, 0x2d800000, v135
	v_mul_f32_e32 v24, 0x4b800000, v22
	v_cmp_gt_f32_e32 vcc, s2, v22
	s_waitcnt lgkmcnt(6)
	v_add_f32_e32 v20, v20, v34
	s_waitcnt lgkmcnt(5)
	v_add_f32_e32 v20, v20, v35
	v_cndmask_b32_e32 v22, v22, v24, vcc
	v_rsq_f32_e32 v22, v22
	s_waitcnt lgkmcnt(4)
	v_add_f32_e32 v20, v20, v40
	v_mul_f32_e32 v24, 0x45800000, v22
	v_cndmask_b32_e32 v22, v22, v24, vcc
	s_waitcnt vmcnt(0)
; __device__ __forceinline__ void dt_phase(Frame& F, const bf16* A, const bf16* Wdt, const unsigned long long* rowss, const float* dt_bias, float* dt_out) {
;     ...
;         for (int j = 0; j < 8; ++j) { const int idx = F.tid + 512 * j; float s = 0.f;
; #pragma unroll
;             for (int w = 0; w < 8; ++w) s += P[w * 4096 + idx];
;             const int row = u * 32 + (idx >> 7), col = idx & 127;
;             const float v = s * rsqrtf((float)rowss[row] * (1.0f / (4096.0f * 16777216.0f)) + RMS_EPS) + dt_bias[col];
;             dt_out[(size_t)row * 128 + col] = fmaxf(v, 0.f) + log1pf(__expf(-fabsf(v))); }
	v_fmac_f32_e32 v30, v20, v22
	v_mul_f32_e64 v20, |v30|, s3
	v_exp_f32_e32 v20, v20
	v_max_f32_e32 v22, 0, v30
	v_add_f32_e32 v24, 1.0, v20
	v_add_f32_e32 v26, -1.0, v24
	v_frexp_mant_f32_e32 v30, v24
	v_cvt_f64_f32_e32 v[28:29], v24
	v_sub_f32_e32 v31, v26, v24
	v_frexp_exp_i32_f64_e32 v28, v[28:29]
	v_cmp_gt_f32_e32 vcc, s4, v30
	v_sub_f32_e32 v26, v20, v26
	v_add_f32_e32 v29, 1.0, v31
	v_subbrev_co_u32_e32 v28, vcc, 0, v28, vcc
	v_add_f32_e32 v26, v26, v29
	v_sub_u32_e32 v29, 0, v28
	v_ldexp_f32 v24, v24, v29
	v_ldexp_f32 v26, v26, v29
	v_add_f32_e32 v29, -1.0, v24
	v_add_f32_e32 v30, 1.0, v24
	v_add_f32_e32 v31, 1.0, v29
	v_add_f32_e32 v34, -1.0, v30
	v_sub_f32_e32 v31, v24, v31
	v_sub_f32_e32 v24, v24, v34
	v_add_f32_e32 v24, v26, v24
	v_add_f32_e32 v31, v26, v31
	v_add_f32_e32 v26, v30, v24
	v_rcp_f32_e32 v35, v26
	v_add_f32_e32 v34, v29, v31
	v_sub_f32_e32 v30, v26, v30
	v_sub_f32_e32 v29, v34, v29
	v_sub_f32_e32 v24, v24, v30
	v_mul_f32_e32 v30, v34, v35
	v_sub_f32_e32 v29, v31, v29
	v_mul_f32_e32 v31, v26, v30
	v_fma_f32 v38, v30, v26, -v31
	v_fmac_f32_e32 v38, v30, v24
	v_add_f32_e32 v39, v31, v38
	v_sub_f32_e32 v40, v34, v39
	v_sub_f32_e32 v34, v34, v40
	v_sub_f32_e32 v31, v39, v31
	v_sub_f32_e32 v34, v34, v39
	v_add_f32_e32 v29, v29, v34
	v_sub_f32_e32 v31, v31, v38
	v_add_f32_e32 v29, v31, v29
	v_add_f32_e32 v31, v40, v29
	v_mul_f32_e32 v34, v35, v31
	v_mul_f32_e32 v38, v26, v34
	v_fma_f32 v26, v34, v26, -v38
	v_fmac_f32_e32 v26, v34, v24
	v_sub_f32_e32 v24, v40, v31
	v_add_f32_e32 v24, v29, v24
	v_add_f32_e32 v29, v38, v26
	v_sub_f32_e32 v39, v31, v29
	v_sub_f32_e32 v31, v31, v39
	v_sub_f32_e32 v38, v29, v38
	v_sub_f32_e32 v29, v31, v29
	v_add_f32_e32 v24, v24, v29
	v_sub_f32_e32 v26, v38, v26
	v_cvt_f32_i32_e32 v28, v28
	v_add_f32_e32 v24, v26, v24
	v_add_f32_e32 v26, v30, v34
	v_add_f32_e32 v24, v39, v24
	v_sub_f32_e32 v29, v26, v30
	v_mul_f32_e32 v24, v35, v24
	v_sub_f32_e32 v29, v34, v29
	v_add_f32_e32 v24, v29, v24
	v_mul_f32_e32 v34, 0x3f317218, v28
	v_add_f32_e32 v29, v26, v24
	v_fma_f32 v35, v28, s5, -v34
	v_mul_f32_e32 v30, v29, v29
	v_fmac_f32_e32 v35, 0xb102e308, v28
	v_sub_f32_e32 v26, v29, v26
	v_fmamk_f32 v31, v30, 0x3e9b6dac, v136
	v_sub_f32_e32 v24, v24, v26
	v_add_f32_e32 v26, v34, v35
	v_fmaak_f32 v31, v30, v31, 0x3f2aaada
	v_sub_f32_e32 v28, v26, v34
	v_ldexp_f32 v34, v29, 1
	v_mul_f32_e32 v29, v29, v30
	v_mul_f32_e32 v29, v29, v31
	v_add_f32_e32 v30, v34, v29
	v_sub_f32_e32 v31, v30, v34
	v_ldexp_f32 v24, v24, 1
	v_sub_f32_e32 v29, v29, v31
	v_add_f32_e32 v24, v24, v29
	v_add_f32_e32 v29, v30, v24
	v_sub_f32_e32 v30, v29, v30
	v_sub_f32_e32 v24, v24, v30
	v_add_f32_e32 v30, v26, v29
	v_sub_f32_e32 v31, v30, v26
	v_sub_f32_e32 v34, v30, v31
	v_sub_f32_e32 v28, v35, v28
	v_sub_f32_e32 v26, v26, v34
	v_sub_f32_e32 v29, v29, v31
	v_add_f32_e32 v26, v29, v26
	v_add_f32_e32 v29, v28, v24
	v_sub_f32_e32 v31, v29, v28
	v_sub_f32_e32 v34, v29, v31
	v_sub_f32_e32 v28, v28, v34
	v_sub_f32_e32 v24, v24, v31
	v_add_f32_e32 v26, v29, v26
	v_add_f32_e32 v24, v24, v28
	v_add_f32_e32 v28, v30, v26
	v_sub_f32_e32 v29, v28, v30
	v_sub_f32_e32 v26, v26, v29
	v_add_f32_e32 v24, v24, v26
	v_add_f32_e32 v24, v28, v24
	v_cmp_neq_f32_e32 vcc, s6, v20
	v_lshlrev_b64 v[28:29], 9, v[32:33]
	v_lshl_add_u64 v[28:29], v[84:85], 0, v[28:29]
	v_cndmask_b32_e32 v24, v137, v24, vcc
	v_cmp_ngt_f32_e32 vcc, -1.0, v20
	s_nop 1
	v_cndmask_b32_e32 v24, v138, v24, vcc
	v_cmp_neq_f32_e32 vcc, -1.0, v20
	s_nop 1
	v_cndmask_b32_e32 v24, v139, v24, vcc
	v_cmp_lt_f32_e64 vcc, |v20|, s7
	s_nop 1
	v_cndmask_b32_e32 v20, v24, v20, vcc
	v_add_f32_e32 v20, v22, v20
	global_store_dword v[28:29], v20, off
	global_load_dword v22, v[82:83], off
	v_add_f32_e32 v20, 0, v21
	v_add_f32_e32 v20, v20, v23
	v_add_f32_e32 v23, v20, v25
	v_ffbh_u32_e32 v20, v37
	v_min_u32_e32 v24, 32, v20
	v_lshlrev_b64 v[20:21], v24, v[36:37]
	v_min_u32_e32 v20, 1, v20
	v_or_b32_e32 v20, v21, v20
	v_cvt_f32_u32_e32 v20, v20
	v_add_f32_e32 v21, v23, v27
	v_sub_u32_e32 v23, 32, v24
	s_waitcnt lgkmcnt(3)
	v_add_f32_e32 v21, v21, v41
	v_ldexp_f32 v20, v20, v23
	v_fmamk_f32 v20, v20, 0x2d800000, v135
	v_mul_f32_e32 v23, 0x4b800000, v20
	v_cmp_gt_f32_e32 vcc, s2, v20
	s_waitcnt lgkmcnt(2)
	v_add_f32_e32 v21, v21, v42
	s_waitcnt lgkmcnt(1)
	v_add_f32_e32 v21, v21, v43
	v_cndmask_b32_e32 v20, v20, v23, vcc
	v_rsq_f32_e32 v20, v20
	s_waitcnt lgkmcnt(0)
	v_add_f32_e32 v21, v21, v44
	v_mul_f32_e32 v23, 0x45800000, v20
	v_cndmask_b32_e32 v20, v20, v23, vcc
	s_waitcnt vmcnt(0)
; __device__ __forceinline__ void dt_phase(Frame& F, const bf16* A, const bf16* Wdt, const unsigned long long* rowss, const float* dt_bias, float* dt_out) {
;     ...
;     for (int u = blockIdx.x; u < M / 32; u += F.G) {
;     ...
;         for (int j = 0; j < 8; ++j) { const int idx = F.tid + 512 * j; float s = 0.f;
; #pragma unroll
;             for (int w = 0; w < 8; ++w) s += P[w * 4096 + idx];
;             const int row = u * 32 + (idx >> 7), col = idx & 127;
;             const float v = s * rsqrtf((float)rowss[row] * (1.0f / (4096.0f * 16777216.0f)) + RMS_EPS) + dt_bias[col];
;             dt_out[(size_t)row * 128 + col] = fmaxf(v, 0.f) + log1pf(__expf(-fabsf(v))); }
	v_fmac_f32_e32 v22, v21, v20
	v_mul_f32_e64 v20, |v22|, s3
	v_exp_f32_e32 v24, v20
	v_max_f32_e32 v25, 0, v22
	v_add_f32_e32 v22, 1.0, v24
	v_add_f32_e32 v23, -1.0, v22
	v_frexp_mant_f32_e32 v26, v22
	v_cvt_f64_f32_e32 v[20:21], v22
	v_sub_f32_e32 v27, v23, v22
	v_frexp_exp_i32_f64_e32 v20, v[20:21]
	v_cmp_gt_f32_e32 vcc, s4, v26
	v_sub_f32_e32 v23, v24, v23
	v_add_f32_e32 v21, 1.0, v27
	v_subbrev_co_u32_e32 v20, vcc, 0, v20, vcc
	v_add_f32_e32 v21, v23, v21
	v_sub_u32_e32 v23, 0, v20
	v_ldexp_f32 v22, v22, v23
	v_ldexp_f32 v21, v21, v23
	v_add_f32_e32 v23, -1.0, v22
	v_add_f32_e32 v26, 1.0, v22
	v_add_f32_e32 v27, 1.0, v23
	v_add_f32_e32 v28, -1.0, v26
	v_sub_f32_e32 v27, v22, v27
	v_sub_f32_e32 v22, v22, v28
	v_add_f32_e32 v27, v21, v27
	v_add_f32_e32 v21, v21, v22
	v_add_f32_e32 v28, v26, v21
	v_rcp_f32_e32 v29, v28
	v_add_f32_e32 v22, v23, v27
	v_sub_f32_e32 v26, v28, v26
	v_sub_f32_e32 v23, v22, v23
	v_sub_f32_e32 v21, v21, v26
	v_mul_f32_e32 v26, v22, v29
	v_sub_f32_e32 v23, v27, v23
	v_mul_f32_e32 v27, v28, v26
	v_fma_f32 v30, v26, v28, -v27
	v_fmac_f32_e32 v30, v26, v21
	v_add_f32_e32 v31, v27, v30
	v_sub_f32_e32 v32, v22, v31
	v_sub_f32_e32 v22, v22, v32
	v_sub_f32_e32 v27, v31, v27
	v_sub_f32_e32 v22, v22, v31
	v_sub_f32_e32 v27, v27, v30
	v_add_f32_e32 v22, v23, v22
	v_add_f32_e32 v22, v27, v22
	v_add_f32_e32 v23, v32, v22
	v_mul_f32_e32 v27, v29, v23
	v_mul_f32_e32 v31, v28, v27
	v_fma_f32 v28, v27, v28, -v31
	v_fmac_f32_e32 v28, v27, v21
	v_sub_f32_e32 v30, v32, v23
	v_add_f32_e32 v21, v31, v28
	v_add_f32_e32 v22, v22, v30
	v_sub_f32_e32 v30, v21, v31
	v_sub_f32_e32 v31, v23, v21
	v_sub_f32_e32 v23, v23, v31
	v_sub_f32_e32 v21, v23, v21
	v_add_f32_e32 v21, v22, v21
	v_sub_f32_e32 v22, v30, v28
	v_cvt_f32_i32_e32 v20, v20
	v_add_f32_e32 v21, v22, v21
	v_add_f32_e32 v22, v26, v27
	v_add_f32_e32 v21, v31, v21
	v_sub_f32_e32 v23, v22, v26
	v_mul_f32_e32 v21, v29, v21
	v_sub_f32_e32 v23, v27, v23
	v_add_f32_e32 v21, v23, v21
	v_mul_f32_e32 v28, 0x3f317218, v20
	v_add_f32_e32 v23, v22, v21
	v_fma_f32 v29, v20, s5, -v28
	v_fmac_f32_e32 v29, 0xb102e308, v20
	v_sub_f32_e32 v20, v23, v22
	v_mul_f32_e32 v26, v23, v23
	v_sub_f32_e32 v20, v21, v20
	v_add_f32_e32 v21, v28, v29
	v_fmamk_f32 v27, v26, 0x3e9b6dac, v136
	v_sub_f32_e32 v22, v21, v28
	v_fmaak_f32 v27, v26, v27, 0x3f2aaada
	v_sub_f32_e32 v28, v29, v22
	v_ldexp_f32 v22, v23, 1
	v_mul_f32_e32 v23, v23, v26
	v_mul_f32_e32 v23, v23, v27
	v_add_f32_e32 v26, v22, v23
	v_sub_f32_e32 v22, v26, v22
	v_ldexp_f32 v20, v20, 1
	v_sub_f32_e32 v22, v23, v22
	v_add_f32_e32 v20, v20, v22
	v_add_f32_e32 v27, v26, v20
	v_add_f32_e32 v29, v21, v27
	v_sub_f32_e32 v22, v27, v26
	v_sub_f32_e32 v30, v29, v21
	v_sub_f32_e32 v26, v20, v22
	v_sub_f32_e32 v20, v29, v30
	v_sub_f32_e32 v31, v21, v20
	v_or_b32_e32 v20, s0, v119
	v_ashrrev_i32_e32 v21, 31, v20
	v_lshl_add_u64 v[22:23], v[20:21], 3, s[18:19]
	global_load_dwordx2 v[34:35], v[22:23], off
	v_sub_f32_e32 v22, v27, v30
	v_add_f32_e32 v22, v22, v31
	v_add_f32_e32 v23, v28, v26
	v_sub_f32_e32 v27, v23, v28
	v_add_f32_e32 v22, v23, v22
	v_sub_f32_e32 v30, v23, v27
	v_add_f32_e32 v23, v29, v22
	v_sub_f32_e32 v28, v28, v30
	v_sub_f32_e32 v26, v26, v27
	v_sub_f32_e32 v27, v23, v29
	v_add_f32_e32 v26, v26, v28
	v_sub_f32_e32 v22, v22, v27
	v_add_f32_e32 v22, v26, v22
	v_add_f32_e32 v22, v23, v22
	v_cmp_neq_f32_e32 vcc, s6, v24
	v_or_b32_e32 v30, s0, v124
	v_or_b32_e32 v32, s0, v129
	v_cndmask_b32_e32 v22, v137, v22, vcc
	v_cmp_ngt_f32_e32 vcc, -1.0, v24
	v_ashrrev_i32_e32 v31, 31, v30
	v_ashrrev_i32_e32 v33, 31, v32
	v_cndmask_b32_e32 v22, v138, v22, vcc
	v_cmp_neq_f32_e32 vcc, -1.0, v24
	v_lshl_add_u64 v[38:39], v[30:31], 3, s[18:19]
	v_lshl_add_u64 v[44:45], v[32:33], 3, s[18:19]
	v_cndmask_b32_e32 v22, v139, v22, vcc
	v_cmp_lt_f32_e64 vcc, |v24|, s7
	v_lshlrev_b64 v[20:21], 9, v[20:21]
	v_lshl_add_u64 v[20:21], v[84:85], 0, v[20:21]
	v_cndmask_b32_e32 v22, v22, v24, vcc
	v_add_f32_e32 v22, v25, v22
	global_store_dword v[18:19], v22, off
	global_load_dword v42, v[82:83], off
	ds_read2st64_b32 v[24:25], v94 offset0:32 offset1:40
	ds_read2st64_b32 v[26:27], v94 offset0:96 offset1:104
	ds_read2st64_b32 v[28:29], v94 offset0:160 offset1:168
	ds_read2st64_b32 v[22:23], v94 offset0:224 offset1:232
	s_waitcnt lgkmcnt(3)
	v_add_f32_e32 v18, 0, v24
	s_waitcnt lgkmcnt(2)
	v_add_f32_e32 v18, v18, v26
	s_waitcnt lgkmcnt(1)
	v_add_f32_e32 v18, v18, v28
	s_waitcnt lgkmcnt(0)
	v_add_f32_e32 v22, v18, v22
	v_or_b32_e32 v18, s0, v134
	v_ashrrev_i32_e32 v19, 31, v18
	v_lshl_add_u64 v[46:47], v[18:19], 3, s[18:19]
	global_load_dwordx2 v[48:49], v[38:39], off
	global_load_dwordx2 v[40:41], v[44:45], off
	global_load_dwordx2 v[36:37], v[46:47], off
	v_readlane_b32 s0, v251, 0
	v_lshlrev_b64 v[18:19], 9, v[18:19]
	s_add_i32 s8, s8, s0
	v_lshl_add_u64 v[18:19], v[84:85], 0, v[18:19]
	s_cmpk_gt_i32 s8, 0xff
	v_readlane_b32 s1, v251, 1
	s_waitcnt vmcnt(5)
	v_ffbh_u32_e32 v24, v35
	v_min_u32_e32 v24, 32, v24
	v_lshlrev_b64 v[34:35], v24, v[34:35]
	v_min_u32_e32 v26, 1, v34
	v_or_b32_e32 v26, v35, v26
	v_cvt_f32_u32_e32 v26, v26
	v_sub_u32_e32 v24, 32, v24
	ds_read_b32 v28, v115
	ds_read_b32 v34, v116
	ds_read_b32 v35, v117
	ds_read_b32 v38, v118
	ds_read_b32 v39, v120
	ds_read_b32 v43, v121
	ds_read_b32 v44, v122
	ds_read_b32 v45, v123
	s_waitcnt lgkmcnt(7)
	v_add_f32_e32 v22, v22, v28
	v_ldexp_f32 v24, v26, v24
	v_fmamk_f32 v24, v24, 0x2d800000, v135
	v_mul_f32_e32 v26, 0x4b800000, v24
	v_cmp_gt_f32_e32 vcc, s2, v24
	s_waitcnt lgkmcnt(6)
	v_add_f32_e32 v22, v22, v34
	s_waitcnt lgkmcnt(5)
	v_add_f32_e32 v22, v22, v35
	v_cndmask_b32_e32 v24, v24, v26, vcc
	v_rsq_f32_e32 v24, v24
	s_waitcnt lgkmcnt(4)
; __device__ __forceinline__ void dt_phase(Frame& F, const bf16* A, const bf16* Wdt, const unsigned long long* rowss, const float* dt_bias, float* dt_out) {
;     ...
;         for (int j = 0; j < 8; ++j) { const int idx = F.tid + 512 * j; float s = 0.f;
; #pragma unroll
;             for (int w = 0; w < 8; ++w) s += P[w * 4096 + idx];
;             const int row = u * 32 + (idx >> 7), col = idx & 127;
;             const float v = s * rsqrtf((float)rowss[row] * (1.0f / (4096.0f * 16777216.0f)) + RMS_EPS) + dt_bias[col];
;             dt_out[(size_t)row * 128 + col] = fmaxf(v, 0.f) + log1pf(__expf(-fabsf(v))); }
	v_add_f32_e32 v22, v22, v38
	v_mul_f32_e32 v26, 0x45800000, v24
	v_cndmask_b32_e32 v24, v24, v26, vcc
	s_waitcnt vmcnt(3)
	v_fmac_f32_e32 v42, v22, v24
	v_mul_f32_e64 v22, |v42|, s3
	v_exp_f32_e32 v22, v22
	v_max_f32_e32 v24, 0, v42
	v_add_f32_e32 v26, 1.0, v22
	v_add_f32_e32 v28, -1.0, v26
	v_sub_f32_e32 v34, v28, v26
	v_add_f32_e32 v34, 1.0, v34
	v_sub_f32_e32 v28, v22, v28
	v_add_f32_e32 v28, v28, v34
	v_frexp_mant_f32_e32 v38, v26
	v_cvt_f64_f32_e32 v[34:35], v26
	v_frexp_exp_i32_f64_e32 v34, v[34:35]
	v_cmp_gt_f32_e32 vcc, s4, v38
	s_nop 1
	v_subbrev_co_u32_e32 v34, vcc, 0, v34, vcc
	v_sub_u32_e32 v35, 0, v34
	v_ldexp_f32 v26, v26, v35
	v_ldexp_f32 v28, v28, v35
	v_add_f32_e32 v35, -1.0, v26
	v_add_f32_e32 v46, 1.0, v26
	v_add_f32_e32 v38, 1.0, v35
	v_add_f32_e32 v47, -1.0, v46
	v_sub_f32_e32 v38, v26, v38
	v_sub_f32_e32 v26, v26, v47
	v_add_f32_e32 v26, v28, v26
	v_add_f32_e32 v38, v28, v38
	v_add_f32_e32 v28, v46, v26
	v_rcp_f32_e32 v47, v28
	v_add_f32_e32 v42, v35, v38
	v_sub_f32_e32 v35, v42, v35
	v_sub_f32_e32 v35, v38, v35
	v_sub_f32_e32 v38, v28, v46
	v_sub_f32_e32 v26, v26, v38
	v_mul_f32_e32 v38, v42, v47
	v_mul_f32_e32 v46, v28, v38
	v_fma_f32 v50, v38, v28, -v46
	v_fmac_f32_e32 v50, v38, v26
	v_add_f32_e32 v51, v46, v50
	v_sub_f32_e32 v52, v42, v51
	v_sub_f32_e32 v42, v42, v52
	v_sub_f32_e32 v46, v51, v46
	v_sub_f32_e32 v42, v42, v51
	v_add_f32_e32 v35, v35, v42
	v_sub_f32_e32 v42, v46, v50
	v_add_f32_e32 v35, v42, v35
	v_add_f32_e32 v42, v52, v35
	v_mul_f32_e32 v46, v47, v42
	v_mul_f32_e32 v50, v28, v46
	v_fma_f32 v28, v46, v28, -v50
	v_fmac_f32_e32 v28, v46, v26
	v_sub_f32_e32 v26, v52, v42
	v_add_f32_e32 v26, v35, v26
	v_add_f32_e32 v35, v50, v28
	v_sub_f32_e32 v51, v42, v35
	v_sub_f32_e32 v42, v42, v51
	v_sub_f32_e32 v50, v35, v50
	v_sub_f32_e32 v35, v42, v35
	v_add_f32_e32 v26, v26, v35
	v_sub_f32_e32 v28, v50, v28
	v_cvt_f32_i32_e32 v34, v34
	v_add_f32_e32 v26, v28, v26
	v_add_f32_e32 v28, v38, v46
	v_add_f32_e32 v26, v51, v26
	v_sub_f32_e32 v35, v28, v38
	v_mul_f32_e32 v26, v47, v26
	v_sub_f32_e32 v35, v46, v35
	v_add_f32_e32 v26, v35, v26
	v_mul_f32_e32 v46, 0x3f317218, v34
	v_add_f32_e32 v35, v28, v26
	v_fma_f32 v47, v34, s5, -v46
	v_mul_f32_e32 v38, v35, v35
	v_fmac_f32_e32 v47, 0xb102e308, v34
	v_sub_f32_e32 v28, v35, v28
	v_fmamk_f32 v42, v38, 0x3e9b6dac, v136
	v_sub_f32_e32 v26, v26, v28
	v_add_f32_e32 v28, v46, v47
	v_fmaak_f32 v42, v38, v42, 0x3f2aaada
	v_sub_f32_e32 v34, v28, v46
	v_ldexp_f32 v46, v35, 1
	v_mul_f32_e32 v35, v35, v38
	v_mul_f32_e32 v35, v35, v42
	v_add_f32_e32 v38, v46, v35
	v_sub_f32_e32 v42, v38, v46
	v_ldexp_f32 v26, v26, 1
	v_sub_f32_e32 v35, v35, v42
	v_add_f32_e32 v26, v26, v35
	v_add_f32_e32 v35, v38, v26
	v_sub_f32_e32 v38, v35, v38
	v_sub_f32_e32 v26, v26, v38
	v_add_f32_e32 v38, v28, v35
	v_sub_f32_e32 v42, v38, v28
	v_sub_f32_e32 v46, v38, v42
	v_sub_f32_e32 v34, v47, v34
	v_sub_f32_e32 v28, v28, v46
	v_sub_f32_e32 v35, v35, v42
	v_add_f32_e32 v28, v35, v28
	v_add_f32_e32 v35, v34, v26
	v_sub_f32_e32 v42, v35, v34
	v_sub_f32_e32 v46, v35, v42
	v_sub_f32_e32 v34, v34, v46
	v_sub_f32_e32 v26, v26, v42
	v_add_f32_e32 v28, v35, v28
	v_add_f32_e32 v26, v26, v34
	v_add_f32_e32 v34, v38, v28
	v_sub_f32_e32 v35, v34, v38
	v_sub_f32_e32 v28, v28, v35
	v_add_f32_e32 v26, v26, v28
	v_add_f32_e32 v26, v34, v26
	v_cmp_neq_f32_e32 vcc, s6, v22
	s_nop 1
	v_cndmask_b32_e32 v26, v137, v26, vcc
	v_cmp_ngt_f32_e32 vcc, -1.0, v22
	s_nop 1
	v_cndmask_b32_e32 v26, v138, v26, vcc
	v_cmp_neq_f32_e32 vcc, -1.0, v22
	s_nop 1
	v_cndmask_b32_e32 v26, v139, v26, vcc
	v_cmp_lt_f32_e64 vcc, |v22|, s7
	s_nop 1
	v_cndmask_b32_e32 v22, v26, v22, vcc
	v_add_f32_e32 v22, v24, v22
	global_store_dword v[20:21], v22, off
	global_load_dword v22, v[82:83], off
	v_add_f32_e32 v20, 0, v25
	v_add_f32_e32 v20, v20, v27
	v_add_f32_e32 v24, v20, v29
	s_waitcnt vmcnt(4)
	v_ffbh_u32_e32 v20, v49
	v_min_u32_e32 v25, 32, v20
	v_lshlrev_b64 v[20:21], v25, v[48:49]
	v_min_u32_e32 v20, 1, v20
	v_or_b32_e32 v20, v21, v20
	v_cvt_f32_u32_e32 v20, v20
	v_add_f32_e32 v21, v24, v23
	v_sub_u32_e32 v23, 32, v25
	s_waitcnt lgkmcnt(3)
	v_add_f32_e32 v21, v21, v39
	v_ldexp_f32 v20, v20, v23
	v_fmamk_f32 v20, v20, 0x2d800000, v135
	v_mul_f32_e32 v23, 0x4b800000, v20
	v_cmp_gt_f32_e32 vcc, s2, v20
	s_waitcnt lgkmcnt(2)
	v_add_f32_e32 v21, v21, v43
	s_waitcnt lgkmcnt(1)
	v_add_f32_e32 v21, v21, v44
	v_cndmask_b32_e32 v20, v20, v23, vcc
	v_rsq_f32_e32 v20, v20
	s_waitcnt lgkmcnt(0)
	v_add_f32_e32 v21, v21, v45
	v_mul_f32_e32 v23, 0x45800000, v20
	v_cndmask_b32_e32 v20, v20, v23, vcc
	s_waitcnt vmcnt(0)
; __device__ __forceinline__ void dt_phase(Frame& F, const bf16* A, const bf16* Wdt, const unsigned long long* rowss, const float* dt_bias, float* dt_out) {
;     ...
;         for (int j = 0; j < 8; ++j) { const int idx = F.tid + 512 * j; float s = 0.f;
; #pragma unroll
;             for (int w = 0; w < 8; ++w) s += P[w * 4096 + idx];
;             const int row = u * 32 + (idx >> 7), col = idx & 127;
;             const float v = s * rsqrtf((float)rowss[row] * (1.0f / (4096.0f * 16777216.0f)) + RMS_EPS) + dt_bias[col];
;             dt_out[(size_t)row * 128 + col] = fmaxf(v, 0.f) + log1pf(__expf(-fabsf(v))); }
	v_fmac_f32_e32 v22, v21, v20
	v_mul_f32_e64 v20, |v22|, s3
	v_exp_f32_e32 v23, v20
	v_max_f32_e32 v22, 0, v22
	v_add_f32_e32 v24, 1.0, v23
	v_add_f32_e32 v25, -1.0, v24
	v_frexp_mant_f32_e32 v26, v24
	v_cvt_f64_f32_e32 v[20:21], v24
	v_sub_f32_e32 v27, v25, v24
	v_frexp_exp_i32_f64_e32 v20, v[20:21]
	v_cmp_gt_f32_e32 vcc, s4, v26
	v_sub_f32_e32 v25, v23, v25
	v_add_f32_e32 v21, 1.0, v27
	v_subbrev_co_u32_e32 v20, vcc, 0, v20, vcc
	v_add_f32_e32 v21, v25, v21
	v_sub_u32_e32 v25, 0, v20
	v_ldexp_f32 v24, v24, v25
	v_ldexp_f32 v21, v21, v25
	v_add_f32_e32 v25, -1.0, v24
	v_add_f32_e32 v28, 1.0, v24
	v_add_f32_e32 v26, 1.0, v25
	v_add_f32_e32 v29, -1.0, v28
	v_sub_f32_e32 v26, v24, v26
	v_sub_f32_e32 v24, v24, v29
	v_add_f32_e32 v26, v21, v26
	v_add_f32_e32 v21, v21, v24
	v_add_f32_e32 v24, v28, v21
	v_rcp_f32_e32 v29, v24
	v_add_f32_e32 v27, v25, v26
	v_sub_f32_e32 v25, v27, v25
	v_sub_f32_e32 v25, v26, v25
	v_sub_f32_e32 v26, v24, v28
	v_sub_f32_e32 v21, v21, v26
	v_mul_f32_e32 v26, v27, v29
	v_mul_f32_e32 v28, v24, v26
	v_fma_f32 v34, v26, v24, -v28
	v_fmac_f32_e32 v34, v26, v21
	v_add_f32_e32 v35, v28, v34
	v_sub_f32_e32 v38, v27, v35
	v_sub_f32_e32 v27, v27, v38
	v_sub_f32_e32 v28, v35, v28
	v_sub_f32_e32 v27, v27, v35
	v_add_f32_e32 v25, v25, v27
	v_sub_f32_e32 v27, v28, v34
	v_add_f32_e32 v25, v27, v25
	v_add_f32_e32 v27, v38, v25
	v_mul_f32_e32 v28, v29, v27
	v_mul_f32_e32 v34, v24, v28
	v_fma_f32 v24, v28, v24, -v34
	v_fmac_f32_e32 v24, v28, v21
	v_sub_f32_e32 v21, v38, v27
	v_add_f32_e32 v21, v25, v21
	v_add_f32_e32 v25, v34, v24
	v_sub_f32_e32 v35, v27, v25
	v_sub_f32_e32 v27, v27, v35
	v_sub_f32_e32 v34, v25, v34
	v_sub_f32_e32 v25, v27, v25
	v_add_f32_e32 v21, v21, v25
	v_sub_f32_e32 v24, v34, v24
	v_cvt_f32_i32_e32 v20, v20
	v_add_f32_e32 v21, v24, v21
	v_add_f32_e32 v24, v26, v28
	v_add_f32_e32 v21, v35, v21
	v_sub_f32_e32 v25, v24, v26
	v_mul_f32_e32 v21, v29, v21
	v_sub_f32_e32 v25, v28, v25
	v_add_f32_e32 v21, v25, v21
	v_mul_f32_e32 v28, 0x3f317218, v20
	v_add_f32_e32 v25, v24, v21
	v_fma_f32 v29, v20, s5, -v28
	v_mul_f32_e32 v26, v25, v25
	v_fmac_f32_e32 v29, 0xb102e308, v20
	v_sub_f32_e32 v20, v25, v24
	v_fmamk_f32 v27, v26, 0x3e9b6dac, v136
	v_sub_f32_e32 v20, v21, v20
	v_add_f32_e32 v21, v28, v29
	v_fmaak_f32 v27, v26, v27, 0x3f2aaada
	v_sub_f32_e32 v24, v21, v28
	v_ldexp_f32 v28, v25, 1
	v_mul_f32_e32 v25, v25, v26
	v_mul_f32_e32 v25, v25, v27
	v_add_f32_e32 v26, v28, v25
	v_sub_f32_e32 v27, v26, v28
	v_ldexp_f32 v20, v20, 1
	v_sub_f32_e32 v25, v25, v27
	v_add_f32_e32 v20, v20, v25
	v_add_f32_e32 v25, v26, v20
	v_sub_f32_e32 v26, v25, v26
	v_sub_f32_e32 v20, v20, v26
	v_add_f32_e32 v26, v21, v25
	v_sub_f32_e32 v27, v26, v21
	v_sub_f32_e32 v28, v26, v27
	v_sub_f32_e32 v24, v29, v24
	v_sub_f32_e32 v21, v21, v28
	v_sub_f32_e32 v25, v25, v27
	v_add_f32_e32 v21, v25, v21
	v_add_f32_e32 v25, v24, v20
	v_sub_f32_e32 v27, v25, v24
	v_sub_f32_e32 v28, v25, v27
	v_sub_f32_e32 v24, v24, v28
	v_sub_f32_e32 v20, v20, v27
	v_add_f32_e32 v21, v25, v21
	v_add_f32_e32 v20, v20, v24
	v_add_f32_e32 v24, v26, v21
	v_sub_f32_e32 v25, v24, v26
	v_sub_f32_e32 v21, v21, v25
	v_add_f32_e32 v20, v20, v21
	v_add_f32_e32 v20, v24, v20
	v_cmp_neq_f32_e32 vcc, s6, v23
	s_nop 1
	v_cndmask_b32_e32 v20, v137, v20, vcc
	v_cmp_ngt_f32_e32 vcc, -1.0, v23
	s_nop 1
	v_cndmask_b32_e32 v20, v138, v20, vcc
	v_cmp_neq_f32_e32 vcc, -1.0, v23
	s_nop 1
	v_cndmask_b32_e32 v20, v139, v20, vcc
	v_cmp_lt_f32_e64 vcc, |v23|, s7
	s_nop 1
	v_cndmask_b32_e32 v20, v20, v23, vcc
	v_add_f32_e32 v22, v22, v20
	v_lshlrev_b64 v[20:21], 9, v[30:31]
	v_lshl_add_u64 v[20:21], v[84:85], 0, v[20:21]
	global_store_dword v[20:21], v22, off
	global_load_dword v30, v[82:83], off
	ds_read2st64_b32 v[20:21], v94 offset0:48 offset1:56
	ds_read2st64_b32 v[22:23], v94 offset0:112 offset1:120
	ds_read2st64_b32 v[24:25], v94 offset0:176 offset1:184
	ds_read2st64_b32 v[26:27], v94 offset0:240 offset1:248
	s_waitcnt lgkmcnt(3)
	v_add_f32_e32 v20, 0, v20
	s_waitcnt lgkmcnt(2)
	v_add_f32_e32 v20, v20, v22
	v_ffbh_u32_e32 v22, v41
	v_min_u32_e32 v22, 32, v22
	v_lshlrev_b64 v[28:29], v22, v[40:41]
	s_waitcnt lgkmcnt(1)
	v_add_f32_e32 v20, v20, v24
	v_min_u32_e32 v24, 1, v28
	v_or_b32_e32 v24, v29, v24
	v_cvt_f32_u32_e32 v24, v24
	v_sub_u32_e32 v22, 32, v22
	s_waitcnt lgkmcnt(0)
	v_add_f32_e32 v20, v20, v26
	ds_read_b32 v26, v125
	ds_read_b32 v28, v126
	ds_read_b32 v29, v127
	ds_read_b32 v31, v128
	ds_read_b32 v34, v130
	ds_read_b32 v35, v131
	ds_read_b32 v38, v132
	ds_read_b32 v39, v133
	v_ldexp_f32 v22, v24, v22
	v_fmamk_f32 v22, v22, 0x2d800000, v135
	v_mul_f32_e32 v24, 0x4b800000, v22
	v_cmp_gt_f32_e32 vcc, s2, v22
	s_waitcnt lgkmcnt(7)
	v_add_f32_e32 v20, v20, v26
	s_waitcnt lgkmcnt(6)
	v_add_f32_e32 v20, v20, v28
	v_cndmask_b32_e32 v22, v22, v24, vcc
	v_rsq_f32_e32 v22, v22
	s_waitcnt lgkmcnt(5)
	v_add_f32_e32 v20, v20, v29
	s_waitcnt lgkmcnt(4)
	v_add_f32_e32 v20, v20, v31
	v_mul_f32_e32 v24, 0x45800000, v22
	v_cndmask_b32_e32 v22, v22, v24, vcc
	s_waitcnt vmcnt(0)
; __device__ __forceinline__ void dt_phase(Frame& F, const bf16* A, const bf16* Wdt, const unsigned long long* rowss, const float* dt_bias, float* dt_out) {
;     ...
;         for (int j = 0; j < 8; ++j) { const int idx = F.tid + 512 * j; float s = 0.f;
; #pragma unroll
;             for (int w = 0; w < 8; ++w) s += P[w * 4096 + idx];
;             const int row = u * 32 + (idx >> 7), col = idx & 127;
;             const float v = s * rsqrtf((float)rowss[row] * (1.0f / (4096.0f * 16777216.0f)) + RMS_EPS) + dt_bias[col];
;             dt_out[(size_t)row * 128 + col] = fmaxf(v, 0.f) + log1pf(__expf(-fabsf(v))); }
	v_fmac_f32_e32 v30, v20, v22
	v_mul_f32_e64 v20, |v30|, s3
	v_exp_f32_e32 v20, v20
	v_max_f32_e32 v22, 0, v30
	v_add_f32_e32 v24, 1.0, v20
	v_add_f32_e32 v26, -1.0, v24
	v_sub_f32_e32 v28, v26, v24
	v_add_f32_e32 v28, 1.0, v28
	v_sub_f32_e32 v26, v20, v26
	v_add_f32_e32 v26, v26, v28
	v_frexp_mant_f32_e32 v30, v24
	v_cvt_f64_f32_e32 v[28:29], v24
	v_frexp_exp_i32_f64_e32 v28, v[28:29]
	v_cmp_gt_f32_e32 vcc, s4, v30
	s_nop 1
	v_subbrev_co_u32_e32 v28, vcc, 0, v28, vcc
	v_sub_u32_e32 v29, 0, v28
	v_ldexp_f32 v24, v24, v29
	v_ldexp_f32 v26, v26, v29
	v_add_f32_e32 v29, -1.0, v24
	v_add_f32_e32 v40, 1.0, v24
	v_add_f32_e32 v30, 1.0, v29
	v_add_f32_e32 v41, -1.0, v40
	v_sub_f32_e32 v30, v24, v30
	v_sub_f32_e32 v24, v24, v41
	v_add_f32_e32 v24, v26, v24
	v_add_f32_e32 v30, v26, v30
	v_add_f32_e32 v26, v40, v24
	v_rcp_f32_e32 v41, v26
	v_add_f32_e32 v31, v29, v30
	v_sub_f32_e32 v29, v31, v29
	v_sub_f32_e32 v29, v30, v29
	v_sub_f32_e32 v30, v26, v40
	v_sub_f32_e32 v24, v24, v30
	v_mul_f32_e32 v30, v31, v41
	v_mul_f32_e32 v40, v26, v30
	v_fma_f32 v42, v30, v26, -v40
	v_fmac_f32_e32 v42, v30, v24
	v_add_f32_e32 v43, v40, v42
	v_sub_f32_e32 v44, v31, v43
	v_sub_f32_e32 v31, v31, v44
	v_sub_f32_e32 v40, v43, v40
	v_sub_f32_e32 v31, v31, v43
	v_add_f32_e32 v29, v29, v31
	v_sub_f32_e32 v31, v40, v42
	v_add_f32_e32 v29, v31, v29
	v_add_f32_e32 v31, v44, v29
	v_mul_f32_e32 v40, v41, v31
	v_mul_f32_e32 v42, v26, v40
	v_fma_f32 v26, v40, v26, -v42
	v_fmac_f32_e32 v26, v40, v24
	v_sub_f32_e32 v24, v44, v31
	v_add_f32_e32 v24, v29, v24
	v_add_f32_e32 v29, v42, v26
	v_sub_f32_e32 v43, v31, v29
	v_sub_f32_e32 v31, v31, v43
	v_sub_f32_e32 v42, v29, v42
	v_sub_f32_e32 v29, v31, v29
	v_add_f32_e32 v24, v24, v29
	v_sub_f32_e32 v26, v42, v26
	v_cvt_f32_i32_e32 v28, v28
	v_add_f32_e32 v24, v26, v24
	v_add_f32_e32 v26, v30, v40
	v_add_f32_e32 v24, v43, v24
	v_sub_f32_e32 v29, v26, v30
	v_mul_f32_e32 v24, v41, v24
	v_sub_f32_e32 v29, v40, v29
	v_add_f32_e32 v24, v29, v24
	v_mul_f32_e32 v40, 0x3f317218, v28
	v_add_f32_e32 v29, v26, v24
	v_fma_f32 v41, v28, s5, -v40
	v_mul_f32_e32 v30, v29, v29
	v_fmac_f32_e32 v41, 0xb102e308, v28
	v_sub_f32_e32 v26, v29, v26
	v_fmamk_f32 v31, v30, 0x3e9b6dac, v136
	v_sub_f32_e32 v24, v24, v26
	v_add_f32_e32 v26, v40, v41
	v_fmaak_f32 v31, v30, v31, 0x3f2aaada
	v_sub_f32_e32 v28, v26, v40
	v_ldexp_f32 v40, v29, 1
	v_mul_f32_e32 v29, v29, v30
	v_mul_f32_e32 v29, v29, v31
	v_add_f32_e32 v30, v40, v29
	v_sub_f32_e32 v31, v30, v40
	v_ldexp_f32 v24, v24, 1
	v_sub_f32_e32 v29, v29, v31
	v_add_f32_e32 v24, v24, v29
	v_add_f32_e32 v29, v30, v24
	v_sub_f32_e32 v30, v29, v30
	v_sub_f32_e32 v24, v24, v30
	v_add_f32_e32 v30, v26, v29
	v_sub_f32_e32 v31, v30, v26
	v_sub_f32_e32 v40, v30, v31
	v_sub_f32_e32 v28, v41, v28
	v_sub_f32_e32 v26, v26, v40
	v_sub_f32_e32 v29, v29, v31
	v_add_f32_e32 v26, v29, v26
	v_add_f32_e32 v29, v28, v24
	v_sub_f32_e32 v31, v29, v28
	v_sub_f32_e32 v40, v29, v31
	v_sub_f32_e32 v28, v28, v40
	v_sub_f32_e32 v24, v24, v31
	v_add_f32_e32 v26, v29, v26
	v_add_f32_e32 v24, v24, v28
	v_add_f32_e32 v28, v30, v26
	v_sub_f32_e32 v29, v28, v30
	v_sub_f32_e32 v26, v26, v29
	v_add_f32_e32 v24, v24, v26
	v_add_f32_e32 v24, v28, v24
	v_cmp_neq_f32_e32 vcc, s6, v20
	v_lshlrev_b64 v[28:29], 9, v[32:33]
	v_lshl_add_u64 v[28:29], v[84:85], 0, v[28:29]
	v_cndmask_b32_e32 v24, v137, v24, vcc
	v_cmp_ngt_f32_e32 vcc, -1.0, v20
	s_nop 1
	v_cndmask_b32_e32 v24, v138, v24, vcc
	v_cmp_neq_f32_e32 vcc, -1.0, v20
	s_nop 1
	v_cndmask_b32_e32 v24, v139, v24, vcc
	v_cmp_lt_f32_e64 vcc, |v20|, s7
	s_nop 1
	v_cndmask_b32_e32 v20, v24, v20, vcc
	v_add_f32_e32 v20, v22, v20
	global_store_dword v[28:29], v20, off
	global_load_dword v22, v[82:83], off
	v_add_f32_e32 v20, 0, v21
	v_add_f32_e32 v20, v20, v23
	v_add_f32_e32 v23, v20, v25
	v_ffbh_u32_e32 v20, v37
	v_min_u32_e32 v24, 32, v20
	v_lshlrev_b64 v[20:21], v24, v[36:37]
	v_min_u32_e32 v20, 1, v20
	v_or_b32_e32 v20, v21, v20
	v_cvt_f32_u32_e32 v20, v20
	v_add_f32_e32 v21, v23, v27
	v_sub_u32_e32 v23, 32, v24
	s_waitcnt lgkmcnt(3)
; __device__ __forceinline__ void dt_phase(Frame& F, const bf16* A, const bf16* Wdt, const unsigned long long* rowss, const float* dt_bias, float* dt_out) {
;     ...
;     for (int u = blockIdx.x; u < M / 32; u += F.G) {
;     ...
;         for (int j = 0; j < 8; ++j) { const int idx = F.tid + 512 * j; float s = 0.f;
; #pragma unroll
;             for (int w = 0; w < 8; ++w) s += P[w * 4096 + idx];
;             const int row = u * 32 + (idx >> 7), col = idx & 127;
;             const float v = s * rsqrtf((float)rowss[row] * (1.0f / (4096.0f * 16777216.0f)) + RMS_EPS) + dt_bias[col];
;             dt_out[(size_t)row * 128 + col] = fmaxf(v, 0.f) + log1pf(__expf(-fabsf(v))); }
;         __syncthreads();
	v_add_f32_e32 v21, v21, v34
	v_ldexp_f32 v20, v20, v23
	v_fmamk_f32 v20, v20, 0x2d800000, v135
	v_mul_f32_e32 v23, 0x4b800000, v20
	v_cmp_gt_f32_e32 vcc, s2, v20
	s_waitcnt lgkmcnt(2)
	v_add_f32_e32 v21, v21, v35
	s_waitcnt lgkmcnt(1)
	v_add_f32_e32 v21, v21, v38
	v_cndmask_b32_e32 v20, v20, v23, vcc
	v_rsq_f32_e32 v20, v20
	s_waitcnt lgkmcnt(0)
	v_add_f32_e32 v21, v21, v39
	v_mul_f32_e32 v23, 0x45800000, v20
	v_cndmask_b32_e32 v20, v20, v23, vcc
	s_waitcnt vmcnt(0)
	v_fmac_f32_e32 v22, v21, v20
	v_mul_f32_e64 v20, |v22|, s3
	v_exp_f32_e32 v23, v20
	v_max_f32_e32 v22, 0, v22
	v_add_f32_e32 v24, 1.0, v23
	v_add_f32_e32 v25, -1.0, v24
	v_frexp_mant_f32_e32 v26, v24
	v_cvt_f64_f32_e32 v[20:21], v24
	v_sub_f32_e32 v27, v25, v24
	v_frexp_exp_i32_f64_e32 v20, v[20:21]
	v_cmp_gt_f32_e32 vcc, s4, v26
	v_sub_f32_e32 v25, v23, v25
	v_add_f32_e32 v21, 1.0, v27
	v_subbrev_co_u32_e32 v20, vcc, 0, v20, vcc
	v_add_f32_e32 v21, v25, v21
	v_sub_u32_e32 v25, 0, v20
	v_ldexp_f32 v24, v24, v25
	v_ldexp_f32 v21, v21, v25
	v_add_f32_e32 v25, -1.0, v24
	v_add_f32_e32 v28, 1.0, v24
	v_add_f32_e32 v26, 1.0, v25
	v_add_f32_e32 v29, -1.0, v28
	v_sub_f32_e32 v26, v24, v26
	v_sub_f32_e32 v24, v24, v29
	v_add_f32_e32 v26, v21, v26
	v_add_f32_e32 v21, v21, v24
	v_add_f32_e32 v24, v28, v21
	v_rcp_f32_e32 v29, v24
	v_add_f32_e32 v27, v25, v26
	v_sub_f32_e32 v25, v27, v25
	v_sub_f32_e32 v25, v26, v25
	v_sub_f32_e32 v26, v24, v28
	v_sub_f32_e32 v21, v21, v26
	v_mul_f32_e32 v26, v27, v29
	v_mul_f32_e32 v28, v24, v26
	v_fma_f32 v30, v26, v24, -v28
	v_fmac_f32_e32 v30, v26, v21
	v_add_f32_e32 v31, v28, v30
	v_sub_f32_e32 v32, v27, v31
	v_sub_f32_e32 v27, v27, v32
	v_sub_f32_e32 v28, v31, v28
	v_sub_f32_e32 v27, v27, v31
	v_add_f32_e32 v25, v25, v27
	v_sub_f32_e32 v27, v28, v30
	v_add_f32_e32 v25, v27, v25
	v_add_f32_e32 v27, v32, v25
	v_mul_f32_e32 v28, v29, v27
	v_mul_f32_e32 v30, v24, v28
	v_fma_f32 v24, v28, v24, -v30
	v_fmac_f32_e32 v24, v28, v21
	v_sub_f32_e32 v21, v32, v27
	v_add_f32_e32 v21, v25, v21
	v_add_f32_e32 v25, v30, v24
	v_sub_f32_e32 v31, v27, v25
	v_sub_f32_e32 v27, v27, v31
	v_sub_f32_e32 v30, v25, v30
	v_sub_f32_e32 v25, v27, v25
	v_add_f32_e32 v21, v21, v25
	v_sub_f32_e32 v24, v30, v24
	v_cvt_f32_i32_e32 v20, v20
	v_add_f32_e32 v21, v24, v21
	v_add_f32_e32 v24, v26, v28
	v_add_f32_e32 v21, v31, v21
	v_sub_f32_e32 v25, v24, v26
	v_mul_f32_e32 v21, v29, v21
	v_sub_f32_e32 v25, v28, v25
	v_add_f32_e32 v21, v25, v21
	v_mul_f32_e32 v28, 0x3f317218, v20
	v_add_f32_e32 v25, v24, v21
	v_fma_f32 v29, v20, s5, -v28
	v_mul_f32_e32 v26, v25, v25
	v_fmac_f32_e32 v29, 0xb102e308, v20
	v_sub_f32_e32 v20, v25, v24
	v_fmamk_f32 v27, v26, 0x3e9b6dac, v136
	v_sub_f32_e32 v20, v21, v20
	v_add_f32_e32 v21, v28, v29
	v_fmaak_f32 v27, v26, v27, 0x3f2aaada
	v_sub_f32_e32 v24, v21, v28
	v_ldexp_f32 v28, v25, 1
	v_mul_f32_e32 v25, v25, v26
	v_mul_f32_e32 v25, v25, v27
	v_add_f32_e32 v26, v28, v25
	v_sub_f32_e32 v27, v26, v28
	v_ldexp_f32 v20, v20, 1
	v_sub_f32_e32 v25, v25, v27
	v_add_f32_e32 v20, v20, v25
	v_add_f32_e32 v25, v26, v20
	v_sub_f32_e32 v26, v25, v26
	v_sub_f32_e32 v20, v20, v26
	v_add_f32_e32 v26, v21, v25
	v_sub_f32_e32 v27, v26, v21
	v_sub_f32_e32 v28, v26, v27
	v_sub_f32_e32 v24, v29, v24
	v_sub_f32_e32 v21, v21, v28
	v_sub_f32_e32 v25, v25, v27
	v_add_f32_e32 v21, v25, v21
	v_add_f32_e32 v25, v24, v20
	v_sub_f32_e32 v27, v25, v24
	v_sub_f32_e32 v28, v25, v27
	v_sub_f32_e32 v24, v24, v28
	v_sub_f32_e32 v20, v20, v27
	v_add_f32_e32 v21, v25, v21
	v_add_f32_e32 v20, v20, v24
	v_add_f32_e32 v24, v26, v21
	v_sub_f32_e32 v25, v24, v26
	v_sub_f32_e32 v21, v21, v25
	v_add_f32_e32 v20, v20, v21
	v_add_f32_e32 v20, v24, v20
	v_cmp_neq_f32_e32 vcc, s6, v23
	s_nop 1
	v_cndmask_b32_e32 v20, v137, v20, vcc
	v_cmp_ngt_f32_e32 vcc, -1.0, v23
	s_nop 1
	v_cndmask_b32_e32 v20, v138, v20, vcc
	v_cmp_neq_f32_e32 vcc, -1.0, v23
	s_nop 1
	v_cndmask_b32_e32 v20, v139, v20, vcc
	v_cmp_lt_f32_e64 vcc, |v23|, s7
	s_nop 1
	v_cndmask_b32_e32 v20, v20, v23, vcc
	v_add_f32_e32 v20, v22, v20
	global_store_dword v[18:19], v20, off
	s_barrier
	s_cbranch_scc0 .LBB0_1908
